# GEMM MFMA blocks at 0 mod 64
# speedup vs baseline: 1.0023x; 1.0023x over previous
; #define PG8_STAGE(bufoff, gbase, voff) do { _Pragma("unroll") for (int _i = 0; _i < 2; ++_i) \
;         __builtin_amdgcn_global_load_lds((const unsigned*)((const char*)(gbase) + (voff)[_i]), (PG8_LAS unsigned*)(lds + (bufoff) + ldsw + _i * 8192), 16, 0, 0); } while (0)
; #define PG8_LDA(dst, b, h) do { _Pragma("unroll") for (int m = 0; m < 4; ++m) _Pragma("unroll") for (int k = 0; k < 2; ++k) dst[m][k] = *(const PG8_LAS bf16x8*)(lds + PG8_SA(b, h) + aoff + m * 2048 + k * 1024); } while (0)
; #define PG8_LDB(dst, b, h) do { _Pragma("unroll") for (int n = 0; n < 2; ++n) _Pragma("unroll") for (int k = 0; k < 2; ++k) dst[n][k] = *(const PG8_LAS bf16x8*)(lds + PG8_SB(b, h) + boff + n * 2048 + k * 1024); } while (0)
; #define PG8_MMA(ai, bj, At, Bt) do { __builtin_amdgcn_s_setprio(1); _Pragma("unroll") for (int m = 0; m < 4; ++m) _Pragma("unroll") for (int n = 0; n < 2; ++n) _Pragma("unroll") for (int k = 0; k < 2; ++k) \
;         acc[ai][bj][m][n] = __builtin_amdgcn_mfma_f32_16x16x32_bf16(Bt[n][k], At[m][k], acc[ai][bj][m][n], 0, 0, 0); __builtin_amdgcn_s_setprio(0); } while (0)
; #define PG8_WAIT_V(n) asm volatile("s_waitcnt vmcnt(" #n ")" ::: "memory")
; #define PG8_WAIT_L(n) asm volatile("s_waitcnt lgkmcnt(" #n ")" ::: "memory")
; #define PG8_BAR __builtin_amdgcn_s_barrier()
; #define PG8_SCHED __builtin_amdgcn_sched_barrier(0)
; template <class Epi, class Sched, bool ALIGN_EPI = false, bool SP2 = false>
; __device__ __forceinline__ void gemm_phase(PG8_LAS unsigned char* lds, const Gemm g, const Sched& S, const Epi& E) {
;     ...
;             const bool last = (t == nt - 2);
;             const char* a1 = cA + (size_t)(t + 1) * kstep;
;             const char* a2 = last ? nA : cA + (size_t)(t + 2) * kstep; const char* b2 = last ? nB : cB + (size_t)(t + 2) * kstep;
;             const char* a3 = a2 + kstep; const char* b3 = b2 + kstep;
;             if (last && has_next) S.a_ready(nxt);
;             if constexpr (SP2) {
;             PG8_LDB(B0, 0, 0); PG8_LDB(B1, 0, 1); PG8_SCHED; PG8_LDA(At, 0, 0); PG8_STAGE(PG8_SA(1, 1), a1 + hstep, voffA);
;             PG8_WAIT_V(8); PG8_WAIT_L(0); PG8_BAR; PG8_MMA(0, 0, At, B0); PG8_MMA(0, 1, At, B1); PG8_BAR; PG8_SCHED;
;             PG8_LDA(At, 0, 1); PG8_STAGE(PG8_SB(0, 0), b2, voffB); PG8_STAGE(PG8_SB(0, 1), b2 + hstep, voffB); PG8_STAGE(PG8_SA(0, 0), a2, voffA);
.LBB0_148:
	s_add_u32 s8, s6, 0xfff80080
	s_addc_u32 s9, s7, -1
	s_add_i32 s39, 0, 0x10000
	s_cmp_eq_u32 s38, 28
	s_cselect_b32 s31, s25, s9
	s_cselect_b32 s30, s34, s8
	s_cselect_b32 s9, s23, s37
	s_cselect_b32 s8, s35, s36
	s_add_i32 s58, 0, 0x14000
	v_add_u32_e32 v140, s39, v181
	v_add_u32_e32 v178, s58, v181
	ds_read_b128 v[128:131], v140
	ds_read_b128 v[132:135], v140 offset:1024
	ds_read_b128 v[136:139], v140 offset:2048
	ds_read_b128 v[140:143], v140 offset:3072
	ds_read_b128 v[174:177], v178
	ds_read_b128 v[184:187], v178 offset:1024
	ds_read_b128 v[198:201], v178 offset:2048
	ds_read_b128 v[202:205], v178 offset:3072
	v_lshl_add_u64 v[246:247], s[6:7], 0, v[154:155]
	s_add_i32 m0, s63, 0xc000
	ds_read_b128 v[206:209], v183
	ds_read_b128 v[210:213], v183 offset:1024
	ds_read_b128 v[214:217], v183 offset:2048
	ds_read_b128 v[218:221], v183 offset:3072
	ds_read_b128 v[222:225], v183 offset:4096
	ds_read_b128 v[226:229], v183 offset:5120
	ds_read_b128 v[238:241], v183 offset:6144
	ds_read_b128 v[242:245], v183 offset:7168
	global_load_lds_dwordx4 v[246:247], off
	v_lshl_add_u64 v[246:247], s[6:7], 0, v[156:157]
	s_add_i32 m0, s63, 0xe000
	s_nop 0
	global_load_lds_dwordx4 v[246:247], off
	s_nop 0
	s_nop 0
	s_waitcnt vmcnt(8)
	s_waitcnt lgkmcnt(0)
	s_barrier
	s_setprio 1
	v_mfma_f32_16x16x32_bf16 v[124:127], v[128:131], v[206:209], v[124:127]
	v_mfma_f32_16x16x32_bf16 v[120:123], v[136:139], v[206:209], v[120:123]
	v_mfma_f32_16x16x32_bf16 v[108:111], v[128:131], v[214:217], v[108:111]
	v_mfma_f32_16x16x32_bf16 v[104:107], v[136:139], v[214:217], v[104:107]
	v_mfma_f32_16x16x32_bf16 v[92:95], v[128:131], v[222:225], v[92:95]
	v_mfma_f32_16x16x32_bf16 v[88:91], v[136:139], v[222:225], v[88:91]
	v_mfma_f32_16x16x32_bf16 v[76:79], v[128:131], v[238:241], v[76:79]
	v_mfma_f32_16x16x32_bf16 v[72:75], v[136:139], v[238:241], v[72:75]
	v_mfma_f32_16x16x32_bf16 v[124:127], v[132:135], v[210:213], v[124:127]
	v_mfma_f32_16x16x32_bf16 v[120:123], v[140:143], v[210:213], v[120:123]
	v_mfma_f32_16x16x32_bf16 v[108:111], v[132:135], v[218:221], v[108:111]
	v_mfma_f32_16x16x32_bf16 v[104:107], v[140:143], v[218:221], v[104:107]
	v_mfma_f32_16x16x32_bf16 v[92:95], v[132:135], v[226:229], v[92:95]
	v_mfma_f32_16x16x32_bf16 v[88:91], v[140:143], v[226:229], v[88:91]
	v_mfma_f32_16x16x32_bf16 v[76:79], v[132:135], v[242:245], v[76:79]
	v_mfma_f32_16x16x32_bf16 v[72:75], v[140:143], v[242:245], v[72:75]
	v_mfma_f32_16x16x32_bf16 v[116:119], v[174:177], v[206:209], v[116:119]
	v_mfma_f32_16x16x32_bf16 v[112:115], v[198:201], v[206:209], v[112:115]
	v_mfma_f32_16x16x32_bf16 v[100:103], v[174:177], v[214:217], v[100:103]
	v_mfma_f32_16x16x32_bf16 v[96:99], v[198:201], v[214:217], v[96:99]
	v_mfma_f32_16x16x32_bf16 v[84:87], v[174:177], v[222:225], v[84:87]
	v_mfma_f32_16x16x32_bf16 v[80:83], v[198:201], v[222:225], v[80:83]
	v_mfma_f32_16x16x32_bf16 v[68:71], v[174:177], v[238:241], v[68:71]
	v_mfma_f32_16x16x32_bf16 v[64:67], v[198:201], v[238:241], v[64:67]
	v_mfma_f32_16x16x32_bf16 v[116:119], v[184:187], v[210:213], v[116:119]
	v_mfma_f32_16x16x32_bf16 v[112:115], v[202:205], v[210:213], v[112:115]
	v_mfma_f32_16x16x32_bf16 v[100:103], v[184:187], v[218:221], v[100:103]
	v_mfma_f32_16x16x32_bf16 v[96:99], v[202:205], v[218:221], v[96:99]
	v_mfma_f32_16x16x32_bf16 v[84:87], v[184:187], v[226:229], v[84:87]
	v_mfma_f32_16x16x32_bf16 v[80:83], v[202:205], v[226:229], v[80:83]
	v_mfma_f32_16x16x32_bf16 v[68:71], v[184:187], v[242:245], v[68:71]
	v_mfma_f32_16x16x32_bf16 v[64:67], v[202:205], v[242:245], v[64:67]
	s_setprio 0
	s_barrier
	s_add_i32 s39, s39, s45
	v_lshl_add_u64 v[246:247], s[8:9], 0, v[148:149]
	s_mov_b32 m0, s39
	ds_read_b128 v[206:209], v183 offset:16384
	ds_read_b128 v[210:213], v183 offset:17408
	ds_read_b128 v[214:217], v183 offset:18432
	ds_read_b128 v[218:221], v183 offset:19456
	ds_read_b128 v[222:225], v183 offset:20480
	ds_read_b128 v[226:229], v183 offset:21504
	ds_read_b128 v[238:241], v183 offset:22528
	ds_read_b128 v[242:245], v183 offset:23552
	global_load_lds_dwordx4 v[246:247], off
	s_add_i32 m0, s39, 0x2000
	s_add_u32 s88, s8, 0x80000
	v_lshl_add_u64 v[248:249], s[8:9], 0, v[144:145]
	s_addc_u32 s89, s9, 0
	s_add_i32 s39, s58, s45
	global_load_lds_dwordx4 v[248:249], off
	v_lshl_add_u64 v[250:251], s[88:89], 0, v[148:149]
	s_mov_b32 m0, s39
	v_lshl_add_u64 v[252:253], s[30:31], 0, v[146:147]
	global_load_lds_dwordx4 v[250:251], off
	v_lshl_add_u64 v[250:251], s[88:89], 0, v[144:145]
	s_add_i32 m0, s39, 0x2000
	s_nop 0
	global_load_lds_dwordx4 v[250:251], off
	v_lshl_add_u64 v[250:251], s[30:31], 0, v[150:151]
	s_mov_b32 m0, s63
	s_nop 0
	global_load_lds_dwordx4 v[250:251], off
	s_mov_b32 m0, s66
	s_nop 0
	global_load_lds_dwordx4 v[252:253], off
	s_nop 0
	s_nop 0
	s_waitcnt vmcnt(8)
	s_waitcnt lgkmcnt(0)
	s_barrier
; #define PG8_STAGE(bufoff, gbase, voff) do { _Pragma("unroll") for (int _i = 0; _i < 2; ++_i) \
;         __builtin_amdgcn_global_load_lds((const unsigned*)((const char*)(gbase) + (voff)[_i]), (PG8_LAS unsigned*)(lds + (bufoff) + ldsw + _i * 8192), 16, 0, 0); } while (0)
; #define PG8_LDA(dst, b, h) do { _Pragma("unroll") for (int m = 0; m < 4; ++m) _Pragma("unroll") for (int k = 0; k < 2; ++k) dst[m][k] = *(const PG8_LAS bf16x8*)(lds + PG8_SA(b, h) + aoff + m * 2048 + k * 1024); } while (0)
; #define PG8_LDB(dst, b, h) do { _Pragma("unroll") for (int n = 0; n < 2; ++n) _Pragma("unroll") for (int k = 0; k < 2; ++k) dst[n][k] = *(const PG8_LAS bf16x8*)(lds + PG8_SB(b, h) + boff + n * 2048 + k * 1024); } while (0)
; #define PG8_MMA(ai, bj, At, Bt) do { __builtin_amdgcn_s_setprio(1); _Pragma("unroll") for (int m = 0; m < 4; ++m) _Pragma("unroll") for (int n = 0; n < 2; ++n) _Pragma("unroll") for (int k = 0; k < 2; ++k) \
;         acc[ai][bj][m][n] = __builtin_amdgcn_mfma_f32_16x16x32_bf16(Bt[n][k], At[m][k], acc[ai][bj][m][n], 0, 0, 0); __builtin_amdgcn_s_setprio(0); } while (0)
; #define PG8_WAIT_V(n) asm volatile("s_waitcnt vmcnt(" #n ")" ::: "memory")
; #define PG8_WAIT_L(n) asm volatile("s_waitcnt lgkmcnt(" #n ")" ::: "memory")
; #define PG8_BAR __builtin_amdgcn_s_barrier()
; #define PG8_SCHED __builtin_amdgcn_sched_barrier(0)
; template <class Epi, class Sched, bool ALIGN_EPI = false, bool SP2 = false>
; __device__ __forceinline__ void gemm_phase(PG8_LAS unsigned char* lds, const Gemm g, const Sched& S, const Epi& E) {
;     ...
;             PG8_WAIT_V(8); PG8_WAIT_L(0); PG8_BAR; PG8_MMA(1, 0, At, B0); PG8_MMA(1, 1, At, B1); PG8_BAR; PG8_SCHED;
;             PG8_LDB(B0, 1, 0); PG8_LDB(B1, 1, 1); PG8_SCHED; PG8_LDA(At, 1, 0); PG8_STAGE(PG8_SA(0, 1), a2 + hstep, voffA);
;             PG8_WAIT_V(8); PG8_WAIT_L(0); PG8_BAR; PG8_MMA(0, 0, At, B0); PG8_MMA(0, 1, At, B1); PG8_BAR; PG8_SCHED;
	s_setprio 1
	v_mfma_f32_16x16x32_bf16 v[60:63], v[128:131], v[206:209], v[60:63]
	v_mfma_f32_16x16x32_bf16 v[56:59], v[136:139], v[206:209], v[56:59]
	v_mfma_f32_16x16x32_bf16 v[44:47], v[128:131], v[214:217], v[44:47]
	v_mfma_f32_16x16x32_bf16 v[40:43], v[136:139], v[214:217], v[40:43]
	v_mfma_f32_16x16x32_bf16 v[28:31], v[128:131], v[222:225], v[28:31]
	v_mfma_f32_16x16x32_bf16 v[24:27], v[136:139], v[222:225], v[24:27]
	v_mfma_f32_16x16x32_bf16 v[12:15], v[128:131], v[238:241], v[12:15]
	v_mfma_f32_16x16x32_bf16 v[8:11], v[136:139], v[238:241], v[8:11]
	v_mfma_f32_16x16x32_bf16 v[60:63], v[132:135], v[210:213], v[60:63]
	v_mfma_f32_16x16x32_bf16 v[56:59], v[140:143], v[210:213], v[56:59]
	v_mfma_f32_16x16x32_bf16 v[44:47], v[132:135], v[218:221], v[44:47]
	v_mfma_f32_16x16x32_bf16 v[40:43], v[140:143], v[218:221], v[40:43]
	v_mfma_f32_16x16x32_bf16 v[28:31], v[132:135], v[226:229], v[28:31]
	v_mfma_f32_16x16x32_bf16 v[24:27], v[140:143], v[226:229], v[24:27]
	v_mfma_f32_16x16x32_bf16 v[12:15], v[132:135], v[242:245], v[12:15]
	v_mfma_f32_16x16x32_bf16 v[8:11], v[140:143], v[242:245], v[8:11]
	v_mfma_f32_16x16x32_bf16 v[52:55], v[174:177], v[206:209], v[52:55]
	v_mfma_f32_16x16x32_bf16 v[48:51], v[198:201], v[206:209], v[48:51]
	v_mfma_f32_16x16x32_bf16 v[36:39], v[174:177], v[214:217], v[36:39]
	v_mfma_f32_16x16x32_bf16 v[32:35], v[198:201], v[214:217], v[32:35]
	v_mfma_f32_16x16x32_bf16 v[20:23], v[174:177], v[222:225], v[20:23]
	v_mfma_f32_16x16x32_bf16 v[16:19], v[198:201], v[222:225], v[16:19]
	v_mfma_f32_16x16x32_bf16 v[4:7], v[174:177], v[238:241], v[4:7]
	v_mfma_f32_16x16x32_bf16 v[0:3], v[198:201], v[238:241], v[0:3]
	v_mfma_f32_16x16x32_bf16 v[52:55], v[184:187], v[210:213], v[52:55]
	v_mfma_f32_16x16x32_bf16 v[48:51], v[202:205], v[210:213], v[48:51]
	v_mfma_f32_16x16x32_bf16 v[36:39], v[184:187], v[218:221], v[36:39]
	v_mfma_f32_16x16x32_bf16 v[32:35], v[202:205], v[218:221], v[32:35]
	v_mfma_f32_16x16x32_bf16 v[20:23], v[184:187], v[226:229], v[20:23]
	v_mfma_f32_16x16x32_bf16 v[16:19], v[202:205], v[226:229], v[16:19]
	v_mfma_f32_16x16x32_bf16 v[4:7], v[184:187], v[242:245], v[4:7]
	v_mfma_f32_16x16x32_bf16 v[0:3], v[202:205], v[242:245], v[0:3]
	s_setprio 0
	s_barrier
	s_add_i32 s39, 0, 0x18000
	s_add_i32 s58, 0, 0x1c000
	v_add_u32_e32 v140, s39, v181
	v_add_u32_e32 v178, s58, v181
	ds_read_b128 v[128:131], v140
	ds_read_b128 v[132:135], v140 offset:1024
	ds_read_b128 v[136:139], v140 offset:2048
	ds_read_b128 v[140:143], v140 offset:3072
	ds_read_b128 v[174:177], v178
	ds_read_b128 v[184:187], v178 offset:1024
	ds_read_b128 v[198:201], v178 offset:2048
	ds_read_b128 v[202:205], v178 offset:3072
	s_add_u32 s30, s30, 0x80000
	s_addc_u32 s31, s31, 0
	s_mov_b32 m0, s67
	v_lshl_add_u64 v[232:233], s[30:31], 0, v[150:151]
	ds_read_b128 v[206:209], v183 offset:32768
	ds_read_b128 v[210:213], v183 offset:33792
	ds_read_b128 v[214:217], v183 offset:34816
	ds_read_b128 v[218:221], v183 offset:35840
	ds_read_b128 v[222:225], v183 offset:36864
	ds_read_b128 v[226:229], v183 offset:37888
	ds_read_b128 v[238:241], v183 offset:38912
	ds_read_b128 v[242:245], v183 offset:39936
	global_load_lds_dwordx4 v[232:233], off
	v_lshl_add_u64 v[232:233], s[30:31], 0, v[146:147]
	s_mov_b32 m0, s72
	s_nop 0
	global_load_lds_dwordx4 v[232:233], off
	s_nop 0
	s_nop 0
	s_nop 0
	s_nop 0
	s_nop 0
	s_nop 0
	s_waitcnt vmcnt(8)
	s_waitcnt lgkmcnt(0)
	s_barrier
	s_setprio 1
	v_mfma_f32_16x16x32_bf16 v[124:127], v[128:131], v[206:209], v[124:127]
	v_mfma_f32_16x16x32_bf16 v[120:123], v[136:139], v[206:209], v[120:123]
	v_mfma_f32_16x16x32_bf16 v[108:111], v[128:131], v[214:217], v[108:111]
	v_mfma_f32_16x16x32_bf16 v[104:107], v[136:139], v[214:217], v[104:107]
	v_mfma_f32_16x16x32_bf16 v[92:95], v[128:131], v[222:225], v[92:95]
	v_mfma_f32_16x16x32_bf16 v[88:91], v[136:139], v[222:225], v[88:91]
	v_mfma_f32_16x16x32_bf16 v[76:79], v[128:131], v[238:241], v[76:79]
	v_mfma_f32_16x16x32_bf16 v[72:75], v[136:139], v[238:241], v[72:75]
	v_mfma_f32_16x16x32_bf16 v[124:127], v[132:135], v[210:213], v[124:127]
	v_mfma_f32_16x16x32_bf16 v[120:123], v[140:143], v[210:213], v[120:123]
	v_mfma_f32_16x16x32_bf16 v[108:111], v[132:135], v[218:221], v[108:111]
	v_mfma_f32_16x16x32_bf16 v[104:107], v[140:143], v[218:221], v[104:107]
	v_mfma_f32_16x16x32_bf16 v[92:95], v[132:135], v[226:229], v[92:95]
	v_mfma_f32_16x16x32_bf16 v[88:91], v[140:143], v[226:229], v[88:91]
	v_mfma_f32_16x16x32_bf16 v[76:79], v[132:135], v[242:245], v[76:79]
	v_mfma_f32_16x16x32_bf16 v[72:75], v[140:143], v[242:245], v[72:75]
	v_mfma_f32_16x16x32_bf16 v[116:119], v[174:177], v[206:209], v[116:119]
	v_mfma_f32_16x16x32_bf16 v[112:115], v[198:201], v[206:209], v[112:115]
	v_mfma_f32_16x16x32_bf16 v[100:103], v[174:177], v[214:217], v[100:103]
	v_mfma_f32_16x16x32_bf16 v[96:99], v[198:201], v[214:217], v[96:99]
	v_mfma_f32_16x16x32_bf16 v[84:87], v[174:177], v[222:225], v[84:87]
	v_mfma_f32_16x16x32_bf16 v[80:83], v[198:201], v[222:225], v[80:83]
	v_mfma_f32_16x16x32_bf16 v[68:71], v[174:177], v[238:241], v[68:71]
	v_mfma_f32_16x16x32_bf16 v[64:67], v[198:201], v[238:241], v[64:67]
	v_mfma_f32_16x16x32_bf16 v[116:119], v[184:187], v[210:213], v[116:119]
	v_mfma_f32_16x16x32_bf16 v[112:115], v[202:205], v[210:213], v[112:115]
	v_mfma_f32_16x16x32_bf16 v[100:103], v[184:187], v[218:221], v[100:103]
	v_mfma_f32_16x16x32_bf16 v[96:99], v[202:205], v[218:221], v[96:99]
	v_mfma_f32_16x16x32_bf16 v[84:87], v[184:187], v[226:229], v[84:87]
	v_mfma_f32_16x16x32_bf16 v[80:83], v[202:205], v[226:229], v[80:83]
	v_mfma_f32_16x16x32_bf16 v[68:71], v[184:187], v[242:245], v[68:71]
	v_mfma_f32_16x16x32_bf16 v[64:67], v[202:205], v[242:245], v[64:67]
	s_setprio 0
	s_barrier
; #define PG8_STAGE(bufoff, gbase, voff) do { _Pragma("unroll") for (int _i = 0; _i < 2; ++_i) \
;         __builtin_amdgcn_global_load_lds((const unsigned*)((const char*)(gbase) + (voff)[_i]), (PG8_LAS unsigned*)(lds + (bufoff) + ldsw + _i * 8192), 16, 0, 0); } while (0)
; #define PG8_LDA(dst, b, h) do { _Pragma("unroll") for (int m = 0; m < 4; ++m) _Pragma("unroll") for (int k = 0; k < 2; ++k) dst[m][k] = *(const PG8_LAS bf16x8*)(lds + PG8_SA(b, h) + aoff + m * 2048 + k * 1024); } while (0)
; #define PG8_MMA(ai, bj, At, Bt) do { __builtin_amdgcn_s_setprio(1); _Pragma("unroll") for (int m = 0; m < 4; ++m) _Pragma("unroll") for (int n = 0; n < 2; ++n) _Pragma("unroll") for (int k = 0; k < 2; ++k) \
;         acc[ai][bj][m][n] = __builtin_amdgcn_mfma_f32_16x16x32_bf16(Bt[n][k], At[m][k], acc[ai][bj][m][n], 0, 0, 0); __builtin_amdgcn_s_setprio(0); } while (0)
; #define PG8_WAIT_V(n) asm volatile("s_waitcnt vmcnt(" #n ")" ::: "memory")
; #define PG8_WAIT_L(n) asm volatile("s_waitcnt lgkmcnt(" #n ")" ::: "memory")
; #define PG8_BAR __builtin_amdgcn_s_barrier()
; #define PG8_SCHED __builtin_amdgcn_sched_barrier(0)
; template <class Epi, class Sched, bool ALIGN_EPI = false, bool SP2 = false>
; __device__ __forceinline__ void gemm_phase(PG8_LAS unsigned char* lds, const Gemm g, const Sched& S, const Epi& E) {
;     ...
;             PG8_LDA(At, 1, 1); PG8_STAGE(PG8_SB(1, 0), b3, voffB); PG8_STAGE(PG8_SB(1, 1), b3 + hstep, voffB); PG8_STAGE(PG8_SA(1, 0), a3, voffA);
;             PG8_WAIT_V(8); PG8_WAIT_L(0); PG8_BAR; PG8_MMA(1, 0, At, B0); PG8_MMA(1, 1, At, B1); PG8_BAR; PG8_SCHED;
	s_add_i32 s30, s39, s45
	v_lshl_add_u64 v[232:233], v[246:247], 0, s[78:79]
	s_mov_b32 m0, s30
	ds_read_b128 v[206:209], v183 offset:49152
	ds_read_b128 v[210:213], v183 offset:50176
	ds_read_b128 v[214:217], v183 offset:51200
	ds_read_b128 v[218:221], v183 offset:52224
	ds_read_b128 v[222:225], v183 offset:53248
	ds_read_b128 v[226:229], v183 offset:54272
	ds_read_b128 v[238:241], v183 offset:55296
	ds_read_b128 v[242:245], v183 offset:56320
	global_load_lds_dwordx4 v[232:233], off
	s_add_i32 m0, s30, 0x2000
	s_add_u32 s8, s8, 0x80080
	v_lshl_add_u64 v[232:233], v[248:249], 0, s[78:79]
	s_addc_u32 s9, s9, 0
	s_add_i32 s30, s58, s45
	global_load_lds_dwordx4 v[232:233], off
	v_lshl_add_u64 v[232:233], s[8:9], 0, v[148:149]
	s_mov_b32 m0, s30
	s_nop 0
	global_load_lds_dwordx4 v[232:233], off
	v_lshl_add_u64 v[232:233], s[8:9], 0, v[144:145]
	s_add_i32 m0, s30, 0x2000
	s_nop 0
	global_load_lds_dwordx4 v[232:233], off
	v_lshl_add_u64 v[232:233], v[250:251], 0, s[78:79]
	s_mov_b32 m0, s73
	s_nop 0
	global_load_lds_dwordx4 v[232:233], off
	v_lshl_add_u64 v[232:233], v[252:253], 0, s[78:79]
	s_mov_b32 m0, s74
	s_nop 0
	global_load_lds_dwordx4 v[232:233], off
	s_nop 0
	s_waitcnt vmcnt(8)
	s_waitcnt lgkmcnt(0)
	s_barrier
	s_setprio 1
	v_mfma_f32_16x16x32_bf16 v[60:63], v[128:131], v[206:209], v[60:63]
	v_mfma_f32_16x16x32_bf16 v[56:59], v[136:139], v[206:209], v[56:59]
	v_mfma_f32_16x16x32_bf16 v[44:47], v[128:131], v[214:217], v[44:47]
	v_mfma_f32_16x16x32_bf16 v[40:43], v[136:139], v[214:217], v[40:43]
	v_mfma_f32_16x16x32_bf16 v[28:31], v[128:131], v[222:225], v[28:31]
	v_mfma_f32_16x16x32_bf16 v[24:27], v[136:139], v[222:225], v[24:27]
	v_mfma_f32_16x16x32_bf16 v[12:15], v[128:131], v[238:241], v[12:15]
	v_mfma_f32_16x16x32_bf16 v[8:11], v[136:139], v[238:241], v[8:11]
	v_mfma_f32_16x16x32_bf16 v[60:63], v[132:135], v[210:213], v[60:63]
	v_mfma_f32_16x16x32_bf16 v[56:59], v[140:143], v[210:213], v[56:59]
	v_mfma_f32_16x16x32_bf16 v[44:47], v[132:135], v[218:221], v[44:47]
	v_mfma_f32_16x16x32_bf16 v[40:43], v[140:143], v[218:221], v[40:43]
	v_mfma_f32_16x16x32_bf16 v[28:31], v[132:135], v[226:229], v[28:31]
	v_mfma_f32_16x16x32_bf16 v[24:27], v[140:143], v[226:229], v[24:27]
	v_mfma_f32_16x16x32_bf16 v[12:15], v[132:135], v[242:245], v[12:15]
	v_mfma_f32_16x16x32_bf16 v[8:11], v[140:143], v[242:245], v[8:11]
	v_mfma_f32_16x16x32_bf16 v[52:55], v[174:177], v[206:209], v[52:55]
	v_mfma_f32_16x16x32_bf16 v[48:51], v[198:201], v[206:209], v[48:51]
	v_mfma_f32_16x16x32_bf16 v[36:39], v[174:177], v[214:217], v[36:39]
	v_mfma_f32_16x16x32_bf16 v[32:35], v[198:201], v[214:217], v[32:35]
	v_mfma_f32_16x16x32_bf16 v[20:23], v[174:177], v[222:225], v[20:23]
	v_mfma_f32_16x16x32_bf16 v[16:19], v[198:201], v[222:225], v[16:19]
	v_mfma_f32_16x16x32_bf16 v[4:7], v[174:177], v[238:241], v[4:7]
	v_mfma_f32_16x16x32_bf16 v[0:3], v[198:201], v[238:241], v[0:3]
	v_mfma_f32_16x16x32_bf16 v[52:55], v[184:187], v[210:213], v[52:55]
	v_mfma_f32_16x16x32_bf16 v[48:51], v[202:205], v[210:213], v[48:51]
	v_mfma_f32_16x16x32_bf16 v[36:39], v[184:187], v[218:221], v[36:39]
	v_mfma_f32_16x16x32_bf16 v[32:35], v[202:205], v[218:221], v[32:35]
	v_mfma_f32_16x16x32_bf16 v[20:23], v[184:187], v[226:229], v[20:23]
	v_mfma_f32_16x16x32_bf16 v[16:19], v[202:205], v[226:229], v[16:19]
	v_mfma_f32_16x16x32_bf16 v[4:7], v[184:187], v[242:245], v[4:7]
	v_mfma_f32_16x16x32_bf16 v[0:3], v[202:205], v[242:245], v[0:3]
	s_setprio 0
	s_barrier
	s_add_i32 s38, s38, 2
	s_add_u32 s6, s6, 0x100
	s_addc_u32 s7, s7, 0
	s_add_u32 s36, s36, 0x100
	s_addc_u32 s37, s37, 0
	s_cmp_gt_u32 s38, 29
	s_cbranch_scc0 .LBB0_148
	s_and_b64 vcc, exec, s[20:21]
	s_cbranch_vccz .LBB0_151
	s_barrier

; #define PG8_STAGE(bufoff, gbase, voff) do { _Pragma("unroll") for (int _i = 0; _i < 2; ++_i) \
;         __builtin_amdgcn_global_load_lds((const unsigned*)((const char*)(gbase) + (voff)[_i]), (PG8_LAS unsigned*)(lds + (bufoff) + ldsw + _i * 8192), 16, 0, 0); } while (0)
; #define PG8_LDA(dst, b, h) do { _Pragma("unroll") for (int m = 0; m < 4; ++m) _Pragma("unroll") for (int k = 0; k < 2; ++k) dst[m][k] = *(const PG8_LAS bf16x8*)(lds + PG8_SA(b, h) + aoff + m * 2048 + k * 1024); } while (0)
; #define PG8_LDB(dst, b, h) do { _Pragma("unroll") for (int n = 0; n < 2; ++n) _Pragma("unroll") for (int k = 0; k < 2; ++k) dst[n][k] = *(const PG8_LAS bf16x8*)(lds + PG8_SB(b, h) + boff + n * 2048 + k * 1024); } while (0)
; #define PG8_MMA(ai, bj, At, Bt) do { __builtin_amdgcn_s_setprio(1); _Pragma("unroll") for (int m = 0; m < 4; ++m) _Pragma("unroll") for (int n = 0; n < 2; ++n) _Pragma("unroll") for (int k = 0; k < 2; ++k) \
;         acc[ai][bj][m][n] = __builtin_amdgcn_mfma_f32_16x16x32_bf16(Bt[n][k], At[m][k], acc[ai][bj][m][n], 0, 0, 0); __builtin_amdgcn_s_setprio(0); } while (0)
; #define PG8_WAIT_V(n) asm volatile("s_waitcnt vmcnt(" #n ")" ::: "memory")
; #define PG8_WAIT_L(n) asm volatile("s_waitcnt lgkmcnt(" #n ")" ::: "memory")
; #define PG8_BAR __builtin_amdgcn_s_barrier()
; #define PG8_SCHED __builtin_amdgcn_sched_barrier(0)
; template <class Epi, class Sched, bool ALIGN_EPI = false, bool SP2 = false>
; __device__ __forceinline__ void gemm_phase(PG8_LAS unsigned char* lds, const Gemm g, const Sched& S, const Epi& E) {
;     ...
;             const bool last = (t == nt - 2);
;             const char* a1 = cA + (size_t)(t + 1) * kstep;
;             const char* a2 = last ? nA : cA + (size_t)(t + 2) * kstep; const char* b2 = last ? nB : cB + (size_t)(t + 2) * kstep;
;             const char* a3 = a2 + kstep; const char* b3 = b2 + kstep;
;             if (last && has_next) S.a_ready(nxt);
;             if constexpr (SP2) {
;             PG8_LDB(B0, 0, 0); PG8_LDB(B1, 0, 1); PG8_SCHED; PG8_LDA(At, 0, 0); PG8_STAGE(PG8_SA(1, 1), a1 + hstep, voffA);
;             PG8_WAIT_V(8); PG8_WAIT_L(0); PG8_BAR; PG8_MMA(0, 0, At, B0); PG8_MMA(0, 1, At, B1); PG8_BAR; PG8_SCHED;
;             PG8_LDA(At, 0, 1); PG8_STAGE(PG8_SB(0, 0), b2, voffB); PG8_STAGE(PG8_SB(0, 1), b2 + hstep, voffB); PG8_STAGE(PG8_SA(0, 0), a2, voffA);
.LBB0_424:
	s_add_u32 s8, s6, 0xfffc0080
	s_addc_u32 s9, s7, -1
	s_add_i32 s60, 0, 0x10000
	s_cmp_eq_u32 s58, 12
	s_cselect_b32 s25, s17, s9
	s_cselect_b32 s24, s38, s8
	s_cselect_b32 s9, s19, s52
	s_cselect_b32 s8, s39, s45
	s_add_i32 s62, 0, 0x14000
	v_add_u32_e32 v140, s60, v201
	v_add_u32_e32 v156, s62, v201
	ds_read_b128 v[128:131], v140
	ds_read_b128 v[132:135], v140 offset:1024
	ds_read_b128 v[136:139], v140 offset:2048
	ds_read_b128 v[140:143], v140 offset:3072
	ds_read_b128 v[144:147], v156
	ds_read_b128 v[148:151], v156 offset:1024
	ds_read_b128 v[152:155], v156 offset:2048
	ds_read_b128 v[156:159], v156 offset:3072
	v_lshl_add_u64 v[198:199], s[6:7], 0, v[168:169]
	s_add_i32 m0, s31, 0xc000
	ds_read_b128 v[172:175], v203
	ds_read_b128 v[176:179], v203 offset:1024
	ds_read_b128 v[180:183], v203 offset:2048
	ds_read_b128 v[184:187], v203 offset:3072
	ds_read_b128 v[204:207], v203 offset:4096
	ds_read_b128 v[208:211], v203 offset:5120
	ds_read_b128 v[212:215], v203 offset:6144
	ds_read_b128 v[216:219], v203 offset:7168
	global_load_lds_dwordx4 v[198:199], off
	v_lshl_add_u64 v[198:199], s[6:7], 0, v[170:171]
	s_add_i32 m0, s31, 0xe000
	s_nop 0
	global_load_lds_dwordx4 v[198:199], off
	s_waitcnt vmcnt(8)
	s_waitcnt lgkmcnt(0)
	s_barrier
	s_setprio 1
	v_mfma_f32_16x16x32_bf16 v[124:127], v[128:131], v[172:175], v[124:127]
	v_mfma_f32_16x16x32_bf16 v[120:123], v[136:139], v[172:175], v[120:123]
	v_mfma_f32_16x16x32_bf16 v[116:119], v[128:131], v[180:183], v[116:119]
	v_mfma_f32_16x16x32_bf16 v[112:115], v[136:139], v[180:183], v[112:115]
	v_mfma_f32_16x16x32_bf16 v[108:111], v[128:131], v[204:207], v[108:111]
	v_mfma_f32_16x16x32_bf16 v[104:107], v[136:139], v[204:207], v[104:107]
	v_mfma_f32_16x16x32_bf16 v[100:103], v[128:131], v[212:215], v[100:103]
	v_mfma_f32_16x16x32_bf16 v[96:99], v[136:139], v[212:215], v[96:99]
	v_mfma_f32_16x16x32_bf16 v[124:127], v[132:135], v[176:179], v[124:127]
	v_mfma_f32_16x16x32_bf16 v[120:123], v[140:143], v[176:179], v[120:123]
	v_mfma_f32_16x16x32_bf16 v[116:119], v[132:135], v[184:187], v[116:119]
	v_mfma_f32_16x16x32_bf16 v[112:115], v[140:143], v[184:187], v[112:115]
	v_mfma_f32_16x16x32_bf16 v[108:111], v[132:135], v[208:211], v[108:111]
	v_mfma_f32_16x16x32_bf16 v[104:107], v[140:143], v[208:211], v[104:107]
	v_mfma_f32_16x16x32_bf16 v[100:103], v[132:135], v[216:219], v[100:103]
	v_mfma_f32_16x16x32_bf16 v[96:99], v[140:143], v[216:219], v[96:99]
	v_mfma_f32_16x16x32_bf16 v[92:95], v[144:147], v[172:175], v[92:95]
	v_mfma_f32_16x16x32_bf16 v[88:91], v[152:155], v[172:175], v[88:91]
	v_mfma_f32_16x16x32_bf16 v[84:87], v[144:147], v[180:183], v[84:87]
	v_mfma_f32_16x16x32_bf16 v[80:83], v[152:155], v[180:183], v[80:83]
	v_mfma_f32_16x16x32_bf16 v[76:79], v[144:147], v[204:207], v[76:79]
	v_mfma_f32_16x16x32_bf16 v[72:75], v[152:155], v[204:207], v[72:75]
	v_mfma_f32_16x16x32_bf16 v[68:71], v[144:147], v[212:215], v[68:71]
	v_mfma_f32_16x16x32_bf16 v[64:67], v[152:155], v[212:215], v[64:67]
	v_mfma_f32_16x16x32_bf16 v[92:95], v[148:151], v[176:179], v[92:95]
	v_mfma_f32_16x16x32_bf16 v[88:91], v[156:159], v[176:179], v[88:91]
	v_mfma_f32_16x16x32_bf16 v[84:87], v[148:151], v[184:187], v[84:87]
	v_mfma_f32_16x16x32_bf16 v[80:83], v[156:159], v[184:187], v[80:83]
	v_mfma_f32_16x16x32_bf16 v[76:79], v[148:151], v[208:211], v[76:79]
	v_mfma_f32_16x16x32_bf16 v[72:75], v[156:159], v[208:211], v[72:75]
	v_mfma_f32_16x16x32_bf16 v[68:71], v[148:151], v[216:219], v[68:71]
	v_mfma_f32_16x16x32_bf16 v[64:67], v[156:159], v[216:219], v[64:67]
	s_setprio 0
	s_barrier
	s_add_i32 s60, s60, s30
	v_lshl_add_u64 v[198:199], s[8:9], 0, v[164:165]
	s_mov_b32 m0, s60
	ds_read_b128 v[172:175], v203 offset:16384
	ds_read_b128 v[176:179], v203 offset:17408
	ds_read_b128 v[180:183], v203 offset:18432
	ds_read_b128 v[184:187], v203 offset:19456
	ds_read_b128 v[204:207], v203 offset:20480
	ds_read_b128 v[208:211], v203 offset:21504
	ds_read_b128 v[212:215], v203 offset:22528
	ds_read_b128 v[216:219], v203 offset:23552
	global_load_lds_dwordx4 v[198:199], off
	s_add_i32 m0, s60, 0x2000
	s_add_u32 s60, s8, 0x40000
	v_lshl_add_u64 v[220:221], s[8:9], 0, v[160:161]
	s_addc_u32 s61, s9, 0
	s_add_i32 s62, s62, s30
	global_load_lds_dwordx4 v[220:221], off
	v_lshl_add_u64 v[222:223], s[60:61], 0, v[164:165]
	s_mov_b32 m0, s62
	v_lshl_add_u64 v[224:225], s[24:25], 0, v[162:163]
	global_load_lds_dwordx4 v[222:223], off
	v_lshl_add_u64 v[222:223], s[60:61], 0, v[160:161]
	s_add_i32 m0, s62, 0x2000
	s_nop 0
	global_load_lds_dwordx4 v[222:223], off
	v_lshl_add_u64 v[222:223], s[24:25], 0, v[166:167]
	s_mov_b32 m0, s31
	s_nop 0
	global_load_lds_dwordx4 v[222:223], off
	s_mov_b32 m0, s34
	s_nop 0
	global_load_lds_dwordx4 v[224:225], off
	s_nop 0
	s_nop 0
	s_waitcnt vmcnt(8)
	s_waitcnt lgkmcnt(0)
	s_barrier
; #define PG8_STAGE(bufoff, gbase, voff) do { _Pragma("unroll") for (int _i = 0; _i < 2; ++_i) \
;         __builtin_amdgcn_global_load_lds((const unsigned*)((const char*)(gbase) + (voff)[_i]), (PG8_LAS unsigned*)(lds + (bufoff) + ldsw + _i * 8192), 16, 0, 0); } while (0)
; #define PG8_LDA(dst, b, h) do { _Pragma("unroll") for (int m = 0; m < 4; ++m) _Pragma("unroll") for (int k = 0; k < 2; ++k) dst[m][k] = *(const PG8_LAS bf16x8*)(lds + PG8_SA(b, h) + aoff + m * 2048 + k * 1024); } while (0)
; #define PG8_LDB(dst, b, h) do { _Pragma("unroll") for (int n = 0; n < 2; ++n) _Pragma("unroll") for (int k = 0; k < 2; ++k) dst[n][k] = *(const PG8_LAS bf16x8*)(lds + PG8_SB(b, h) + boff + n * 2048 + k * 1024); } while (0)
; #define PG8_MMA(ai, bj, At, Bt) do { __builtin_amdgcn_s_setprio(1); _Pragma("unroll") for (int m = 0; m < 4; ++m) _Pragma("unroll") for (int n = 0; n < 2; ++n) _Pragma("unroll") for (int k = 0; k < 2; ++k) \
;         acc[ai][bj][m][n] = __builtin_amdgcn_mfma_f32_16x16x32_bf16(Bt[n][k], At[m][k], acc[ai][bj][m][n], 0, 0, 0); __builtin_amdgcn_s_setprio(0); } while (0)
; #define PG8_WAIT_V(n) asm volatile("s_waitcnt vmcnt(" #n ")" ::: "memory")
; #define PG8_WAIT_L(n) asm volatile("s_waitcnt lgkmcnt(" #n ")" ::: "memory")
; #define PG8_BAR __builtin_amdgcn_s_barrier()
; #define PG8_SCHED __builtin_amdgcn_sched_barrier(0)
; template <class Epi, class Sched, bool ALIGN_EPI = false, bool SP2 = false>
; __device__ __forceinline__ void gemm_phase(PG8_LAS unsigned char* lds, const Gemm g, const Sched& S, const Epi& E) {
;     ...
;             PG8_WAIT_V(8); PG8_WAIT_L(0); PG8_BAR; PG8_MMA(1, 0, At, B0); PG8_MMA(1, 1, At, B1); PG8_BAR; PG8_SCHED;
;             PG8_LDB(B0, 1, 0); PG8_LDB(B1, 1, 1); PG8_SCHED; PG8_LDA(At, 1, 0); PG8_STAGE(PG8_SA(0, 1), a2 + hstep, voffA);
;             PG8_WAIT_V(8); PG8_WAIT_L(0); PG8_BAR; PG8_MMA(0, 0, At, B0); PG8_MMA(0, 1, At, B1); PG8_BAR; PG8_SCHED;
	s_setprio 1
	v_mfma_f32_16x16x32_bf16 v[60:63], v[128:131], v[172:175], v[60:63]
	v_mfma_f32_16x16x32_bf16 v[56:59], v[136:139], v[172:175], v[56:59]
	v_mfma_f32_16x16x32_bf16 v[52:55], v[128:131], v[180:183], v[52:55]
	v_mfma_f32_16x16x32_bf16 v[48:51], v[136:139], v[180:183], v[48:51]
	v_mfma_f32_16x16x32_bf16 v[44:47], v[128:131], v[204:207], v[44:47]
	v_mfma_f32_16x16x32_bf16 v[40:43], v[136:139], v[204:207], v[40:43]
	v_mfma_f32_16x16x32_bf16 v[36:39], v[128:131], v[212:215], v[36:39]
	v_mfma_f32_16x16x32_bf16 v[32:35], v[136:139], v[212:215], v[32:35]
	v_mfma_f32_16x16x32_bf16 v[60:63], v[132:135], v[176:179], v[60:63]
	v_mfma_f32_16x16x32_bf16 v[56:59], v[140:143], v[176:179], v[56:59]
	v_mfma_f32_16x16x32_bf16 v[52:55], v[132:135], v[184:187], v[52:55]
	v_mfma_f32_16x16x32_bf16 v[48:51], v[140:143], v[184:187], v[48:51]
	v_mfma_f32_16x16x32_bf16 v[44:47], v[132:135], v[208:211], v[44:47]
	v_mfma_f32_16x16x32_bf16 v[40:43], v[140:143], v[208:211], v[40:43]
	v_mfma_f32_16x16x32_bf16 v[36:39], v[132:135], v[216:219], v[36:39]
	v_mfma_f32_16x16x32_bf16 v[32:35], v[140:143], v[216:219], v[32:35]
	v_mfma_f32_16x16x32_bf16 v[28:31], v[144:147], v[172:175], v[28:31]
	v_mfma_f32_16x16x32_bf16 v[24:27], v[152:155], v[172:175], v[24:27]
	v_mfma_f32_16x16x32_bf16 v[20:23], v[144:147], v[180:183], v[20:23]
	v_mfma_f32_16x16x32_bf16 v[16:19], v[152:155], v[180:183], v[16:19]
	v_mfma_f32_16x16x32_bf16 v[12:15], v[144:147], v[204:207], v[12:15]
	v_mfma_f32_16x16x32_bf16 v[8:11], v[152:155], v[204:207], v[8:11]
	v_mfma_f32_16x16x32_bf16 v[4:7], v[144:147], v[212:215], v[4:7]
	v_mfma_f32_16x16x32_bf16 v[0:3], v[152:155], v[212:215], v[0:3]
	v_mfma_f32_16x16x32_bf16 v[28:31], v[148:151], v[176:179], v[28:31]
	v_mfma_f32_16x16x32_bf16 v[24:27], v[156:159], v[176:179], v[24:27]
	v_mfma_f32_16x16x32_bf16 v[20:23], v[148:151], v[184:187], v[20:23]
	v_mfma_f32_16x16x32_bf16 v[16:19], v[156:159], v[184:187], v[16:19]
	v_mfma_f32_16x16x32_bf16 v[12:15], v[148:151], v[208:211], v[12:15]
	v_mfma_f32_16x16x32_bf16 v[8:11], v[156:159], v[208:211], v[8:11]
	v_mfma_f32_16x16x32_bf16 v[4:7], v[148:151], v[216:219], v[4:7]
	v_mfma_f32_16x16x32_bf16 v[0:3], v[156:159], v[216:219], v[0:3]
	s_setprio 0
	s_barrier
	s_add_i32 s60, 0, 0x18000
	s_add_i32 s61, 0, 0x1c000
	v_add_u32_e32 v140, s60, v201
	v_add_u32_e32 v156, s61, v201
	ds_read_b128 v[128:131], v140
	ds_read_b128 v[132:135], v140 offset:1024
	ds_read_b128 v[136:139], v140 offset:2048
	ds_read_b128 v[140:143], v140 offset:3072
	ds_read_b128 v[144:147], v156
	ds_read_b128 v[148:151], v156 offset:1024
	ds_read_b128 v[152:155], v156 offset:2048
	ds_read_b128 v[156:159], v156 offset:3072
	s_add_u32 s24, s24, 0x40000
	s_addc_u32 s25, s25, 0
	s_mov_b32 m0, s35
	v_lshl_add_u64 v[226:227], s[24:25], 0, v[166:167]
	ds_read_b128 v[172:175], v203 offset:32768
	ds_read_b128 v[176:179], v203 offset:33792
	ds_read_b128 v[180:183], v203 offset:34816
	ds_read_b128 v[184:187], v203 offset:35840
	ds_read_b128 v[204:207], v203 offset:36864
	ds_read_b128 v[208:211], v203 offset:37888
	ds_read_b128 v[212:215], v203 offset:38912
	ds_read_b128 v[216:219], v203 offset:39936
	global_load_lds_dwordx4 v[226:227], off
	v_lshl_add_u64 v[226:227], s[24:25], 0, v[162:163]
	s_mov_b32 m0, s36
	s_nop 0
	global_load_lds_dwordx4 v[226:227], off
	s_nop 0
	s_nop 0
	s_nop 0
	s_nop 0
	s_nop 0
	s_nop 0
	s_waitcnt vmcnt(8)
	s_waitcnt lgkmcnt(0)
	s_barrier
	s_setprio 1
	v_mfma_f32_16x16x32_bf16 v[124:127], v[128:131], v[172:175], v[124:127]
	v_mfma_f32_16x16x32_bf16 v[120:123], v[136:139], v[172:175], v[120:123]
	v_mfma_f32_16x16x32_bf16 v[116:119], v[128:131], v[180:183], v[116:119]
	v_mfma_f32_16x16x32_bf16 v[112:115], v[136:139], v[180:183], v[112:115]
	v_mfma_f32_16x16x32_bf16 v[108:111], v[128:131], v[204:207], v[108:111]
	v_mfma_f32_16x16x32_bf16 v[104:107], v[136:139], v[204:207], v[104:107]
	v_mfma_f32_16x16x32_bf16 v[100:103], v[128:131], v[212:215], v[100:103]
	v_mfma_f32_16x16x32_bf16 v[96:99], v[136:139], v[212:215], v[96:99]
	v_mfma_f32_16x16x32_bf16 v[124:127], v[132:135], v[176:179], v[124:127]
	v_mfma_f32_16x16x32_bf16 v[120:123], v[140:143], v[176:179], v[120:123]
	v_mfma_f32_16x16x32_bf16 v[116:119], v[132:135], v[184:187], v[116:119]
	v_mfma_f32_16x16x32_bf16 v[112:115], v[140:143], v[184:187], v[112:115]
	v_mfma_f32_16x16x32_bf16 v[108:111], v[132:135], v[208:211], v[108:111]
	v_mfma_f32_16x16x32_bf16 v[104:107], v[140:143], v[208:211], v[104:107]
	v_mfma_f32_16x16x32_bf16 v[100:103], v[132:135], v[216:219], v[100:103]
	v_mfma_f32_16x16x32_bf16 v[96:99], v[140:143], v[216:219], v[96:99]
	v_mfma_f32_16x16x32_bf16 v[92:95], v[144:147], v[172:175], v[92:95]
	v_mfma_f32_16x16x32_bf16 v[88:91], v[152:155], v[172:175], v[88:91]
	v_mfma_f32_16x16x32_bf16 v[84:87], v[144:147], v[180:183], v[84:87]
	v_mfma_f32_16x16x32_bf16 v[80:83], v[152:155], v[180:183], v[80:83]
	v_mfma_f32_16x16x32_bf16 v[76:79], v[144:147], v[204:207], v[76:79]
	v_mfma_f32_16x16x32_bf16 v[72:75], v[152:155], v[204:207], v[72:75]
	v_mfma_f32_16x16x32_bf16 v[68:71], v[144:147], v[212:215], v[68:71]
	v_mfma_f32_16x16x32_bf16 v[64:67], v[152:155], v[212:215], v[64:67]
	v_mfma_f32_16x16x32_bf16 v[92:95], v[148:151], v[176:179], v[92:95]
	v_mfma_f32_16x16x32_bf16 v[88:91], v[156:159], v[176:179], v[88:91]
	v_mfma_f32_16x16x32_bf16 v[84:87], v[148:151], v[184:187], v[84:87]
	v_mfma_f32_16x16x32_bf16 v[80:83], v[156:159], v[184:187], v[80:83]
	v_mfma_f32_16x16x32_bf16 v[76:79], v[148:151], v[208:211], v[76:79]
	v_mfma_f32_16x16x32_bf16 v[72:75], v[156:159], v[208:211], v[72:75]
	v_mfma_f32_16x16x32_bf16 v[68:71], v[148:151], v[216:219], v[68:71]
	v_mfma_f32_16x16x32_bf16 v[64:67], v[156:159], v[216:219], v[64:67]
	s_setprio 0
	s_barrier
; #define PG8_STAGE(bufoff, gbase, voff) do { _Pragma("unroll") for (int _i = 0; _i < 2; ++_i) \
;         __builtin_amdgcn_global_load_lds((const unsigned*)((const char*)(gbase) + (voff)[_i]), (PG8_LAS unsigned*)(lds + (bufoff) + ldsw + _i * 8192), 16, 0, 0); } while (0)
; #define PG8_LDA(dst, b, h) do { _Pragma("unroll") for (int m = 0; m < 4; ++m) _Pragma("unroll") for (int k = 0; k < 2; ++k) dst[m][k] = *(const PG8_LAS bf16x8*)(lds + PG8_SA(b, h) + aoff + m * 2048 + k * 1024); } while (0)
; #define PG8_MMA(ai, bj, At, Bt) do { __builtin_amdgcn_s_setprio(1); _Pragma("unroll") for (int m = 0; m < 4; ++m) _Pragma("unroll") for (int n = 0; n < 2; ++n) _Pragma("unroll") for (int k = 0; k < 2; ++k) \
;         acc[ai][bj][m][n] = __builtin_amdgcn_mfma_f32_16x16x32_bf16(Bt[n][k], At[m][k], acc[ai][bj][m][n], 0, 0, 0); __builtin_amdgcn_s_setprio(0); } while (0)
; #define PG8_WAIT_V(n) asm volatile("s_waitcnt vmcnt(" #n ")" ::: "memory")
; #define PG8_WAIT_L(n) asm volatile("s_waitcnt lgkmcnt(" #n ")" ::: "memory")
; #define PG8_BAR __builtin_amdgcn_s_barrier()
; #define PG8_SCHED __builtin_amdgcn_sched_barrier(0)
; template <class Epi, class Sched, bool ALIGN_EPI = false, bool SP2 = false>
; __device__ __forceinline__ void gemm_phase(PG8_LAS unsigned char* lds, const Gemm g, const Sched& S, const Epi& E) {
;     ...
;             PG8_LDA(At, 1, 1); PG8_STAGE(PG8_SB(1, 0), b3, voffB); PG8_STAGE(PG8_SB(1, 1), b3 + hstep, voffB); PG8_STAGE(PG8_SA(1, 0), a3, voffA);
;             PG8_WAIT_V(8); PG8_WAIT_L(0); PG8_BAR; PG8_MMA(1, 0, At, B0); PG8_MMA(1, 1, At, B1); PG8_BAR; PG8_SCHED;
	s_add_i32 s24, s60, s30
	v_lshl_add_u64 v[198:199], v[198:199], 0, s[78:79]
	s_mov_b32 m0, s24
	ds_read_b128 v[172:175], v203 offset:49152
	ds_read_b128 v[176:179], v203 offset:50176
	ds_read_b128 v[180:183], v203 offset:51200
	ds_read_b128 v[184:187], v203 offset:52224
	ds_read_b128 v[204:207], v203 offset:53248
	ds_read_b128 v[208:211], v203 offset:54272
	ds_read_b128 v[212:215], v203 offset:55296
	ds_read_b128 v[216:219], v203 offset:56320
	global_load_lds_dwordx4 v[198:199], off
	s_add_i32 m0, s24, 0x2000
	s_add_u32 s8, s8, 0x40080
	v_lshl_add_u64 v[198:199], v[220:221], 0, s[78:79]
	s_addc_u32 s9, s9, 0
	s_add_i32 s24, s61, s30
	global_load_lds_dwordx4 v[198:199], off
	v_lshl_add_u64 v[198:199], s[8:9], 0, v[164:165]
	s_mov_b32 m0, s24
	s_nop 0
	global_load_lds_dwordx4 v[198:199], off
	v_lshl_add_u64 v[198:199], s[8:9], 0, v[160:161]
	s_add_i32 m0, s24, 0x2000
	s_nop 0
	global_load_lds_dwordx4 v[198:199], off
	v_lshl_add_u64 v[198:199], v[222:223], 0, s[78:79]
	s_mov_b32 m0, s37
	s_nop 0
	global_load_lds_dwordx4 v[198:199], off
	v_lshl_add_u64 v[198:199], v[224:225], 0, s[78:79]
	s_mov_b32 m0, s40
	s_nop 0
	global_load_lds_dwordx4 v[198:199], off
	s_nop 0
	s_waitcnt vmcnt(8)
	s_waitcnt lgkmcnt(0)
	s_barrier
	s_setprio 1
	v_mfma_f32_16x16x32_bf16 v[60:63], v[128:131], v[172:175], v[60:63]
	v_mfma_f32_16x16x32_bf16 v[56:59], v[136:139], v[172:175], v[56:59]
	v_mfma_f32_16x16x32_bf16 v[52:55], v[128:131], v[180:183], v[52:55]
	v_mfma_f32_16x16x32_bf16 v[48:51], v[136:139], v[180:183], v[48:51]
	v_mfma_f32_16x16x32_bf16 v[44:47], v[128:131], v[204:207], v[44:47]
	v_mfma_f32_16x16x32_bf16 v[40:43], v[136:139], v[204:207], v[40:43]
	v_mfma_f32_16x16x32_bf16 v[36:39], v[128:131], v[212:215], v[36:39]
	v_mfma_f32_16x16x32_bf16 v[32:35], v[136:139], v[212:215], v[32:35]
	v_mfma_f32_16x16x32_bf16 v[60:63], v[132:135], v[176:179], v[60:63]
	v_mfma_f32_16x16x32_bf16 v[56:59], v[140:143], v[176:179], v[56:59]
	v_mfma_f32_16x16x32_bf16 v[52:55], v[132:135], v[184:187], v[52:55]
	v_mfma_f32_16x16x32_bf16 v[48:51], v[140:143], v[184:187], v[48:51]
	v_mfma_f32_16x16x32_bf16 v[44:47], v[132:135], v[208:211], v[44:47]
	v_mfma_f32_16x16x32_bf16 v[40:43], v[140:143], v[208:211], v[40:43]
	v_mfma_f32_16x16x32_bf16 v[36:39], v[132:135], v[216:219], v[36:39]
	v_mfma_f32_16x16x32_bf16 v[32:35], v[140:143], v[216:219], v[32:35]
	v_mfma_f32_16x16x32_bf16 v[28:31], v[144:147], v[172:175], v[28:31]
	v_mfma_f32_16x16x32_bf16 v[24:27], v[152:155], v[172:175], v[24:27]
	v_mfma_f32_16x16x32_bf16 v[20:23], v[144:147], v[180:183], v[20:23]
	v_mfma_f32_16x16x32_bf16 v[16:19], v[152:155], v[180:183], v[16:19]
	v_mfma_f32_16x16x32_bf16 v[12:15], v[144:147], v[204:207], v[12:15]
	v_mfma_f32_16x16x32_bf16 v[8:11], v[152:155], v[204:207], v[8:11]
	v_mfma_f32_16x16x32_bf16 v[4:7], v[144:147], v[212:215], v[4:7]
	v_mfma_f32_16x16x32_bf16 v[0:3], v[152:155], v[212:215], v[0:3]
	v_mfma_f32_16x16x32_bf16 v[28:31], v[148:151], v[176:179], v[28:31]
	v_mfma_f32_16x16x32_bf16 v[24:27], v[156:159], v[176:179], v[24:27]
	v_mfma_f32_16x16x32_bf16 v[20:23], v[148:151], v[184:187], v[20:23]
	v_mfma_f32_16x16x32_bf16 v[16:19], v[156:159], v[184:187], v[16:19]
	v_mfma_f32_16x16x32_bf16 v[12:15], v[148:151], v[208:211], v[12:15]
	v_mfma_f32_16x16x32_bf16 v[8:11], v[156:159], v[208:211], v[8:11]
	v_mfma_f32_16x16x32_bf16 v[4:7], v[148:151], v[216:219], v[4:7]
	v_mfma_f32_16x16x32_bf16 v[0:3], v[156:159], v[216:219], v[0:3]
	s_setprio 0
	s_barrier
	s_add_i32 s58, s58, 2
	s_add_u32 s6, s6, 0x100
	s_addc_u32 s7, s7, 0
	s_add_u32 s45, s45, 0x100
	s_addc_u32 s52, s52, 0
	s_cmp_gt_u32 s58, 13
	s_cbranch_scc0 .LBB0_424
	s_and_b64 vcc, exec, s[14:15]
	s_cbranch_vccz .LBB0_427
	s_barrier

; #define PG8_STAGE(bufoff, gbase, voff) do { _Pragma("unroll") for (int _i = 0; _i < 2; ++_i) \
;         __builtin_amdgcn_global_load_lds((const unsigned*)((const char*)(gbase) + (voff)[_i]), (PG8_LAS unsigned*)(lds + (bufoff) + ldsw + _i * 8192), 16, 0, 0); } while (0)
; #define PG8_LDA(dst, b, h) do { _Pragma("unroll") for (int m = 0; m < 4; ++m) _Pragma("unroll") for (int k = 0; k < 2; ++k) dst[m][k] = *(const PG8_LAS bf16x8*)(lds + PG8_SA(b, h) + aoff + m * 2048 + k * 1024); } while (0)
; #define PG8_LDB(dst, b, h) do { _Pragma("unroll") for (int n = 0; n < 2; ++n) _Pragma("unroll") for (int k = 0; k < 2; ++k) dst[n][k] = *(const PG8_LAS bf16x8*)(lds + PG8_SB(b, h) + boff + n * 2048 + k * 1024); } while (0)
; #define PG8_MMA(ai, bj, At, Bt) do { __builtin_amdgcn_s_setprio(1); _Pragma("unroll") for (int m = 0; m < 4; ++m) _Pragma("unroll") for (int n = 0; n < 2; ++n) _Pragma("unroll") for (int k = 0; k < 2; ++k) \
;         acc[ai][bj][m][n] = __builtin_amdgcn_mfma_f32_16x16x32_bf16(Bt[n][k], At[m][k], acc[ai][bj][m][n], 0, 0, 0); __builtin_amdgcn_s_setprio(0); } while (0)
; #define PG8_WAIT_V(n) asm volatile("s_waitcnt vmcnt(" #n ")" ::: "memory")
; #define PG8_WAIT_L(n) asm volatile("s_waitcnt lgkmcnt(" #n ")" ::: "memory")
; #define PG8_BAR __builtin_amdgcn_s_barrier()
; #define PG8_SCHED __builtin_amdgcn_sched_barrier(0)
; template <class Epi, class Sched, bool ALIGN_EPI = false, bool SP2 = false>
; __device__ __forceinline__ void gemm_phase(PG8_LAS unsigned char* lds, const Gemm g, const Sched& S, const Epi& E) {
;     ...
;             const bool last = (t == nt - 2);
;             const char* a1 = cA + (size_t)(t + 1) * kstep;
;             const char* a2 = last ? nA : cA + (size_t)(t + 2) * kstep; const char* b2 = last ? nB : cB + (size_t)(t + 2) * kstep;
;             const char* a3 = a2 + kstep; const char* b3 = b2 + kstep;
;             if (last && has_next) S.a_ready(nxt);
;             if constexpr (SP2) {
;             PG8_LDB(B0, 0, 0); PG8_LDB(B1, 0, 1); PG8_SCHED; PG8_LDA(At, 0, 0); PG8_STAGE(PG8_SA(1, 1), a1 + hstep, voffA);
;             PG8_WAIT_V(8); PG8_WAIT_L(0); PG8_BAR; PG8_MMA(0, 0, At, B0); PG8_MMA(0, 1, At, B1); PG8_BAR; PG8_SCHED;
;             PG8_LDA(At, 0, 1); PG8_STAGE(PG8_SB(0, 0), b2, voffB); PG8_STAGE(PG8_SB(0, 1), b2 + hstep, voffB); PG8_STAGE(PG8_SA(0, 0), a2, voffA);
.LBB0_596:
	s_add_u32 s26, s24, 0xfff80080
	s_addc_u32 s27, s25, -1
	s_add_i32 s60, 0, 0x10000
	s_cmp_eq_u32 s67, 28
	s_cselect_b32 s29, s19, s27
	s_cselect_b32 s28, s58, s26
	s_cselect_b32 s27, s17, s66
	s_cselect_b32 s26, s62, s63
	s_add_i32 s68, 0, 0x14000
	v_add_u32_e32 v124, s60, v239
	v_add_u32_e32 v148, s68, v239
	ds_read_b128 v[112:115], v124
	ds_read_b128 v[116:119], v124 offset:1024
	ds_read_b128 v[120:123], v124 offset:2048
	ds_read_b128 v[124:127], v124 offset:3072
	ds_read_b128 v[132:135], v148
	ds_read_b128 v[140:143], v148 offset:1024
	ds_read_b128 v[144:147], v148 offset:2048
	ds_read_b128 v[148:151], v148 offset:3072
	v_lshl_add_u64 v[212:213], s[24:25], 0, v[204:205]
	s_add_i32 m0, s36, 0xc000
	ds_read_b128 v[156:159], v241
	ds_read_b128 v[164:167], v241 offset:1024
	ds_read_b128 v[168:171], v241 offset:2048
	ds_read_b128 v[172:175], v241 offset:3072
	ds_read_b128 v[176:179], v241 offset:4096
	ds_read_b128 v[180:183], v241 offset:5120
	ds_read_b128 v[184:187], v241 offset:6144
	ds_read_b128 v[208:211], v241 offset:7168
	global_load_lds_dwordx4 v[212:213], off
	v_lshl_add_u64 v[212:213], s[24:25], 0, v[206:207]
	s_add_i32 m0, s36, 0xe000
	s_nop 0
	global_load_lds_dwordx4 v[212:213], off
	s_nop 0
	s_nop 0
	s_waitcnt vmcnt(8)
	s_waitcnt lgkmcnt(0)
	s_barrier
	s_setprio 1
	v_mfma_f32_16x16x32_bf16 v[160:163], v[112:115], v[156:159], v[160:163]
	v_mfma_f32_16x16x32_bf16 v[152:155], v[120:123], v[156:159], v[152:155]
	v_mfma_f32_16x16x32_bf16 v[108:111], v[112:115], v[168:171], v[108:111]
	v_mfma_f32_16x16x32_bf16 v[104:107], v[120:123], v[168:171], v[104:107]
	v_mfma_f32_16x16x32_bf16 v[92:95], v[112:115], v[176:179], v[92:95]
	v_mfma_f32_16x16x32_bf16 v[88:91], v[120:123], v[176:179], v[88:91]
	v_mfma_f32_16x16x32_bf16 v[76:79], v[112:115], v[184:187], v[76:79]
	v_mfma_f32_16x16x32_bf16 v[72:75], v[120:123], v[184:187], v[72:75]
	v_mfma_f32_16x16x32_bf16 v[160:163], v[116:119], v[164:167], v[160:163]
	v_mfma_f32_16x16x32_bf16 v[152:155], v[124:127], v[164:167], v[152:155]
	v_mfma_f32_16x16x32_bf16 v[108:111], v[116:119], v[172:175], v[108:111]
	v_mfma_f32_16x16x32_bf16 v[104:107], v[124:127], v[172:175], v[104:107]
	v_mfma_f32_16x16x32_bf16 v[92:95], v[116:119], v[180:183], v[92:95]
	v_mfma_f32_16x16x32_bf16 v[88:91], v[124:127], v[180:183], v[88:91]
	v_mfma_f32_16x16x32_bf16 v[76:79], v[116:119], v[208:211], v[76:79]
	v_mfma_f32_16x16x32_bf16 v[72:75], v[124:127], v[208:211], v[72:75]
	v_mfma_f32_16x16x32_bf16 v[136:139], v[132:135], v[156:159], v[136:139]
	v_mfma_f32_16x16x32_bf16 v[128:131], v[144:147], v[156:159], v[128:131]
	v_mfma_f32_16x16x32_bf16 v[100:103], v[132:135], v[168:171], v[100:103]
	v_mfma_f32_16x16x32_bf16 v[96:99], v[144:147], v[168:171], v[96:99]
	v_mfma_f32_16x16x32_bf16 v[84:87], v[132:135], v[176:179], v[84:87]
	v_mfma_f32_16x16x32_bf16 v[80:83], v[144:147], v[176:179], v[80:83]
	v_mfma_f32_16x16x32_bf16 v[68:71], v[132:135], v[184:187], v[68:71]
	v_mfma_f32_16x16x32_bf16 v[64:67], v[144:147], v[184:187], v[64:67]
	v_mfma_f32_16x16x32_bf16 v[136:139], v[140:143], v[164:167], v[136:139]
	v_mfma_f32_16x16x32_bf16 v[128:131], v[148:151], v[164:167], v[128:131]
	v_mfma_f32_16x16x32_bf16 v[100:103], v[140:143], v[172:175], v[100:103]
	v_mfma_f32_16x16x32_bf16 v[96:99], v[148:151], v[172:175], v[96:99]
	v_mfma_f32_16x16x32_bf16 v[84:87], v[140:143], v[180:183], v[84:87]
	v_mfma_f32_16x16x32_bf16 v[80:83], v[148:151], v[180:183], v[80:83]
	v_mfma_f32_16x16x32_bf16 v[68:71], v[140:143], v[208:211], v[68:71]
	v_mfma_f32_16x16x32_bf16 v[64:67], v[148:151], v[208:211], v[64:67]
	s_setprio 0
	s_barrier
	s_add_i32 s60, s60, s35
	v_lshl_add_u64 v[212:213], s[26:27], 0, v[188:189]
	s_mov_b32 m0, s60
	ds_read_b128 v[156:159], v241 offset:16384
	ds_read_b128 v[164:167], v241 offset:17408
	ds_read_b128 v[168:171], v241 offset:18432
	ds_read_b128 v[172:175], v241 offset:19456
	ds_read_b128 v[176:179], v241 offset:20480
	ds_read_b128 v[180:183], v241 offset:21504
	ds_read_b128 v[184:187], v241 offset:22528
	ds_read_b128 v[208:211], v241 offset:23552
	global_load_lds_dwordx4 v[212:213], off
	s_add_i32 m0, s60, 0x2000
	s_add_u32 s60, s26, 0x80000
	v_lshl_add_u64 v[214:215], s[26:27], 0, v[198:199]
	s_addc_u32 s61, s27, 0
	s_add_i32 s68, s68, s35
	global_load_lds_dwordx4 v[214:215], off
	v_lshl_add_u64 v[216:217], s[60:61], 0, v[188:189]
	s_mov_b32 m0, s68
	v_lshl_add_u64 v[218:219], s[28:29], 0, v[200:201]
	global_load_lds_dwordx4 v[216:217], off
	v_lshl_add_u64 v[216:217], s[60:61], 0, v[198:199]
	s_add_i32 m0, s68, 0x2000
	s_nop 0
	global_load_lds_dwordx4 v[216:217], off
	v_lshl_add_u64 v[216:217], s[28:29], 0, v[202:203]
	s_mov_b32 m0, s36
	s_nop 0
	global_load_lds_dwordx4 v[216:217], off
	s_mov_b32 m0, s37
	s_nop 0
	global_load_lds_dwordx4 v[218:219], off
	s_nop 0
	s_nop 0
	s_waitcnt vmcnt(8)
	s_waitcnt lgkmcnt(0)
	s_barrier
; #define PG8_STAGE(bufoff, gbase, voff) do { _Pragma("unroll") for (int _i = 0; _i < 2; ++_i) \
;         __builtin_amdgcn_global_load_lds((const unsigned*)((const char*)(gbase) + (voff)[_i]), (PG8_LAS unsigned*)(lds + (bufoff) + ldsw + _i * 8192), 16, 0, 0); } while (0)
; #define PG8_LDA(dst, b, h) do { _Pragma("unroll") for (int m = 0; m < 4; ++m) _Pragma("unroll") for (int k = 0; k < 2; ++k) dst[m][k] = *(const PG8_LAS bf16x8*)(lds + PG8_SA(b, h) + aoff + m * 2048 + k * 1024); } while (0)
; #define PG8_LDB(dst, b, h) do { _Pragma("unroll") for (int n = 0; n < 2; ++n) _Pragma("unroll") for (int k = 0; k < 2; ++k) dst[n][k] = *(const PG8_LAS bf16x8*)(lds + PG8_SB(b, h) + boff + n * 2048 + k * 1024); } while (0)
; #define PG8_MMA(ai, bj, At, Bt) do { __builtin_amdgcn_s_setprio(1); _Pragma("unroll") for (int m = 0; m < 4; ++m) _Pragma("unroll") for (int n = 0; n < 2; ++n) _Pragma("unroll") for (int k = 0; k < 2; ++k) \
;         acc[ai][bj][m][n] = __builtin_amdgcn_mfma_f32_16x16x32_bf16(Bt[n][k], At[m][k], acc[ai][bj][m][n], 0, 0, 0); __builtin_amdgcn_s_setprio(0); } while (0)
; #define PG8_WAIT_V(n) asm volatile("s_waitcnt vmcnt(" #n ")" ::: "memory")
; #define PG8_WAIT_L(n) asm volatile("s_waitcnt lgkmcnt(" #n ")" ::: "memory")
; #define PG8_BAR __builtin_amdgcn_s_barrier()
; #define PG8_SCHED __builtin_amdgcn_sched_barrier(0)
; template <class Epi, class Sched, bool ALIGN_EPI = false, bool SP2 = false>
; __device__ __forceinline__ void gemm_phase(PG8_LAS unsigned char* lds, const Gemm g, const Sched& S, const Epi& E) {
;     ...
;             PG8_WAIT_V(8); PG8_WAIT_L(0); PG8_BAR; PG8_MMA(1, 0, At, B0); PG8_MMA(1, 1, At, B1); PG8_BAR; PG8_SCHED;
;             PG8_LDB(B0, 1, 0); PG8_LDB(B1, 1, 1); PG8_SCHED; PG8_LDA(At, 1, 0); PG8_STAGE(PG8_SA(0, 1), a2 + hstep, voffA);
;             PG8_WAIT_V(8); PG8_WAIT_L(0); PG8_BAR; PG8_MMA(0, 0, At, B0); PG8_MMA(0, 1, At, B1); PG8_BAR; PG8_SCHED;
	s_setprio 1
	v_mfma_f32_16x16x32_bf16 v[60:63], v[112:115], v[156:159], v[60:63]
	v_mfma_f32_16x16x32_bf16 v[56:59], v[120:123], v[156:159], v[56:59]
	v_mfma_f32_16x16x32_bf16 v[44:47], v[112:115], v[168:171], v[44:47]
	v_mfma_f32_16x16x32_bf16 v[40:43], v[120:123], v[168:171], v[40:43]
	v_mfma_f32_16x16x32_bf16 v[28:31], v[112:115], v[176:179], v[28:31]
	v_mfma_f32_16x16x32_bf16 v[24:27], v[120:123], v[176:179], v[24:27]
	v_mfma_f32_16x16x32_bf16 v[12:15], v[112:115], v[184:187], v[12:15]
	v_mfma_f32_16x16x32_bf16 v[8:11], v[120:123], v[184:187], v[8:11]
	v_mfma_f32_16x16x32_bf16 v[60:63], v[116:119], v[164:167], v[60:63]
	v_mfma_f32_16x16x32_bf16 v[56:59], v[124:127], v[164:167], v[56:59]
	v_mfma_f32_16x16x32_bf16 v[44:47], v[116:119], v[172:175], v[44:47]
	v_mfma_f32_16x16x32_bf16 v[40:43], v[124:127], v[172:175], v[40:43]
	v_mfma_f32_16x16x32_bf16 v[28:31], v[116:119], v[180:183], v[28:31]
	v_mfma_f32_16x16x32_bf16 v[24:27], v[124:127], v[180:183], v[24:27]
	v_mfma_f32_16x16x32_bf16 v[12:15], v[116:119], v[208:211], v[12:15]
	v_mfma_f32_16x16x32_bf16 v[8:11], v[124:127], v[208:211], v[8:11]
	v_mfma_f32_16x16x32_bf16 v[52:55], v[132:135], v[156:159], v[52:55]
	v_mfma_f32_16x16x32_bf16 v[48:51], v[144:147], v[156:159], v[48:51]
	v_mfma_f32_16x16x32_bf16 v[36:39], v[132:135], v[168:171], v[36:39]
	v_mfma_f32_16x16x32_bf16 v[32:35], v[144:147], v[168:171], v[32:35]
	v_mfma_f32_16x16x32_bf16 v[20:23], v[132:135], v[176:179], v[20:23]
	v_mfma_f32_16x16x32_bf16 v[16:19], v[144:147], v[176:179], v[16:19]
	v_mfma_f32_16x16x32_bf16 v[4:7], v[132:135], v[184:187], v[4:7]
	v_mfma_f32_16x16x32_bf16 v[0:3], v[144:147], v[184:187], v[0:3]
	v_mfma_f32_16x16x32_bf16 v[52:55], v[140:143], v[164:167], v[52:55]
	v_mfma_f32_16x16x32_bf16 v[48:51], v[148:151], v[164:167], v[48:51]
	v_mfma_f32_16x16x32_bf16 v[36:39], v[140:143], v[172:175], v[36:39]
	v_mfma_f32_16x16x32_bf16 v[32:35], v[148:151], v[172:175], v[32:35]
	v_mfma_f32_16x16x32_bf16 v[20:23], v[140:143], v[180:183], v[20:23]
	v_mfma_f32_16x16x32_bf16 v[16:19], v[148:151], v[180:183], v[16:19]
	v_mfma_f32_16x16x32_bf16 v[4:7], v[140:143], v[208:211], v[4:7]
	v_mfma_f32_16x16x32_bf16 v[0:3], v[148:151], v[208:211], v[0:3]
	s_setprio 0
	s_barrier
	s_add_i32 s60, 0, 0x18000
	s_add_i32 s61, 0, 0x1c000
	v_add_u32_e32 v124, s60, v239
	v_add_u32_e32 v148, s61, v239
	ds_read_b128 v[112:115], v124
	ds_read_b128 v[116:119], v124 offset:1024
	ds_read_b128 v[120:123], v124 offset:2048
	ds_read_b128 v[124:127], v124 offset:3072
	ds_read_b128 v[132:135], v148
	ds_read_b128 v[140:143], v148 offset:1024
	ds_read_b128 v[144:147], v148 offset:2048
	ds_read_b128 v[148:151], v148 offset:3072
	s_add_u32 s28, s28, 0x80000
	s_addc_u32 s29, s29, 0
	s_mov_b32 m0, s38
	v_lshl_add_u64 v[220:221], s[28:29], 0, v[202:203]
	ds_read_b128 v[156:159], v241 offset:32768
	ds_read_b128 v[164:167], v241 offset:33792
	ds_read_b128 v[168:171], v241 offset:34816
	ds_read_b128 v[172:175], v241 offset:35840
	ds_read_b128 v[176:179], v241 offset:36864
	ds_read_b128 v[180:183], v241 offset:37888
	ds_read_b128 v[184:187], v241 offset:38912
	ds_read_b128 v[208:211], v241 offset:39936
	global_load_lds_dwordx4 v[220:221], off
	v_lshl_add_u64 v[220:221], s[28:29], 0, v[200:201]
	s_mov_b32 m0, s39
	s_nop 0
	global_load_lds_dwordx4 v[220:221], off
	s_nop 0
	s_nop 0
	s_nop 0
	s_nop 0
	s_nop 0
	s_nop 0
	s_waitcnt vmcnt(8)
	s_waitcnt lgkmcnt(0)
	s_barrier
	s_setprio 1
	v_mfma_f32_16x16x32_bf16 v[160:163], v[112:115], v[156:159], v[160:163]
	v_mfma_f32_16x16x32_bf16 v[152:155], v[120:123], v[156:159], v[152:155]
	v_mfma_f32_16x16x32_bf16 v[108:111], v[112:115], v[168:171], v[108:111]
	v_mfma_f32_16x16x32_bf16 v[104:107], v[120:123], v[168:171], v[104:107]
	v_mfma_f32_16x16x32_bf16 v[92:95], v[112:115], v[176:179], v[92:95]
	v_mfma_f32_16x16x32_bf16 v[88:91], v[120:123], v[176:179], v[88:91]
	v_mfma_f32_16x16x32_bf16 v[76:79], v[112:115], v[184:187], v[76:79]
	v_mfma_f32_16x16x32_bf16 v[72:75], v[120:123], v[184:187], v[72:75]
	v_mfma_f32_16x16x32_bf16 v[160:163], v[116:119], v[164:167], v[160:163]
	v_mfma_f32_16x16x32_bf16 v[152:155], v[124:127], v[164:167], v[152:155]
	v_mfma_f32_16x16x32_bf16 v[108:111], v[116:119], v[172:175], v[108:111]
	v_mfma_f32_16x16x32_bf16 v[104:107], v[124:127], v[172:175], v[104:107]
	v_mfma_f32_16x16x32_bf16 v[92:95], v[116:119], v[180:183], v[92:95]
	v_mfma_f32_16x16x32_bf16 v[88:91], v[124:127], v[180:183], v[88:91]
	v_mfma_f32_16x16x32_bf16 v[76:79], v[116:119], v[208:211], v[76:79]
	v_mfma_f32_16x16x32_bf16 v[72:75], v[124:127], v[208:211], v[72:75]
	v_mfma_f32_16x16x32_bf16 v[136:139], v[132:135], v[156:159], v[136:139]
	v_mfma_f32_16x16x32_bf16 v[128:131], v[144:147], v[156:159], v[128:131]
	v_mfma_f32_16x16x32_bf16 v[100:103], v[132:135], v[168:171], v[100:103]
	v_mfma_f32_16x16x32_bf16 v[96:99], v[144:147], v[168:171], v[96:99]
	v_mfma_f32_16x16x32_bf16 v[84:87], v[132:135], v[176:179], v[84:87]
	v_mfma_f32_16x16x32_bf16 v[80:83], v[144:147], v[176:179], v[80:83]
	v_mfma_f32_16x16x32_bf16 v[68:71], v[132:135], v[184:187], v[68:71]
	v_mfma_f32_16x16x32_bf16 v[64:67], v[144:147], v[184:187], v[64:67]
	v_mfma_f32_16x16x32_bf16 v[136:139], v[140:143], v[164:167], v[136:139]
	v_mfma_f32_16x16x32_bf16 v[128:131], v[148:151], v[164:167], v[128:131]
	v_mfma_f32_16x16x32_bf16 v[100:103], v[140:143], v[172:175], v[100:103]
	v_mfma_f32_16x16x32_bf16 v[96:99], v[148:151], v[172:175], v[96:99]
	v_mfma_f32_16x16x32_bf16 v[84:87], v[140:143], v[180:183], v[84:87]
	v_mfma_f32_16x16x32_bf16 v[80:83], v[148:151], v[180:183], v[80:83]
	v_mfma_f32_16x16x32_bf16 v[68:71], v[140:143], v[208:211], v[68:71]
	v_mfma_f32_16x16x32_bf16 v[64:67], v[148:151], v[208:211], v[64:67]
	s_setprio 0
	s_barrier
; #define PG8_STAGE(bufoff, gbase, voff) do { _Pragma("unroll") for (int _i = 0; _i < 2; ++_i) \
;         __builtin_amdgcn_global_load_lds((const unsigned*)((const char*)(gbase) + (voff)[_i]), (PG8_LAS unsigned*)(lds + (bufoff) + ldsw + _i * 8192), 16, 0, 0); } while (0)
; #define PG8_LDA(dst, b, h) do { _Pragma("unroll") for (int m = 0; m < 4; ++m) _Pragma("unroll") for (int k = 0; k < 2; ++k) dst[m][k] = *(const PG8_LAS bf16x8*)(lds + PG8_SA(b, h) + aoff + m * 2048 + k * 1024); } while (0)
; #define PG8_MMA(ai, bj, At, Bt) do { __builtin_amdgcn_s_setprio(1); _Pragma("unroll") for (int m = 0; m < 4; ++m) _Pragma("unroll") for (int n = 0; n < 2; ++n) _Pragma("unroll") for (int k = 0; k < 2; ++k) \
;         acc[ai][bj][m][n] = __builtin_amdgcn_mfma_f32_16x16x32_bf16(Bt[n][k], At[m][k], acc[ai][bj][m][n], 0, 0, 0); __builtin_amdgcn_s_setprio(0); } while (0)
; #define PG8_WAIT_V(n) asm volatile("s_waitcnt vmcnt(" #n ")" ::: "memory")
; #define PG8_WAIT_L(n) asm volatile("s_waitcnt lgkmcnt(" #n ")" ::: "memory")
; #define PG8_BAR __builtin_amdgcn_s_barrier()
; #define PG8_SCHED __builtin_amdgcn_sched_barrier(0)
; template <class Epi, class Sched, bool ALIGN_EPI = false, bool SP2 = false>
; __device__ __forceinline__ void gemm_phase(PG8_LAS unsigned char* lds, const Gemm g, const Sched& S, const Epi& E) {
;     ...
;             PG8_LDA(At, 1, 1); PG8_STAGE(PG8_SB(1, 0), b3, voffB); PG8_STAGE(PG8_SB(1, 1), b3 + hstep, voffB); PG8_STAGE(PG8_SA(1, 0), a3, voffA);
;             PG8_WAIT_V(8); PG8_WAIT_L(0); PG8_BAR; PG8_MMA(1, 0, At, B0); PG8_MMA(1, 1, At, B1); PG8_BAR; PG8_SCHED;
	s_add_i32 s28, s60, s35
	v_lshl_add_u64 v[212:213], v[212:213], 0, s[78:79]
	s_mov_b32 m0, s28
	ds_read_b128 v[156:159], v241 offset:49152
	ds_read_b128 v[164:167], v241 offset:50176
	ds_read_b128 v[168:171], v241 offset:51200
	ds_read_b128 v[172:175], v241 offset:52224
	ds_read_b128 v[176:179], v241 offset:53248
	ds_read_b128 v[180:183], v241 offset:54272
	ds_read_b128 v[184:187], v241 offset:55296
	ds_read_b128 v[208:211], v241 offset:56320
	global_load_lds_dwordx4 v[212:213], off
	s_add_i32 m0, s28, 0x2000
	s_add_u32 s26, s26, 0x80080
	v_lshl_add_u64 v[212:213], v[214:215], 0, s[78:79]
	s_addc_u32 s27, s27, 0
	s_add_i32 s28, s61, s35
	global_load_lds_dwordx4 v[212:213], off
	v_lshl_add_u64 v[212:213], s[26:27], 0, v[188:189]
	s_mov_b32 m0, s28
	s_nop 0
	global_load_lds_dwordx4 v[212:213], off
	v_lshl_add_u64 v[212:213], s[26:27], 0, v[198:199]
	s_add_i32 m0, s28, 0x2000
	s_nop 0
	global_load_lds_dwordx4 v[212:213], off
	v_lshl_add_u64 v[212:213], v[216:217], 0, s[78:79]
	s_mov_b32 m0, s40
	s_nop 0
	global_load_lds_dwordx4 v[212:213], off
	v_lshl_add_u64 v[212:213], v[218:219], 0, s[78:79]
	s_mov_b32 m0, s41
	s_nop 0
	global_load_lds_dwordx4 v[212:213], off
	s_nop 0
	s_waitcnt vmcnt(8)
	s_waitcnt lgkmcnt(0)
	s_barrier
	s_setprio 1
	v_mfma_f32_16x16x32_bf16 v[60:63], v[112:115], v[156:159], v[60:63]
	v_mfma_f32_16x16x32_bf16 v[56:59], v[120:123], v[156:159], v[56:59]
	v_mfma_f32_16x16x32_bf16 v[44:47], v[112:115], v[168:171], v[44:47]
	v_mfma_f32_16x16x32_bf16 v[40:43], v[120:123], v[168:171], v[40:43]
	v_mfma_f32_16x16x32_bf16 v[28:31], v[112:115], v[176:179], v[28:31]
	v_mfma_f32_16x16x32_bf16 v[24:27], v[120:123], v[176:179], v[24:27]
	v_mfma_f32_16x16x32_bf16 v[12:15], v[112:115], v[184:187], v[12:15]
	v_mfma_f32_16x16x32_bf16 v[8:11], v[120:123], v[184:187], v[8:11]
	v_mfma_f32_16x16x32_bf16 v[60:63], v[116:119], v[164:167], v[60:63]
	v_mfma_f32_16x16x32_bf16 v[56:59], v[124:127], v[164:167], v[56:59]
	v_mfma_f32_16x16x32_bf16 v[44:47], v[116:119], v[172:175], v[44:47]
	v_mfma_f32_16x16x32_bf16 v[40:43], v[124:127], v[172:175], v[40:43]
	v_mfma_f32_16x16x32_bf16 v[28:31], v[116:119], v[180:183], v[28:31]
	v_mfma_f32_16x16x32_bf16 v[24:27], v[124:127], v[180:183], v[24:27]
	v_mfma_f32_16x16x32_bf16 v[12:15], v[116:119], v[208:211], v[12:15]
	v_mfma_f32_16x16x32_bf16 v[8:11], v[124:127], v[208:211], v[8:11]
	v_mfma_f32_16x16x32_bf16 v[52:55], v[132:135], v[156:159], v[52:55]
	v_mfma_f32_16x16x32_bf16 v[48:51], v[144:147], v[156:159], v[48:51]
	v_mfma_f32_16x16x32_bf16 v[36:39], v[132:135], v[168:171], v[36:39]
	v_mfma_f32_16x16x32_bf16 v[32:35], v[144:147], v[168:171], v[32:35]
	v_mfma_f32_16x16x32_bf16 v[20:23], v[132:135], v[176:179], v[20:23]
	v_mfma_f32_16x16x32_bf16 v[16:19], v[144:147], v[176:179], v[16:19]
	v_mfma_f32_16x16x32_bf16 v[4:7], v[132:135], v[184:187], v[4:7]
	v_mfma_f32_16x16x32_bf16 v[0:3], v[144:147], v[184:187], v[0:3]
	v_mfma_f32_16x16x32_bf16 v[52:55], v[140:143], v[164:167], v[52:55]
	v_mfma_f32_16x16x32_bf16 v[48:51], v[148:151], v[164:167], v[48:51]
	v_mfma_f32_16x16x32_bf16 v[36:39], v[140:143], v[172:175], v[36:39]
	v_mfma_f32_16x16x32_bf16 v[32:35], v[148:151], v[172:175], v[32:35]
	v_mfma_f32_16x16x32_bf16 v[20:23], v[140:143], v[180:183], v[20:23]
	v_mfma_f32_16x16x32_bf16 v[16:19], v[148:151], v[180:183], v[16:19]
	v_mfma_f32_16x16x32_bf16 v[4:7], v[140:143], v[208:211], v[4:7]
	v_mfma_f32_16x16x32_bf16 v[0:3], v[148:151], v[208:211], v[0:3]
	s_setprio 0
	s_barrier
	s_add_i32 s67, s67, 2
	s_add_u32 s24, s24, 0x100
	s_addc_u32 s25, s25, 0
	s_add_u32 s63, s63, 0x100
	s_addc_u32 s66, s66, 0
	s_cmp_gt_u32 s67, 29
	s_cbranch_scc0 .LBB0_596
	s_and_b64 vcc, exec, s[14:15]
	s_cbranch_vccz .LBB0_599
	s_barrier

; #define PG8_STAGE(bufoff, gbase, voff) do { _Pragma("unroll") for (int _i = 0; _i < 2; ++_i) \
;         __builtin_amdgcn_global_load_lds((const unsigned*)((const char*)(gbase) + (voff)[_i]), (PG8_LAS unsigned*)(lds + (bufoff) + ldsw + _i * 8192), 16, 0, 0); } while (0)
; #define PG8_LDA(dst, b, h) do { _Pragma("unroll") for (int m = 0; m < 4; ++m) _Pragma("unroll") for (int k = 0; k < 2; ++k) dst[m][k] = *(const PG8_LAS bf16x8*)(lds + PG8_SA(b, h) + aoff + m * 2048 + k * 1024); } while (0)
; #define PG8_LDB(dst, b, h) do { _Pragma("unroll") for (int n = 0; n < 2; ++n) _Pragma("unroll") for (int k = 0; k < 2; ++k) dst[n][k] = *(const PG8_LAS bf16x8*)(lds + PG8_SB(b, h) + boff + n * 2048 + k * 1024); } while (0)
; #define PG8_MMA(ai, bj, At, Bt) do { __builtin_amdgcn_s_setprio(1); _Pragma("unroll") for (int m = 0; m < 4; ++m) _Pragma("unroll") for (int n = 0; n < 2; ++n) _Pragma("unroll") for (int k = 0; k < 2; ++k) \
;         acc[ai][bj][m][n] = __builtin_amdgcn_mfma_f32_16x16x32_bf16(Bt[n][k], At[m][k], acc[ai][bj][m][n], 0, 0, 0); __builtin_amdgcn_s_setprio(0); } while (0)
; #define PG8_WAIT_V(n) asm volatile("s_waitcnt vmcnt(" #n ")" ::: "memory")
; #define PG8_WAIT_L(n) asm volatile("s_waitcnt lgkmcnt(" #n ")" ::: "memory")
; #define PG8_BAR __builtin_amdgcn_s_barrier()
; #define PG8_SCHED __builtin_amdgcn_sched_barrier(0)
; template <class Epi, class Sched, bool ALIGN_EPI = false, bool SP2 = false>
; __device__ __forceinline__ void gemm_phase(PG8_LAS unsigned char* lds, const Gemm g, const Sched& S, const Epi& E) {
;     ...
;             const bool last = (t == nt - 2);
;             const char* a1 = cA + (size_t)(t + 1) * kstep;
;             const char* a2 = last ? nA : cA + (size_t)(t + 2) * kstep; const char* b2 = last ? nB : cB + (size_t)(t + 2) * kstep;
;             const char* a3 = a2 + kstep; const char* b3 = b2 + kstep;
;             if (last && has_next) S.a_ready(nxt);
;             if constexpr (SP2) {
;             PG8_LDB(B0, 0, 0); PG8_LDB(B1, 0, 1); PG8_SCHED; PG8_LDA(At, 0, 0); PG8_STAGE(PG8_SA(1, 1), a1 + hstep, voffA);
;             PG8_WAIT_V(8); PG8_WAIT_L(0); PG8_BAR; PG8_MMA(0, 0, At, B0); PG8_MMA(0, 1, At, B1); PG8_BAR; PG8_SCHED;
;             PG8_LDA(At, 0, 1); PG8_STAGE(PG8_SB(0, 0), b2, voffB); PG8_STAGE(PG8_SB(0, 1), b2 + hstep, voffB); PG8_STAGE(PG8_SA(0, 0), a2, voffA);
.LBB0_684:
	s_add_u32 s24, s8, 0xfff80080
	s_addc_u32 s25, s9, -1
	s_add_i32 s60, 0, 0x10000
	s_cmp_eq_u32 s63, 28
	s_cselect_b32 s27, s19, s25
	s_cselect_b32 s26, s45, s24
	v_add_u32_e32 v154, s60, v157
	s_cselect_b32 s25, s17, s62
	s_cselect_b32 s24, s52, s58
	s_add_i32 s66, 0, 0x14000
	ds_read_b128 v[160:163], v154
	ds_read_b128 v[164:167], v154 offset:1024
	ds_read_b128 v[168:171], v154 offset:2048
	ds_read_b128 v[172:175], v154 offset:3072
	v_add_u32_e32 v154, s66, v157
	ds_read_b128 v[176:179], v154
	ds_read_b128 v[180:183], v154 offset:1024
	ds_read_b128 v[184:187], v154 offset:2048
	ds_read_b128 v[198:201], v154 offset:3072
	v_lshl_add_u64 v[154:155], s[8:9], 0, v[134:135]
	s_add_i32 m0, s34, 0xc000
	ds_read_b128 v[202:205], v159
	ds_read_b128 v[206:209], v159 offset:1024
	ds_read_b128 v[210:213], v159 offset:2048
	ds_read_b128 v[214:217], v159 offset:3072
	ds_read_b128 v[218:221], v159 offset:4096
	ds_read_b128 v[222:225], v159 offset:5120
	ds_read_b128 v[226:229], v159 offset:6144
	ds_read_b128 v[238:241], v159 offset:7168
	global_load_lds_dwordx4 v[154:155], off
	v_lshl_add_u64 v[154:155], s[8:9], 0, v[136:137]
	s_add_i32 m0, s34, 0xe000
	s_nop 0
	global_load_lds_dwordx4 v[154:155], off
	s_waitcnt vmcnt(8)
	s_waitcnt lgkmcnt(0)
	s_barrier
	s_setprio 1
	v_mfma_f32_16x16x32_bf16 v[124:127], v[160:163], v[202:205], v[124:127]
	v_mfma_f32_16x16x32_bf16 v[120:123], v[168:171], v[202:205], v[120:123]
	v_mfma_f32_16x16x32_bf16 v[108:111], v[160:163], v[210:213], v[108:111]
	v_mfma_f32_16x16x32_bf16 v[104:107], v[168:171], v[210:213], v[104:107]
	v_mfma_f32_16x16x32_bf16 v[92:95], v[160:163], v[218:221], v[92:95]
	v_mfma_f32_16x16x32_bf16 v[88:91], v[168:171], v[218:221], v[88:91]
	v_mfma_f32_16x16x32_bf16 v[76:79], v[160:163], v[226:229], v[76:79]
	v_mfma_f32_16x16x32_bf16 v[72:75], v[168:171], v[226:229], v[72:75]
	v_mfma_f32_16x16x32_bf16 v[124:127], v[164:167], v[206:209], v[124:127]
	v_mfma_f32_16x16x32_bf16 v[120:123], v[172:175], v[206:209], v[120:123]
	v_mfma_f32_16x16x32_bf16 v[108:111], v[164:167], v[214:217], v[108:111]
	v_mfma_f32_16x16x32_bf16 v[104:107], v[172:175], v[214:217], v[104:107]
	v_mfma_f32_16x16x32_bf16 v[92:95], v[164:167], v[222:225], v[92:95]
	v_mfma_f32_16x16x32_bf16 v[88:91], v[172:175], v[222:225], v[88:91]
	v_mfma_f32_16x16x32_bf16 v[76:79], v[164:167], v[238:241], v[76:79]
	v_mfma_f32_16x16x32_bf16 v[72:75], v[172:175], v[238:241], v[72:75]
	v_mfma_f32_16x16x32_bf16 v[116:119], v[176:179], v[202:205], v[116:119]
	v_mfma_f32_16x16x32_bf16 v[112:115], v[184:187], v[202:205], v[112:115]
	v_mfma_f32_16x16x32_bf16 v[100:103], v[176:179], v[210:213], v[100:103]
	v_mfma_f32_16x16x32_bf16 v[96:99], v[184:187], v[210:213], v[96:99]
	v_mfma_f32_16x16x32_bf16 v[84:87], v[176:179], v[218:221], v[84:87]
	v_mfma_f32_16x16x32_bf16 v[80:83], v[184:187], v[218:221], v[80:83]
	v_mfma_f32_16x16x32_bf16 v[68:71], v[176:179], v[226:229], v[68:71]
	v_mfma_f32_16x16x32_bf16 v[64:67], v[184:187], v[226:229], v[64:67]
	v_mfma_f32_16x16x32_bf16 v[116:119], v[180:183], v[206:209], v[116:119]
	v_mfma_f32_16x16x32_bf16 v[112:115], v[198:201], v[206:209], v[112:115]
	v_mfma_f32_16x16x32_bf16 v[100:103], v[180:183], v[214:217], v[100:103]
	v_mfma_f32_16x16x32_bf16 v[96:99], v[198:201], v[214:217], v[96:99]
	v_mfma_f32_16x16x32_bf16 v[84:87], v[180:183], v[222:225], v[84:87]
	v_mfma_f32_16x16x32_bf16 v[80:83], v[198:201], v[222:225], v[80:83]
	v_mfma_f32_16x16x32_bf16 v[68:71], v[180:183], v[238:241], v[68:71]
	v_mfma_f32_16x16x32_bf16 v[64:67], v[198:201], v[238:241], v[64:67]
	s_setprio 0
	s_barrier
	s_add_i32 s60, s60, s31
	v_lshl_add_u64 v[154:155], s[24:25], 0, v[188:189]
	s_mov_b32 m0, s60
	ds_read_b128 v[202:205], v159 offset:16384
	ds_read_b128 v[206:209], v159 offset:17408
	ds_read_b128 v[210:213], v159 offset:18432
	ds_read_b128 v[214:217], v159 offset:19456
	ds_read_b128 v[218:221], v159 offset:20480
	ds_read_b128 v[222:225], v159 offset:21504
	ds_read_b128 v[226:229], v159 offset:22528
	ds_read_b128 v[238:241], v159 offset:23552
	global_load_lds_dwordx4 v[154:155], off
	s_add_i32 m0, s60, 0x2000
	s_add_u32 s60, s24, 0x80000
	v_lshl_add_u64 v[232:233], s[24:25], 0, v[128:129]
	s_addc_u32 s61, s25, 0
	s_add_i32 s66, s66, s31
	global_load_lds_dwordx4 v[232:233], off
	v_lshl_add_u64 v[242:243], s[60:61], 0, v[188:189]
	s_mov_b32 m0, s66
	v_lshl_add_u64 v[244:245], s[26:27], 0, v[130:131]
	global_load_lds_dwordx4 v[242:243], off
	v_lshl_add_u64 v[242:243], s[60:61], 0, v[128:129]
	s_add_i32 m0, s66, 0x2000
	s_nop 0
	global_load_lds_dwordx4 v[242:243], off
	v_lshl_add_u64 v[242:243], s[26:27], 0, v[132:133]
	s_mov_b32 m0, s34
	s_nop 0
	global_load_lds_dwordx4 v[242:243], off
	s_mov_b32 m0, s35
	s_nop 0
	global_load_lds_dwordx4 v[244:245], off
	s_nop 0
	s_nop 0
	s_waitcnt vmcnt(8)
	s_waitcnt lgkmcnt(0)
	s_barrier
; #define PG8_STAGE(bufoff, gbase, voff) do { _Pragma("unroll") for (int _i = 0; _i < 2; ++_i) \
;         __builtin_amdgcn_global_load_lds((const unsigned*)((const char*)(gbase) + (voff)[_i]), (PG8_LAS unsigned*)(lds + (bufoff) + ldsw + _i * 8192), 16, 0, 0); } while (0)
; #define PG8_LDA(dst, b, h) do { _Pragma("unroll") for (int m = 0; m < 4; ++m) _Pragma("unroll") for (int k = 0; k < 2; ++k) dst[m][k] = *(const PG8_LAS bf16x8*)(lds + PG8_SA(b, h) + aoff + m * 2048 + k * 1024); } while (0)
; #define PG8_LDB(dst, b, h) do { _Pragma("unroll") for (int n = 0; n < 2; ++n) _Pragma("unroll") for (int k = 0; k < 2; ++k) dst[n][k] = *(const PG8_LAS bf16x8*)(lds + PG8_SB(b, h) + boff + n * 2048 + k * 1024); } while (0)
; #define PG8_MMA(ai, bj, At, Bt) do { __builtin_amdgcn_s_setprio(1); _Pragma("unroll") for (int m = 0; m < 4; ++m) _Pragma("unroll") for (int n = 0; n < 2; ++n) _Pragma("unroll") for (int k = 0; k < 2; ++k) \
;         acc[ai][bj][m][n] = __builtin_amdgcn_mfma_f32_16x16x32_bf16(Bt[n][k], At[m][k], acc[ai][bj][m][n], 0, 0, 0); __builtin_amdgcn_s_setprio(0); } while (0)
; #define PG8_WAIT_V(n) asm volatile("s_waitcnt vmcnt(" #n ")" ::: "memory")
; #define PG8_WAIT_L(n) asm volatile("s_waitcnt lgkmcnt(" #n ")" ::: "memory")
; #define PG8_BAR __builtin_amdgcn_s_barrier()
; #define PG8_SCHED __builtin_amdgcn_sched_barrier(0)
; template <class Epi, class Sched, bool ALIGN_EPI = false, bool SP2 = false>
; __device__ __forceinline__ void gemm_phase(PG8_LAS unsigned char* lds, const Gemm g, const Sched& S, const Epi& E) {
;     ...
;             PG8_WAIT_V(8); PG8_WAIT_L(0); PG8_BAR; PG8_MMA(1, 0, At, B0); PG8_MMA(1, 1, At, B1); PG8_BAR; PG8_SCHED;
;             PG8_LDB(B0, 1, 0); PG8_LDB(B1, 1, 1); PG8_SCHED; PG8_LDA(At, 1, 0); PG8_STAGE(PG8_SA(0, 1), a2 + hstep, voffA);
;             PG8_WAIT_V(8); PG8_WAIT_L(0); PG8_BAR; PG8_MMA(0, 0, At, B0); PG8_MMA(0, 1, At, B1); PG8_BAR; PG8_SCHED;
	s_setprio 1
	v_mfma_f32_16x16x32_bf16 v[60:63], v[160:163], v[202:205], v[60:63]
	v_mfma_f32_16x16x32_bf16 v[56:59], v[168:171], v[202:205], v[56:59]
	v_mfma_f32_16x16x32_bf16 v[44:47], v[160:163], v[210:213], v[44:47]
	v_mfma_f32_16x16x32_bf16 v[40:43], v[168:171], v[210:213], v[40:43]
	v_mfma_f32_16x16x32_bf16 v[28:31], v[160:163], v[218:221], v[28:31]
	v_mfma_f32_16x16x32_bf16 v[24:27], v[168:171], v[218:221], v[24:27]
	v_mfma_f32_16x16x32_bf16 v[12:15], v[160:163], v[226:229], v[12:15]
	v_mfma_f32_16x16x32_bf16 v[8:11], v[168:171], v[226:229], v[8:11]
	v_mfma_f32_16x16x32_bf16 v[60:63], v[164:167], v[206:209], v[60:63]
	v_mfma_f32_16x16x32_bf16 v[56:59], v[172:175], v[206:209], v[56:59]
	v_mfma_f32_16x16x32_bf16 v[44:47], v[164:167], v[214:217], v[44:47]
	v_mfma_f32_16x16x32_bf16 v[40:43], v[172:175], v[214:217], v[40:43]
	v_mfma_f32_16x16x32_bf16 v[28:31], v[164:167], v[222:225], v[28:31]
	v_mfma_f32_16x16x32_bf16 v[24:27], v[172:175], v[222:225], v[24:27]
	v_mfma_f32_16x16x32_bf16 v[12:15], v[164:167], v[238:241], v[12:15]
	v_mfma_f32_16x16x32_bf16 v[8:11], v[172:175], v[238:241], v[8:11]
	v_mfma_f32_16x16x32_bf16 v[52:55], v[176:179], v[202:205], v[52:55]
	v_mfma_f32_16x16x32_bf16 v[48:51], v[184:187], v[202:205], v[48:51]
	v_mfma_f32_16x16x32_bf16 v[36:39], v[176:179], v[210:213], v[36:39]
	v_mfma_f32_16x16x32_bf16 v[32:35], v[184:187], v[210:213], v[32:35]
	v_mfma_f32_16x16x32_bf16 v[20:23], v[176:179], v[218:221], v[20:23]
	v_mfma_f32_16x16x32_bf16 v[16:19], v[184:187], v[218:221], v[16:19]
	v_mfma_f32_16x16x32_bf16 v[4:7], v[176:179], v[226:229], v[4:7]
	v_mfma_f32_16x16x32_bf16 v[0:3], v[184:187], v[226:229], v[0:3]
	v_mfma_f32_16x16x32_bf16 v[52:55], v[180:183], v[206:209], v[52:55]
	v_mfma_f32_16x16x32_bf16 v[48:51], v[198:201], v[206:209], v[48:51]
	v_mfma_f32_16x16x32_bf16 v[36:39], v[180:183], v[214:217], v[36:39]
	v_mfma_f32_16x16x32_bf16 v[32:35], v[198:201], v[214:217], v[32:35]
	v_mfma_f32_16x16x32_bf16 v[20:23], v[180:183], v[222:225], v[20:23]
	v_mfma_f32_16x16x32_bf16 v[16:19], v[198:201], v[222:225], v[16:19]
	v_mfma_f32_16x16x32_bf16 v[4:7], v[180:183], v[238:241], v[4:7]
	v_mfma_f32_16x16x32_bf16 v[0:3], v[198:201], v[238:241], v[0:3]
	s_setprio 0
	s_barrier
	s_add_i32 s60, 0, 0x18000
	s_add_i32 s61, 0, 0x1c000
	v_add_u32_e32 v172, s60, v157
	v_add_u32_e32 v194, s61, v157
	ds_read_b128 v[160:163], v172
	ds_read_b128 v[164:167], v172 offset:1024
	ds_read_b128 v[168:171], v172 offset:2048
	ds_read_b128 v[172:175], v172 offset:3072
	ds_read_b128 v[176:179], v194
	ds_read_b128 v[180:183], v194 offset:1024
	ds_read_b128 v[184:187], v194 offset:2048
	ds_read_b128 v[198:201], v194 offset:3072
	s_add_u32 s26, s26, 0x80000
	s_addc_u32 s27, s27, 0
	s_mov_b32 m0, s36
	v_lshl_add_u64 v[246:247], s[26:27], 0, v[132:133]
	ds_read_b128 v[202:205], v159 offset:32768
	ds_read_b128 v[206:209], v159 offset:33792
	ds_read_b128 v[210:213], v159 offset:34816
	ds_read_b128 v[214:217], v159 offset:35840
	ds_read_b128 v[218:221], v159 offset:36864
	ds_read_b128 v[222:225], v159 offset:37888
	ds_read_b128 v[226:229], v159 offset:38912
	ds_read_b128 v[238:241], v159 offset:39936
	global_load_lds_dwordx4 v[246:247], off
	v_lshl_add_u64 v[246:247], s[26:27], 0, v[130:131]
	s_mov_b32 m0, s37
	s_nop 0
	global_load_lds_dwordx4 v[246:247], off
	s_nop 0
	s_nop 0
	s_nop 0
	s_nop 0
	s_nop 0
	s_nop 0
	s_waitcnt vmcnt(8)
	s_waitcnt lgkmcnt(0)
	s_barrier
	s_setprio 1
	v_mfma_f32_16x16x32_bf16 v[124:127], v[160:163], v[202:205], v[124:127]
	v_mfma_f32_16x16x32_bf16 v[120:123], v[168:171], v[202:205], v[120:123]
	v_mfma_f32_16x16x32_bf16 v[108:111], v[160:163], v[210:213], v[108:111]
	v_mfma_f32_16x16x32_bf16 v[104:107], v[168:171], v[210:213], v[104:107]
	v_mfma_f32_16x16x32_bf16 v[92:95], v[160:163], v[218:221], v[92:95]
	v_mfma_f32_16x16x32_bf16 v[88:91], v[168:171], v[218:221], v[88:91]
	v_mfma_f32_16x16x32_bf16 v[76:79], v[160:163], v[226:229], v[76:79]
	v_mfma_f32_16x16x32_bf16 v[72:75], v[168:171], v[226:229], v[72:75]
	v_mfma_f32_16x16x32_bf16 v[124:127], v[164:167], v[206:209], v[124:127]
	v_mfma_f32_16x16x32_bf16 v[120:123], v[172:175], v[206:209], v[120:123]
	v_mfma_f32_16x16x32_bf16 v[108:111], v[164:167], v[214:217], v[108:111]
	v_mfma_f32_16x16x32_bf16 v[104:107], v[172:175], v[214:217], v[104:107]
	v_mfma_f32_16x16x32_bf16 v[92:95], v[164:167], v[222:225], v[92:95]
	v_mfma_f32_16x16x32_bf16 v[88:91], v[172:175], v[222:225], v[88:91]
	v_mfma_f32_16x16x32_bf16 v[76:79], v[164:167], v[238:241], v[76:79]
	v_mfma_f32_16x16x32_bf16 v[72:75], v[172:175], v[238:241], v[72:75]
	v_mfma_f32_16x16x32_bf16 v[116:119], v[176:179], v[202:205], v[116:119]
	v_mfma_f32_16x16x32_bf16 v[112:115], v[184:187], v[202:205], v[112:115]
	v_mfma_f32_16x16x32_bf16 v[100:103], v[176:179], v[210:213], v[100:103]
	v_mfma_f32_16x16x32_bf16 v[96:99], v[184:187], v[210:213], v[96:99]
	v_mfma_f32_16x16x32_bf16 v[84:87], v[176:179], v[218:221], v[84:87]
	v_mfma_f32_16x16x32_bf16 v[80:83], v[184:187], v[218:221], v[80:83]
	v_mfma_f32_16x16x32_bf16 v[68:71], v[176:179], v[226:229], v[68:71]
	v_mfma_f32_16x16x32_bf16 v[64:67], v[184:187], v[226:229], v[64:67]
	v_mfma_f32_16x16x32_bf16 v[116:119], v[180:183], v[206:209], v[116:119]
	v_mfma_f32_16x16x32_bf16 v[112:115], v[198:201], v[206:209], v[112:115]
	v_mfma_f32_16x16x32_bf16 v[100:103], v[180:183], v[214:217], v[100:103]
	v_mfma_f32_16x16x32_bf16 v[96:99], v[198:201], v[214:217], v[96:99]
	v_mfma_f32_16x16x32_bf16 v[84:87], v[180:183], v[222:225], v[84:87]
	v_mfma_f32_16x16x32_bf16 v[80:83], v[198:201], v[222:225], v[80:83]
	v_mfma_f32_16x16x32_bf16 v[68:71], v[180:183], v[238:241], v[68:71]
	v_mfma_f32_16x16x32_bf16 v[64:67], v[198:201], v[238:241], v[64:67]
	s_setprio 0
	s_barrier
; #define PG8_STAGE(bufoff, gbase, voff) do { _Pragma("unroll") for (int _i = 0; _i < 2; ++_i) \
;         __builtin_amdgcn_global_load_lds((const unsigned*)((const char*)(gbase) + (voff)[_i]), (PG8_LAS unsigned*)(lds + (bufoff) + ldsw + _i * 8192), 16, 0, 0); } while (0)
; #define PG8_LDA(dst, b, h) do { _Pragma("unroll") for (int m = 0; m < 4; ++m) _Pragma("unroll") for (int k = 0; k < 2; ++k) dst[m][k] = *(const PG8_LAS bf16x8*)(lds + PG8_SA(b, h) + aoff + m * 2048 + k * 1024); } while (0)
; #define PG8_MMA(ai, bj, At, Bt) do { __builtin_amdgcn_s_setprio(1); _Pragma("unroll") for (int m = 0; m < 4; ++m) _Pragma("unroll") for (int n = 0; n < 2; ++n) _Pragma("unroll") for (int k = 0; k < 2; ++k) \
;         acc[ai][bj][m][n] = __builtin_amdgcn_mfma_f32_16x16x32_bf16(Bt[n][k], At[m][k], acc[ai][bj][m][n], 0, 0, 0); __builtin_amdgcn_s_setprio(0); } while (0)
; #define PG8_WAIT_V(n) asm volatile("s_waitcnt vmcnt(" #n ")" ::: "memory")
; #define PG8_WAIT_L(n) asm volatile("s_waitcnt lgkmcnt(" #n ")" ::: "memory")
; #define PG8_BAR __builtin_amdgcn_s_barrier()
; #define PG8_SCHED __builtin_amdgcn_sched_barrier(0)
; template <class Epi, class Sched, bool ALIGN_EPI = false, bool SP2 = false>
; __device__ __forceinline__ void gemm_phase(PG8_LAS unsigned char* lds, const Gemm g, const Sched& S, const Epi& E) {
;     ...
;             PG8_LDA(At, 1, 1); PG8_STAGE(PG8_SB(1, 0), b3, voffB); PG8_STAGE(PG8_SB(1, 1), b3 + hstep, voffB); PG8_STAGE(PG8_SA(1, 0), a3, voffA);
;             PG8_WAIT_V(8); PG8_WAIT_L(0); PG8_BAR; PG8_MMA(1, 0, At, B0); PG8_MMA(1, 1, At, B1); PG8_BAR; PG8_SCHED;
	s_add_i32 s26, s60, s31
	v_lshl_add_u64 v[154:155], v[154:155], 0, s[78:79]
	s_mov_b32 m0, s26
	ds_read_b128 v[202:205], v159 offset:49152
	ds_read_b128 v[206:209], v159 offset:50176
	ds_read_b128 v[210:213], v159 offset:51200
	ds_read_b128 v[214:217], v159 offset:52224
	ds_read_b128 v[218:221], v159 offset:53248
	ds_read_b128 v[222:225], v159 offset:54272
	ds_read_b128 v[226:229], v159 offset:55296
	ds_read_b128 v[238:241], v159 offset:56320
	global_load_lds_dwordx4 v[154:155], off
	s_add_i32 m0, s26, 0x2000
	s_add_u32 s24, s24, 0x80080
	v_lshl_add_u64 v[154:155], v[232:233], 0, s[78:79]
	s_addc_u32 s25, s25, 0
	s_add_i32 s26, s61, s31
	global_load_lds_dwordx4 v[154:155], off
	v_lshl_add_u64 v[154:155], s[24:25], 0, v[188:189]
	s_mov_b32 m0, s26
	s_nop 0
	global_load_lds_dwordx4 v[154:155], off
	v_lshl_add_u64 v[154:155], s[24:25], 0, v[128:129]
	s_add_i32 m0, s26, 0x2000
	s_nop 0
	global_load_lds_dwordx4 v[154:155], off
	v_lshl_add_u64 v[154:155], v[242:243], 0, s[78:79]
	s_mov_b32 m0, s38
	s_nop 0
	global_load_lds_dwordx4 v[154:155], off
	v_lshl_add_u64 v[154:155], v[244:245], 0, s[78:79]
	s_mov_b32 m0, s39
	s_nop 0
	global_load_lds_dwordx4 v[154:155], off
	s_nop 0
	s_waitcnt vmcnt(8)
	s_waitcnt lgkmcnt(0)
	s_barrier
	s_setprio 1
	v_mfma_f32_16x16x32_bf16 v[60:63], v[160:163], v[202:205], v[60:63]
	v_mfma_f32_16x16x32_bf16 v[56:59], v[168:171], v[202:205], v[56:59]
	v_mfma_f32_16x16x32_bf16 v[44:47], v[160:163], v[210:213], v[44:47]
	v_mfma_f32_16x16x32_bf16 v[40:43], v[168:171], v[210:213], v[40:43]
	v_mfma_f32_16x16x32_bf16 v[28:31], v[160:163], v[218:221], v[28:31]
	v_mfma_f32_16x16x32_bf16 v[24:27], v[168:171], v[218:221], v[24:27]
	v_mfma_f32_16x16x32_bf16 v[12:15], v[160:163], v[226:229], v[12:15]
	v_mfma_f32_16x16x32_bf16 v[8:11], v[168:171], v[226:229], v[8:11]
	v_mfma_f32_16x16x32_bf16 v[60:63], v[164:167], v[206:209], v[60:63]
	v_mfma_f32_16x16x32_bf16 v[56:59], v[172:175], v[206:209], v[56:59]
	v_mfma_f32_16x16x32_bf16 v[44:47], v[164:167], v[214:217], v[44:47]
	v_mfma_f32_16x16x32_bf16 v[40:43], v[172:175], v[214:217], v[40:43]
	v_mfma_f32_16x16x32_bf16 v[28:31], v[164:167], v[222:225], v[28:31]
	v_mfma_f32_16x16x32_bf16 v[24:27], v[172:175], v[222:225], v[24:27]
	v_mfma_f32_16x16x32_bf16 v[12:15], v[164:167], v[238:241], v[12:15]
	v_mfma_f32_16x16x32_bf16 v[8:11], v[172:175], v[238:241], v[8:11]
	v_mfma_f32_16x16x32_bf16 v[52:55], v[176:179], v[202:205], v[52:55]
	v_mfma_f32_16x16x32_bf16 v[48:51], v[184:187], v[202:205], v[48:51]
	v_mfma_f32_16x16x32_bf16 v[36:39], v[176:179], v[210:213], v[36:39]
	v_mfma_f32_16x16x32_bf16 v[32:35], v[184:187], v[210:213], v[32:35]
	v_mfma_f32_16x16x32_bf16 v[20:23], v[176:179], v[218:221], v[20:23]
	v_mfma_f32_16x16x32_bf16 v[16:19], v[184:187], v[218:221], v[16:19]
	v_mfma_f32_16x16x32_bf16 v[4:7], v[176:179], v[226:229], v[4:7]
	v_mfma_f32_16x16x32_bf16 v[0:3], v[184:187], v[226:229], v[0:3]
	v_mfma_f32_16x16x32_bf16 v[52:55], v[180:183], v[206:209], v[52:55]
	v_mfma_f32_16x16x32_bf16 v[48:51], v[198:201], v[206:209], v[48:51]
	v_mfma_f32_16x16x32_bf16 v[36:39], v[180:183], v[214:217], v[36:39]
	v_mfma_f32_16x16x32_bf16 v[32:35], v[198:201], v[214:217], v[32:35]
	v_mfma_f32_16x16x32_bf16 v[20:23], v[180:183], v[222:225], v[20:23]
	v_mfma_f32_16x16x32_bf16 v[16:19], v[198:201], v[222:225], v[16:19]
	v_mfma_f32_16x16x32_bf16 v[4:7], v[180:183], v[238:241], v[4:7]
	v_mfma_f32_16x16x32_bf16 v[0:3], v[198:201], v[238:241], v[0:3]
	s_setprio 0
	s_barrier
	s_add_i32 s63, s63, 2
	s_add_u32 s8, s8, 0x100
	s_addc_u32 s9, s9, 0
	s_add_u32 s58, s58, 0x100
	s_addc_u32 s62, s62, 0
	s_cmp_gt_u32 s63, 29
	s_cbranch_scc0 .LBB0_684
	s_and_b64 vcc, exec, s[14:15]
	s_cbranch_vccz .LBB0_687
	s_barrier

; #define PG8_STAGE(bufoff, gbase, voff) do { _Pragma("unroll") for (int _i = 0; _i < 2; ++_i) \
;         __builtin_amdgcn_global_load_lds((const unsigned*)((const char*)(gbase) + (voff)[_i]), (PG8_LAS unsigned*)(lds + (bufoff) + ldsw + _i * 8192), 16, 0, 0); } while (0)
; #define PG8_LDA(dst, b, h) do { _Pragma("unroll") for (int m = 0; m < 4; ++m) _Pragma("unroll") for (int k = 0; k < 2; ++k) dst[m][k] = *(const PG8_LAS bf16x8*)(lds + PG8_SA(b, h) + aoff + m * 2048 + k * 1024); } while (0)
; #define PG8_LDB(dst, b, h) do { _Pragma("unroll") for (int n = 0; n < 2; ++n) _Pragma("unroll") for (int k = 0; k < 2; ++k) dst[n][k] = *(const PG8_LAS bf16x8*)(lds + PG8_SB(b, h) + boff + n * 2048 + k * 1024); } while (0)
; #define PG8_MMA(ai, bj, At, Bt) do { __builtin_amdgcn_s_setprio(1); _Pragma("unroll") for (int m = 0; m < 4; ++m) _Pragma("unroll") for (int n = 0; n < 2; ++n) _Pragma("unroll") for (int k = 0; k < 2; ++k) \
;         acc[ai][bj][m][n] = __builtin_amdgcn_mfma_f32_16x16x32_bf16(Bt[n][k], At[m][k], acc[ai][bj][m][n], 0, 0, 0); __builtin_amdgcn_s_setprio(0); } while (0)
; #define PG8_WAIT_V(n) asm volatile("s_waitcnt vmcnt(" #n ")" ::: "memory")
; #define PG8_WAIT_L(n) asm volatile("s_waitcnt lgkmcnt(" #n ")" ::: "memory")
; #define PG8_BAR __builtin_amdgcn_s_barrier()
; #define PG8_SCHED __builtin_amdgcn_sched_barrier(0)
; template <class Epi, class Sched, bool ALIGN_EPI = false, bool SP2 = false>
; __device__ __forceinline__ void gemm_phase(PG8_LAS unsigned char* lds, const Gemm g, const Sched& S, const Epi& E) {
;     ...
;             const bool last = (t == nt - 2);
;             const char* a1 = cA + (size_t)(t + 1) * kstep;
;             const char* a2 = last ? nA : cA + (size_t)(t + 2) * kstep; const char* b2 = last ? nB : cB + (size_t)(t + 2) * kstep;
;             const char* a3 = a2 + kstep; const char* b3 = b2 + kstep;
;             if (last && has_next) S.a_ready(nxt);
;             if constexpr (SP2) {
;             PG8_LDB(B0, 0, 0); PG8_LDB(B1, 0, 1); PG8_SCHED; PG8_LDA(At, 0, 0); PG8_STAGE(PG8_SA(1, 1), a1 + hstep, voffA);
;             PG8_WAIT_V(8); PG8_WAIT_L(0); PG8_BAR; PG8_MMA(0, 0, At, B0); PG8_MMA(0, 1, At, B1); PG8_BAR; PG8_SCHED;
;             PG8_LDA(At, 0, 1); PG8_STAGE(PG8_SB(0, 0), b2, voffB); PG8_STAGE(PG8_SB(0, 1), b2 + hstep, voffB); PG8_STAGE(PG8_SA(0, 0), a2, voffA);
.LBB0_757:
	s_add_u32 s28, s26, 0xffe00080
	s_addc_u32 s29, s27, -1
	s_add_i32 s60, 0, 0x10000
	s_cmpk_eq_i32 s72, 0x7c
	s_cselect_b32 s31, s21, s29
	s_cselect_b32 s30, s63, s28
	s_cselect_b32 s29, s19, s68
	s_cselect_b32 s28, s66, s67
	s_add_i32 s73, 0, 0x14000
	v_add_u32_e32 v124, s60, v239
	v_add_u32_e32 v148, s73, v239
	ds_read_b128 v[112:115], v124
	ds_read_b128 v[116:119], v124 offset:1024
	ds_read_b128 v[120:123], v124 offset:2048
	ds_read_b128 v[124:127], v124 offset:3072
	ds_read_b128 v[132:135], v148
	ds_read_b128 v[140:143], v148 offset:1024
	ds_read_b128 v[144:147], v148 offset:2048
	ds_read_b128 v[148:151], v148 offset:3072
	v_lshl_add_u64 v[212:213], s[26:27], 0, v[204:205]
	s_add_i32 m0, s38, 0xc000
	ds_read_b128 v[152:155], v241
	ds_read_b128 v[164:167], v241 offset:1024
	ds_read_b128 v[168:171], v241 offset:2048
	ds_read_b128 v[172:175], v241 offset:3072
	ds_read_b128 v[176:179], v241 offset:4096
	ds_read_b128 v[180:183], v241 offset:5120
	ds_read_b128 v[184:187], v241 offset:6144
	ds_read_b128 v[208:211], v241 offset:7168
	global_load_lds_dwordx4 v[212:213], off
	v_lshl_add_u64 v[212:213], s[26:27], 0, v[206:207]
	s_add_i32 m0, s38, 0xe000
	s_nop 0
	global_load_lds_dwordx4 v[212:213], off
	s_nop 0
	s_nop 0
	s_nop 0
	s_waitcnt vmcnt(8)
	s_waitcnt lgkmcnt(0)
	s_barrier
	s_setprio 1
	v_mfma_f32_16x16x32_bf16 v[160:163], v[112:115], v[152:155], v[160:163]
	v_mfma_f32_16x16x32_bf16 v[156:159], v[120:123], v[152:155], v[156:159]
	v_mfma_f32_16x16x32_bf16 v[108:111], v[112:115], v[168:171], v[108:111]
	v_mfma_f32_16x16x32_bf16 v[104:107], v[120:123], v[168:171], v[104:107]
	v_mfma_f32_16x16x32_bf16 v[92:95], v[112:115], v[176:179], v[92:95]
	v_mfma_f32_16x16x32_bf16 v[88:91], v[120:123], v[176:179], v[88:91]
	v_mfma_f32_16x16x32_bf16 v[76:79], v[112:115], v[184:187], v[76:79]
	v_mfma_f32_16x16x32_bf16 v[72:75], v[120:123], v[184:187], v[72:75]
	v_mfma_f32_16x16x32_bf16 v[160:163], v[116:119], v[164:167], v[160:163]
	v_mfma_f32_16x16x32_bf16 v[156:159], v[124:127], v[164:167], v[156:159]
	v_mfma_f32_16x16x32_bf16 v[108:111], v[116:119], v[172:175], v[108:111]
	v_mfma_f32_16x16x32_bf16 v[104:107], v[124:127], v[172:175], v[104:107]
	v_mfma_f32_16x16x32_bf16 v[92:95], v[116:119], v[180:183], v[92:95]
	v_mfma_f32_16x16x32_bf16 v[88:91], v[124:127], v[180:183], v[88:91]
	v_mfma_f32_16x16x32_bf16 v[76:79], v[116:119], v[208:211], v[76:79]
	v_mfma_f32_16x16x32_bf16 v[72:75], v[124:127], v[208:211], v[72:75]
	v_mfma_f32_16x16x32_bf16 v[136:139], v[132:135], v[152:155], v[136:139]
	v_mfma_f32_16x16x32_bf16 v[128:131], v[144:147], v[152:155], v[128:131]
	v_mfma_f32_16x16x32_bf16 v[100:103], v[132:135], v[168:171], v[100:103]
	v_mfma_f32_16x16x32_bf16 v[96:99], v[144:147], v[168:171], v[96:99]
	v_mfma_f32_16x16x32_bf16 v[84:87], v[132:135], v[176:179], v[84:87]
	v_mfma_f32_16x16x32_bf16 v[80:83], v[144:147], v[176:179], v[80:83]
	v_mfma_f32_16x16x32_bf16 v[68:71], v[132:135], v[184:187], v[68:71]
	v_mfma_f32_16x16x32_bf16 v[64:67], v[144:147], v[184:187], v[64:67]
	v_mfma_f32_16x16x32_bf16 v[136:139], v[140:143], v[164:167], v[136:139]
	v_mfma_f32_16x16x32_bf16 v[128:131], v[148:151], v[164:167], v[128:131]
	v_mfma_f32_16x16x32_bf16 v[100:103], v[140:143], v[172:175], v[100:103]
	v_mfma_f32_16x16x32_bf16 v[96:99], v[148:151], v[172:175], v[96:99]
	v_mfma_f32_16x16x32_bf16 v[84:87], v[140:143], v[180:183], v[84:87]
	v_mfma_f32_16x16x32_bf16 v[80:83], v[148:151], v[180:183], v[80:83]
	v_mfma_f32_16x16x32_bf16 v[68:71], v[140:143], v[208:211], v[68:71]
	v_mfma_f32_16x16x32_bf16 v[64:67], v[148:151], v[208:211], v[64:67]
	s_setprio 0
	s_barrier
	s_add_i32 s60, s60, s37
	v_lshl_add_u64 v[212:213], s[28:29], 0, v[188:189]
	s_mov_b32 m0, s60
	ds_read_b128 v[152:155], v241 offset:16384
	ds_read_b128 v[164:167], v241 offset:17408
	ds_read_b128 v[168:171], v241 offset:18432
	ds_read_b128 v[172:175], v241 offset:19456
	ds_read_b128 v[176:179], v241 offset:20480
	ds_read_b128 v[180:183], v241 offset:21504
	ds_read_b128 v[184:187], v241 offset:22528
	ds_read_b128 v[208:211], v241 offset:23552
	global_load_lds_dwordx4 v[212:213], off
	s_add_i32 m0, s60, 0x2000
	s_add_u32 s60, s28, 0x200000
	v_lshl_add_u64 v[214:215], s[28:29], 0, v[198:199]
	s_addc_u32 s61, s29, 0
	s_add_i32 s73, s73, s37
	global_load_lds_dwordx4 v[214:215], off
	v_lshl_add_u64 v[216:217], s[60:61], 0, v[188:189]
	s_mov_b32 m0, s73
	v_lshl_add_u64 v[218:219], s[30:31], 0, v[200:201]
	global_load_lds_dwordx4 v[216:217], off
	v_lshl_add_u64 v[216:217], s[60:61], 0, v[198:199]
	s_add_i32 m0, s73, 0x2000
	s_nop 0
	global_load_lds_dwordx4 v[216:217], off
	v_lshl_add_u64 v[216:217], s[30:31], 0, v[202:203]
	s_mov_b32 m0, s38
	s_nop 0
	global_load_lds_dwordx4 v[216:217], off
	s_mov_b32 m0, s39
	s_nop 0
	global_load_lds_dwordx4 v[218:219], off
	s_nop 0
	s_nop 0
	s_waitcnt vmcnt(8)
	s_waitcnt lgkmcnt(0)
	s_barrier
; #define PG8_STAGE(bufoff, gbase, voff) do { _Pragma("unroll") for (int _i = 0; _i < 2; ++_i) \
;         __builtin_amdgcn_global_load_lds((const unsigned*)((const char*)(gbase) + (voff)[_i]), (PG8_LAS unsigned*)(lds + (bufoff) + ldsw + _i * 8192), 16, 0, 0); } while (0)
; #define PG8_LDA(dst, b, h) do { _Pragma("unroll") for (int m = 0; m < 4; ++m) _Pragma("unroll") for (int k = 0; k < 2; ++k) dst[m][k] = *(const PG8_LAS bf16x8*)(lds + PG8_SA(b, h) + aoff + m * 2048 + k * 1024); } while (0)
; #define PG8_LDB(dst, b, h) do { _Pragma("unroll") for (int n = 0; n < 2; ++n) _Pragma("unroll") for (int k = 0; k < 2; ++k) dst[n][k] = *(const PG8_LAS bf16x8*)(lds + PG8_SB(b, h) + boff + n * 2048 + k * 1024); } while (0)
; #define PG8_MMA(ai, bj, At, Bt) do { __builtin_amdgcn_s_setprio(1); _Pragma("unroll") for (int m = 0; m < 4; ++m) _Pragma("unroll") for (int n = 0; n < 2; ++n) _Pragma("unroll") for (int k = 0; k < 2; ++k) \
;         acc[ai][bj][m][n] = __builtin_amdgcn_mfma_f32_16x16x32_bf16(Bt[n][k], At[m][k], acc[ai][bj][m][n], 0, 0, 0); __builtin_amdgcn_s_setprio(0); } while (0)
; #define PG8_WAIT_V(n) asm volatile("s_waitcnt vmcnt(" #n ")" ::: "memory")
; #define PG8_WAIT_L(n) asm volatile("s_waitcnt lgkmcnt(" #n ")" ::: "memory")
; #define PG8_BAR __builtin_amdgcn_s_barrier()
; #define PG8_SCHED __builtin_amdgcn_sched_barrier(0)
; template <class Epi, class Sched, bool ALIGN_EPI = false, bool SP2 = false>
; __device__ __forceinline__ void gemm_phase(PG8_LAS unsigned char* lds, const Gemm g, const Sched& S, const Epi& E) {
;     ...
;             PG8_WAIT_V(8); PG8_WAIT_L(0); PG8_BAR; PG8_MMA(1, 0, At, B0); PG8_MMA(1, 1, At, B1); PG8_BAR; PG8_SCHED;
;             PG8_LDB(B0, 1, 0); PG8_LDB(B1, 1, 1); PG8_SCHED; PG8_LDA(At, 1, 0); PG8_STAGE(PG8_SA(0, 1), a2 + hstep, voffA);
;             PG8_WAIT_V(8); PG8_WAIT_L(0); PG8_BAR; PG8_MMA(0, 0, At, B0); PG8_MMA(0, 1, At, B1); PG8_BAR; PG8_SCHED;
	s_setprio 1
	v_mfma_f32_16x16x32_bf16 v[60:63], v[112:115], v[152:155], v[60:63]
	v_mfma_f32_16x16x32_bf16 v[56:59], v[120:123], v[152:155], v[56:59]
	v_mfma_f32_16x16x32_bf16 v[44:47], v[112:115], v[168:171], v[44:47]
	v_mfma_f32_16x16x32_bf16 v[40:43], v[120:123], v[168:171], v[40:43]
	v_mfma_f32_16x16x32_bf16 v[28:31], v[112:115], v[176:179], v[28:31]
	v_mfma_f32_16x16x32_bf16 v[24:27], v[120:123], v[176:179], v[24:27]
	v_mfma_f32_16x16x32_bf16 v[12:15], v[112:115], v[184:187], v[12:15]
	v_mfma_f32_16x16x32_bf16 v[8:11], v[120:123], v[184:187], v[8:11]
	v_mfma_f32_16x16x32_bf16 v[60:63], v[116:119], v[164:167], v[60:63]
	v_mfma_f32_16x16x32_bf16 v[56:59], v[124:127], v[164:167], v[56:59]
	v_mfma_f32_16x16x32_bf16 v[44:47], v[116:119], v[172:175], v[44:47]
	v_mfma_f32_16x16x32_bf16 v[40:43], v[124:127], v[172:175], v[40:43]
	v_mfma_f32_16x16x32_bf16 v[28:31], v[116:119], v[180:183], v[28:31]
	v_mfma_f32_16x16x32_bf16 v[24:27], v[124:127], v[180:183], v[24:27]
	v_mfma_f32_16x16x32_bf16 v[12:15], v[116:119], v[208:211], v[12:15]
	v_mfma_f32_16x16x32_bf16 v[8:11], v[124:127], v[208:211], v[8:11]
	v_mfma_f32_16x16x32_bf16 v[52:55], v[132:135], v[152:155], v[52:55]
	v_mfma_f32_16x16x32_bf16 v[48:51], v[144:147], v[152:155], v[48:51]
	v_mfma_f32_16x16x32_bf16 v[36:39], v[132:135], v[168:171], v[36:39]
	v_mfma_f32_16x16x32_bf16 v[32:35], v[144:147], v[168:171], v[32:35]
	v_mfma_f32_16x16x32_bf16 v[20:23], v[132:135], v[176:179], v[20:23]
	v_mfma_f32_16x16x32_bf16 v[16:19], v[144:147], v[176:179], v[16:19]
	v_mfma_f32_16x16x32_bf16 v[4:7], v[132:135], v[184:187], v[4:7]
	v_mfma_f32_16x16x32_bf16 v[0:3], v[144:147], v[184:187], v[0:3]
	v_mfma_f32_16x16x32_bf16 v[52:55], v[140:143], v[164:167], v[52:55]
	v_mfma_f32_16x16x32_bf16 v[48:51], v[148:151], v[164:167], v[48:51]
	v_mfma_f32_16x16x32_bf16 v[36:39], v[140:143], v[172:175], v[36:39]
	v_mfma_f32_16x16x32_bf16 v[32:35], v[148:151], v[172:175], v[32:35]
	v_mfma_f32_16x16x32_bf16 v[20:23], v[140:143], v[180:183], v[20:23]
	v_mfma_f32_16x16x32_bf16 v[16:19], v[148:151], v[180:183], v[16:19]
	v_mfma_f32_16x16x32_bf16 v[4:7], v[140:143], v[208:211], v[4:7]
	v_mfma_f32_16x16x32_bf16 v[0:3], v[148:151], v[208:211], v[0:3]
	s_setprio 0
	s_barrier
	s_add_i32 s60, 0, 0x18000
	s_add_i32 s61, 0, 0x1c000
	v_add_u32_e32 v124, s60, v239
	v_add_u32_e32 v148, s61, v239
	ds_read_b128 v[112:115], v124
	ds_read_b128 v[116:119], v124 offset:1024
	ds_read_b128 v[120:123], v124 offset:2048
	ds_read_b128 v[124:127], v124 offset:3072
	ds_read_b128 v[132:135], v148
	ds_read_b128 v[140:143], v148 offset:1024
	ds_read_b128 v[144:147], v148 offset:2048
	ds_read_b128 v[148:151], v148 offset:3072
	s_add_u32 s30, s30, 0x200000
	s_addc_u32 s31, s31, 0
	s_mov_b32 m0, s40
	v_lshl_add_u64 v[220:221], s[30:31], 0, v[202:203]
	ds_read_b128 v[152:155], v241 offset:32768
	ds_read_b128 v[164:167], v241 offset:33792
	ds_read_b128 v[168:171], v241 offset:34816
	ds_read_b128 v[172:175], v241 offset:35840
	ds_read_b128 v[176:179], v241 offset:36864
	ds_read_b128 v[180:183], v241 offset:37888
	ds_read_b128 v[184:187], v241 offset:38912
	ds_read_b128 v[208:211], v241 offset:39936
	global_load_lds_dwordx4 v[220:221], off
	v_lshl_add_u64 v[220:221], s[30:31], 0, v[200:201]
	s_mov_b32 m0, s41
	s_nop 0
	global_load_lds_dwordx4 v[220:221], off
	s_nop 0
	s_nop 0
	s_nop 0
	s_nop 0
	s_nop 0
	s_nop 0
	s_waitcnt vmcnt(8)
	s_waitcnt lgkmcnt(0)
	s_barrier
	s_setprio 1
	v_mfma_f32_16x16x32_bf16 v[160:163], v[112:115], v[152:155], v[160:163]
	v_mfma_f32_16x16x32_bf16 v[156:159], v[120:123], v[152:155], v[156:159]
	v_mfma_f32_16x16x32_bf16 v[108:111], v[112:115], v[168:171], v[108:111]
	v_mfma_f32_16x16x32_bf16 v[104:107], v[120:123], v[168:171], v[104:107]
	v_mfma_f32_16x16x32_bf16 v[92:95], v[112:115], v[176:179], v[92:95]
	v_mfma_f32_16x16x32_bf16 v[88:91], v[120:123], v[176:179], v[88:91]
	v_mfma_f32_16x16x32_bf16 v[76:79], v[112:115], v[184:187], v[76:79]
	v_mfma_f32_16x16x32_bf16 v[72:75], v[120:123], v[184:187], v[72:75]
	v_mfma_f32_16x16x32_bf16 v[160:163], v[116:119], v[164:167], v[160:163]
	v_mfma_f32_16x16x32_bf16 v[156:159], v[124:127], v[164:167], v[156:159]
	v_mfma_f32_16x16x32_bf16 v[108:111], v[116:119], v[172:175], v[108:111]
	v_mfma_f32_16x16x32_bf16 v[104:107], v[124:127], v[172:175], v[104:107]
	v_mfma_f32_16x16x32_bf16 v[92:95], v[116:119], v[180:183], v[92:95]
	v_mfma_f32_16x16x32_bf16 v[88:91], v[124:127], v[180:183], v[88:91]
	v_mfma_f32_16x16x32_bf16 v[76:79], v[116:119], v[208:211], v[76:79]
	v_mfma_f32_16x16x32_bf16 v[72:75], v[124:127], v[208:211], v[72:75]
	v_mfma_f32_16x16x32_bf16 v[136:139], v[132:135], v[152:155], v[136:139]
	v_mfma_f32_16x16x32_bf16 v[128:131], v[144:147], v[152:155], v[128:131]
	v_mfma_f32_16x16x32_bf16 v[100:103], v[132:135], v[168:171], v[100:103]
	v_mfma_f32_16x16x32_bf16 v[96:99], v[144:147], v[168:171], v[96:99]
	v_mfma_f32_16x16x32_bf16 v[84:87], v[132:135], v[176:179], v[84:87]
	v_mfma_f32_16x16x32_bf16 v[80:83], v[144:147], v[176:179], v[80:83]
	v_mfma_f32_16x16x32_bf16 v[68:71], v[132:135], v[184:187], v[68:71]
	v_mfma_f32_16x16x32_bf16 v[64:67], v[144:147], v[184:187], v[64:67]
	v_mfma_f32_16x16x32_bf16 v[136:139], v[140:143], v[164:167], v[136:139]
	v_mfma_f32_16x16x32_bf16 v[128:131], v[148:151], v[164:167], v[128:131]
	v_mfma_f32_16x16x32_bf16 v[100:103], v[140:143], v[172:175], v[100:103]
	v_mfma_f32_16x16x32_bf16 v[96:99], v[148:151], v[172:175], v[96:99]
	v_mfma_f32_16x16x32_bf16 v[84:87], v[140:143], v[180:183], v[84:87]
	v_mfma_f32_16x16x32_bf16 v[80:83], v[148:151], v[180:183], v[80:83]
	v_mfma_f32_16x16x32_bf16 v[68:71], v[140:143], v[208:211], v[68:71]
	v_mfma_f32_16x16x32_bf16 v[64:67], v[148:151], v[208:211], v[64:67]
	s_setprio 0
	s_barrier
; #define PG8_STAGE(bufoff, gbase, voff) do { _Pragma("unroll") for (int _i = 0; _i < 2; ++_i) \
;         __builtin_amdgcn_global_load_lds((const unsigned*)((const char*)(gbase) + (voff)[_i]), (PG8_LAS unsigned*)(lds + (bufoff) + ldsw + _i * 8192), 16, 0, 0); } while (0)
; #define PG8_LDA(dst, b, h) do { _Pragma("unroll") for (int m = 0; m < 4; ++m) _Pragma("unroll") for (int k = 0; k < 2; ++k) dst[m][k] = *(const PG8_LAS bf16x8*)(lds + PG8_SA(b, h) + aoff + m * 2048 + k * 1024); } while (0)
; #define PG8_MMA(ai, bj, At, Bt) do { __builtin_amdgcn_s_setprio(1); _Pragma("unroll") for (int m = 0; m < 4; ++m) _Pragma("unroll") for (int n = 0; n < 2; ++n) _Pragma("unroll") for (int k = 0; k < 2; ++k) \
;         acc[ai][bj][m][n] = __builtin_amdgcn_mfma_f32_16x16x32_bf16(Bt[n][k], At[m][k], acc[ai][bj][m][n], 0, 0, 0); __builtin_amdgcn_s_setprio(0); } while (0)
; #define PG8_WAIT_V(n) asm volatile("s_waitcnt vmcnt(" #n ")" ::: "memory")
; #define PG8_WAIT_L(n) asm volatile("s_waitcnt lgkmcnt(" #n ")" ::: "memory")
; #define PG8_BAR __builtin_amdgcn_s_barrier()
; #define PG8_SCHED __builtin_amdgcn_sched_barrier(0)
; template <class Epi, class Sched, bool ALIGN_EPI = false, bool SP2 = false>
; __device__ __forceinline__ void gemm_phase(PG8_LAS unsigned char* lds, const Gemm g, const Sched& S, const Epi& E) {
;     ...
;             PG8_LDA(At, 1, 1); PG8_STAGE(PG8_SB(1, 0), b3, voffB); PG8_STAGE(PG8_SB(1, 1), b3 + hstep, voffB); PG8_STAGE(PG8_SA(1, 0), a3, voffA);
;             PG8_WAIT_V(8); PG8_WAIT_L(0); PG8_BAR; PG8_MMA(1, 0, At, B0); PG8_MMA(1, 1, At, B1); PG8_BAR; PG8_SCHED;
	s_add_i32 s30, s60, s37
	v_lshl_add_u64 v[212:213], v[212:213], 0, s[78:79]
	s_mov_b32 m0, s30
	ds_read_b128 v[152:155], v241 offset:49152
	ds_read_b128 v[164:167], v241 offset:50176
	ds_read_b128 v[168:171], v241 offset:51200
	ds_read_b128 v[172:175], v241 offset:52224
	ds_read_b128 v[176:179], v241 offset:53248
	ds_read_b128 v[180:183], v241 offset:54272
	ds_read_b128 v[184:187], v241 offset:55296
	ds_read_b128 v[208:211], v241 offset:56320
	global_load_lds_dwordx4 v[212:213], off
	s_add_i32 m0, s30, 0x2000
	s_add_u32 s28, s28, 0x200080
	v_lshl_add_u64 v[212:213], v[214:215], 0, s[78:79]
	s_addc_u32 s29, s29, 0
	s_add_i32 s30, s61, s37
	global_load_lds_dwordx4 v[212:213], off
	v_lshl_add_u64 v[212:213], s[28:29], 0, v[188:189]
	s_mov_b32 m0, s30
	s_nop 0
	global_load_lds_dwordx4 v[212:213], off
	v_lshl_add_u64 v[212:213], s[28:29], 0, v[198:199]
	s_add_i32 m0, s30, 0x2000
	s_nop 0
	global_load_lds_dwordx4 v[212:213], off
	v_lshl_add_u64 v[212:213], v[216:217], 0, s[78:79]
	s_mov_b32 m0, s44
	s_nop 0
	global_load_lds_dwordx4 v[212:213], off
	v_lshl_add_u64 v[212:213], v[218:219], 0, s[78:79]
	s_mov_b32 m0, s45
	s_nop 0
	global_load_lds_dwordx4 v[212:213], off
	s_nop 0
	s_waitcnt vmcnt(8)
	s_waitcnt lgkmcnt(0)
	s_barrier
	s_setprio 1
	v_mfma_f32_16x16x32_bf16 v[60:63], v[112:115], v[152:155], v[60:63]
	v_mfma_f32_16x16x32_bf16 v[56:59], v[120:123], v[152:155], v[56:59]
	v_mfma_f32_16x16x32_bf16 v[44:47], v[112:115], v[168:171], v[44:47]
	v_mfma_f32_16x16x32_bf16 v[40:43], v[120:123], v[168:171], v[40:43]
	v_mfma_f32_16x16x32_bf16 v[28:31], v[112:115], v[176:179], v[28:31]
	v_mfma_f32_16x16x32_bf16 v[24:27], v[120:123], v[176:179], v[24:27]
	v_mfma_f32_16x16x32_bf16 v[12:15], v[112:115], v[184:187], v[12:15]
	v_mfma_f32_16x16x32_bf16 v[8:11], v[120:123], v[184:187], v[8:11]
	v_mfma_f32_16x16x32_bf16 v[60:63], v[116:119], v[164:167], v[60:63]
	v_mfma_f32_16x16x32_bf16 v[56:59], v[124:127], v[164:167], v[56:59]
	v_mfma_f32_16x16x32_bf16 v[44:47], v[116:119], v[172:175], v[44:47]
	v_mfma_f32_16x16x32_bf16 v[40:43], v[124:127], v[172:175], v[40:43]
	v_mfma_f32_16x16x32_bf16 v[28:31], v[116:119], v[180:183], v[28:31]
	v_mfma_f32_16x16x32_bf16 v[24:27], v[124:127], v[180:183], v[24:27]
	v_mfma_f32_16x16x32_bf16 v[12:15], v[116:119], v[208:211], v[12:15]
	v_mfma_f32_16x16x32_bf16 v[8:11], v[124:127], v[208:211], v[8:11]
	v_mfma_f32_16x16x32_bf16 v[52:55], v[132:135], v[152:155], v[52:55]
	v_mfma_f32_16x16x32_bf16 v[48:51], v[144:147], v[152:155], v[48:51]
	v_mfma_f32_16x16x32_bf16 v[36:39], v[132:135], v[168:171], v[36:39]
	v_mfma_f32_16x16x32_bf16 v[32:35], v[144:147], v[168:171], v[32:35]
	v_mfma_f32_16x16x32_bf16 v[20:23], v[132:135], v[176:179], v[20:23]
	v_mfma_f32_16x16x32_bf16 v[16:19], v[144:147], v[176:179], v[16:19]
	v_mfma_f32_16x16x32_bf16 v[4:7], v[132:135], v[184:187], v[4:7]
	v_mfma_f32_16x16x32_bf16 v[0:3], v[144:147], v[184:187], v[0:3]
	v_mfma_f32_16x16x32_bf16 v[52:55], v[140:143], v[164:167], v[52:55]
	v_mfma_f32_16x16x32_bf16 v[48:51], v[148:151], v[164:167], v[48:51]
	v_mfma_f32_16x16x32_bf16 v[36:39], v[140:143], v[172:175], v[36:39]
	v_mfma_f32_16x16x32_bf16 v[32:35], v[148:151], v[172:175], v[32:35]
	v_mfma_f32_16x16x32_bf16 v[20:23], v[140:143], v[180:183], v[20:23]
	v_mfma_f32_16x16x32_bf16 v[16:19], v[148:151], v[180:183], v[16:19]
	v_mfma_f32_16x16x32_bf16 v[4:7], v[140:143], v[208:211], v[4:7]
	v_mfma_f32_16x16x32_bf16 v[0:3], v[148:151], v[208:211], v[0:3]
	s_setprio 0
	s_barrier
	s_add_i32 s72, s72, 2
	s_add_u32 s26, s26, 0x100
	s_addc_u32 s27, s27, 0
	s_add_u32 s67, s67, 0x100
	s_addc_u32 s68, s68, 0
	s_cmpk_gt_u32 s72, 0x7d
	s_cbranch_scc0 .LBB0_757
	s_and_b64 vcc, exec, s[16:17]
	s_cbranch_vccz .LBB0_760
	s_barrier

; #define PG8_STAGE(bufoff, gbase, voff) do { _Pragma("unroll") for (int _i = 0; _i < 2; ++_i) \
;         __builtin_amdgcn_global_load_lds((const unsigned*)((const char*)(gbase) + (voff)[_i]), (PG8_LAS unsigned*)(lds + (bufoff) + ldsw + _i * 8192), 16, 0, 0); } while (0)
; #define PG8_LDA(dst, b, h) do { _Pragma("unroll") for (int m = 0; m < 4; ++m) _Pragma("unroll") for (int k = 0; k < 2; ++k) dst[m][k] = *(const PG8_LAS bf16x8*)(lds + PG8_SA(b, h) + aoff + m * 2048 + k * 1024); } while (0)
; #define PG8_LDB(dst, b, h) do { _Pragma("unroll") for (int n = 0; n < 2; ++n) _Pragma("unroll") for (int k = 0; k < 2; ++k) dst[n][k] = *(const PG8_LAS bf16x8*)(lds + PG8_SB(b, h) + boff + n * 2048 + k * 1024); } while (0)
; #define PG8_MMA(ai, bj, At, Bt) do { __builtin_amdgcn_s_setprio(1); _Pragma("unroll") for (int m = 0; m < 4; ++m) _Pragma("unroll") for (int n = 0; n < 2; ++n) _Pragma("unroll") for (int k = 0; k < 2; ++k) \
;         acc[ai][bj][m][n] = __builtin_amdgcn_mfma_f32_16x16x32_bf16(Bt[n][k], At[m][k], acc[ai][bj][m][n], 0, 0, 0); __builtin_amdgcn_s_setprio(0); } while (0)
; #define PG8_WAIT_V(n) asm volatile("s_waitcnt vmcnt(" #n ")" ::: "memory")
; #define PG8_WAIT_L(n) asm volatile("s_waitcnt lgkmcnt(" #n ")" ::: "memory")
; #define PG8_BAR __builtin_amdgcn_s_barrier()
; #define PG8_SCHED __builtin_amdgcn_sched_barrier(0)
; template <class Epi, class Sched, bool ALIGN_EPI = false, bool SP2 = false>
; __device__ __forceinline__ void gemm_phase(PG8_LAS unsigned char* lds, const Gemm g, const Sched& S, const Epi& E) {
;     ...
;         for (int t = 0; t < nt; t += 2) {
;             const bool last = (t == nt - 2);
;             const char* a1 = cA + (size_t)(t + 1) * kstep;
;             const char* a2 = last ? nA : cA + (size_t)(t + 2) * kstep; const char* b2 = last ? nB : cB + (size_t)(t + 2) * kstep;
;             const char* a3 = a2 + kstep; const char* b3 = b2 + kstep;
;             if (last && has_next) S.a_ready(nxt);
;             if constexpr (SP2) {
;             PG8_LDB(B0, 0, 0); PG8_LDB(B1, 0, 1); PG8_SCHED; PG8_LDA(At, 0, 0); PG8_STAGE(PG8_SA(1, 1), a1 + hstep, voffA);
;             PG8_WAIT_V(8); PG8_WAIT_L(0); PG8_BAR; PG8_MMA(0, 0, At, B0); PG8_MMA(0, 1, At, B1); PG8_BAR; PG8_SCHED;
;             PG8_LDA(At, 0, 1); PG8_STAGE(PG8_SB(0, 0), b2, voffB); PG8_STAGE(PG8_SB(0, 1), b2 + hstep, voffB); PG8_STAGE(PG8_SA(0, 0), a2, voffA);
.LBB0_851:
	s_add_i32 s63, s24, 2
	s_add_u32 s60, s22, 0x80
	s_addc_u32 s25, s23, 0
	s_add_i32 s66, 0, 0x10000
	s_cmp_eq_u32 s39, s24
	s_cselect_b32 s25, s7, s25
	s_cselect_b32 s24, s6, s60
	s_cselect_b32 s61, s21, s62
	s_cselect_b32 s60, s20, s58
	s_add_i32 s67, 0, 0x14000
	v_add_u32_e32 v154, s66, v139
	v_add_u32_e32 v170, s67, v139
	ds_read_b128 v[142:145], v154
	ds_read_b128 v[146:149], v154 offset:1024
	ds_read_b128 v[150:153], v154 offset:2048
	ds_read_b128 v[154:157], v154 offset:3072
	ds_read_b128 v[158:161], v170
	ds_read_b128 v[162:165], v170 offset:1024
	ds_read_b128 v[166:169], v170 offset:2048
	ds_read_b128 v[170:173], v170 offset:3072
	v_lshl_add_u64 v[186:187], s[22:23], 0, v[134:135]
	s_add_i32 m0, s30, 0xc000
	ds_read_b128 v[174:177], v141
	ds_read_b128 v[178:181], v141 offset:1024
	ds_read_b128 v[182:185], v141 offset:2048
	ds_read_b128 v[198:201], v141 offset:3072
	ds_read_b128 v[202:205], v141 offset:4096
	ds_read_b128 v[206:209], v141 offset:5120
	ds_read_b128 v[210:213], v141 offset:6144
	ds_read_b128 v[214:217], v141 offset:7168
	global_load_lds_dwordx4 v[186:187], off
	v_lshl_add_u64 v[186:187], s[22:23], 0, v[136:137]
	s_add_i32 m0, s30, 0xe000
	s_nop 0
	global_load_lds_dwordx4 v[186:187], off
	s_nop 0
	s_nop 0
	s_nop 0
	s_nop 0
	s_waitcnt vmcnt(8)
	s_waitcnt lgkmcnt(0)
	s_barrier
	s_setprio 1
	v_mfma_f32_16x16x32_bf16 v[120:123], v[142:145], v[174:177], v[120:123]
	v_mfma_f32_16x16x32_bf16 v[124:127], v[150:153], v[174:177], v[124:127]
	v_mfma_f32_16x16x32_bf16 v[108:111], v[142:145], v[182:185], v[108:111]
	v_mfma_f32_16x16x32_bf16 v[104:107], v[150:153], v[182:185], v[104:107]
	v_mfma_f32_16x16x32_bf16 v[92:95], v[142:145], v[202:205], v[92:95]
	v_mfma_f32_16x16x32_bf16 v[88:91], v[150:153], v[202:205], v[88:91]
	v_mfma_f32_16x16x32_bf16 v[76:79], v[142:145], v[210:213], v[76:79]
	v_mfma_f32_16x16x32_bf16 v[72:75], v[150:153], v[210:213], v[72:75]
	v_mfma_f32_16x16x32_bf16 v[120:123], v[146:149], v[178:181], v[120:123]
	v_mfma_f32_16x16x32_bf16 v[124:127], v[154:157], v[178:181], v[124:127]
	v_mfma_f32_16x16x32_bf16 v[108:111], v[146:149], v[198:201], v[108:111]
	v_mfma_f32_16x16x32_bf16 v[104:107], v[154:157], v[198:201], v[104:107]
	v_mfma_f32_16x16x32_bf16 v[92:95], v[146:149], v[206:209], v[92:95]
	v_mfma_f32_16x16x32_bf16 v[88:91], v[154:157], v[206:209], v[88:91]
	v_mfma_f32_16x16x32_bf16 v[76:79], v[146:149], v[214:217], v[76:79]
	v_mfma_f32_16x16x32_bf16 v[72:75], v[154:157], v[214:217], v[72:75]
	v_mfma_f32_16x16x32_bf16 v[116:119], v[158:161], v[174:177], v[116:119]
	v_mfma_f32_16x16x32_bf16 v[112:115], v[166:169], v[174:177], v[112:115]
	v_mfma_f32_16x16x32_bf16 v[100:103], v[158:161], v[182:185], v[100:103]
	v_mfma_f32_16x16x32_bf16 v[96:99], v[166:169], v[182:185], v[96:99]
	v_mfma_f32_16x16x32_bf16 v[84:87], v[158:161], v[202:205], v[84:87]
	v_mfma_f32_16x16x32_bf16 v[80:83], v[166:169], v[202:205], v[80:83]
	v_mfma_f32_16x16x32_bf16 v[68:71], v[158:161], v[210:213], v[68:71]
	v_mfma_f32_16x16x32_bf16 v[64:67], v[166:169], v[210:213], v[64:67]
	v_mfma_f32_16x16x32_bf16 v[116:119], v[162:165], v[178:181], v[116:119]
	v_mfma_f32_16x16x32_bf16 v[112:115], v[170:173], v[178:181], v[112:115]
	v_mfma_f32_16x16x32_bf16 v[100:103], v[162:165], v[198:201], v[100:103]
	v_mfma_f32_16x16x32_bf16 v[96:99], v[170:173], v[198:201], v[96:99]
	v_mfma_f32_16x16x32_bf16 v[84:87], v[162:165], v[206:209], v[84:87]
	v_mfma_f32_16x16x32_bf16 v[80:83], v[170:173], v[206:209], v[80:83]
	v_mfma_f32_16x16x32_bf16 v[68:71], v[162:165], v[214:217], v[68:71]
	v_mfma_f32_16x16x32_bf16 v[64:67], v[170:173], v[214:217], v[64:67]
	s_setprio 0
	s_barrier
	s_add_i32 s66, s66, s29
	v_lshl_add_u64 v[186:187], s[60:61], 0, v[188:189]
	s_mov_b32 m0, s66
	ds_read_b128 v[174:177], v141 offset:16384
	ds_read_b128 v[178:181], v141 offset:17408
	ds_read_b128 v[182:185], v141 offset:18432
	ds_read_b128 v[198:201], v141 offset:19456
	ds_read_b128 v[202:205], v141 offset:20480
	ds_read_b128 v[206:209], v141 offset:21504
	ds_read_b128 v[210:213], v141 offset:22528
	ds_read_b128 v[214:217], v141 offset:23552
	global_load_lds_dwordx4 v[186:187], off
	s_add_i32 m0, s66, 0x2000
	v_lshl_add_u64 v[218:219], s[60:61], 0, v[128:129]
	s_add_u32 s60, s60, s0
	s_addc_u32 s61, s61, s1
	s_add_i32 s66, s67, s29
	global_load_lds_dwordx4 v[218:219], off
	v_lshl_add_u64 v[220:221], s[60:61], 0, v[188:189]
	s_mov_b32 m0, s66
	v_lshl_add_u64 v[222:223], s[60:61], 0, v[128:129]
	global_load_lds_dwordx4 v[220:221], off
	s_add_i32 m0, s66, 0x2000
	v_lshl_add_u64 v[224:225], s[24:25], 0, v[132:133]
	global_load_lds_dwordx4 v[222:223], off
	s_mov_b32 m0, s30
	v_lshl_add_u64 v[226:227], s[24:25], 0, v[130:131]
	global_load_lds_dwordx4 v[224:225], off
	s_mov_b32 m0, s31
	s_nop 0
	global_load_lds_dwordx4 v[226:227], off
	s_nop 0
	s_nop 0
	s_nop 0
	s_nop 0
	s_nop 0
	s_waitcnt vmcnt(8)
	s_waitcnt lgkmcnt(0)
	s_barrier
; #define PG8_STAGE(bufoff, gbase, voff) do { _Pragma("unroll") for (int _i = 0; _i < 2; ++_i) \
;         __builtin_amdgcn_global_load_lds((const unsigned*)((const char*)(gbase) + (voff)[_i]), (PG8_LAS unsigned*)(lds + (bufoff) + ldsw + _i * 8192), 16, 0, 0); } while (0)
; #define PG8_LDA(dst, b, h) do { _Pragma("unroll") for (int m = 0; m < 4; ++m) _Pragma("unroll") for (int k = 0; k < 2; ++k) dst[m][k] = *(const PG8_LAS bf16x8*)(lds + PG8_SA(b, h) + aoff + m * 2048 + k * 1024); } while (0)
; #define PG8_LDB(dst, b, h) do { _Pragma("unroll") for (int n = 0; n < 2; ++n) _Pragma("unroll") for (int k = 0; k < 2; ++k) dst[n][k] = *(const PG8_LAS bf16x8*)(lds + PG8_SB(b, h) + boff + n * 2048 + k * 1024); } while (0)
; #define PG8_MMA(ai, bj, At, Bt) do { __builtin_amdgcn_s_setprio(1); _Pragma("unroll") for (int m = 0; m < 4; ++m) _Pragma("unroll") for (int n = 0; n < 2; ++n) _Pragma("unroll") for (int k = 0; k < 2; ++k) \
;         acc[ai][bj][m][n] = __builtin_amdgcn_mfma_f32_16x16x32_bf16(Bt[n][k], At[m][k], acc[ai][bj][m][n], 0, 0, 0); __builtin_amdgcn_s_setprio(0); } while (0)
; #define PG8_WAIT_V(n) asm volatile("s_waitcnt vmcnt(" #n ")" ::: "memory")
; #define PG8_WAIT_L(n) asm volatile("s_waitcnt lgkmcnt(" #n ")" ::: "memory")
; #define PG8_BAR __builtin_amdgcn_s_barrier()
; #define PG8_SCHED __builtin_amdgcn_sched_barrier(0)
; template <class Epi, class Sched, bool ALIGN_EPI = false, bool SP2 = false>
; __device__ __forceinline__ void gemm_phase(PG8_LAS unsigned char* lds, const Gemm g, const Sched& S, const Epi& E) {
;     ...
;             PG8_WAIT_V(8); PG8_WAIT_L(0); PG8_BAR; PG8_MMA(1, 0, At, B0); PG8_MMA(1, 1, At, B1); PG8_BAR; PG8_SCHED;
;             PG8_LDB(B0, 1, 0); PG8_LDB(B1, 1, 1); PG8_SCHED; PG8_LDA(At, 1, 0); PG8_STAGE(PG8_SA(0, 1), a2 + hstep, voffA);
;             PG8_WAIT_V(8); PG8_WAIT_L(0); PG8_BAR; PG8_MMA(0, 0, At, B0); PG8_MMA(0, 1, At, B1); PG8_BAR; PG8_SCHED;
	s_setprio 1
	v_mfma_f32_16x16x32_bf16 v[60:63], v[142:145], v[174:177], v[60:63]
	v_mfma_f32_16x16x32_bf16 v[56:59], v[150:153], v[174:177], v[56:59]
	v_mfma_f32_16x16x32_bf16 v[44:47], v[142:145], v[182:185], v[44:47]
	v_mfma_f32_16x16x32_bf16 v[40:43], v[150:153], v[182:185], v[40:43]
	v_mfma_f32_16x16x32_bf16 v[28:31], v[142:145], v[202:205], v[28:31]
	v_mfma_f32_16x16x32_bf16 v[24:27], v[150:153], v[202:205], v[24:27]
	v_mfma_f32_16x16x32_bf16 v[12:15], v[142:145], v[210:213], v[12:15]
	v_mfma_f32_16x16x32_bf16 v[8:11], v[150:153], v[210:213], v[8:11]
	v_mfma_f32_16x16x32_bf16 v[60:63], v[146:149], v[178:181], v[60:63]
	v_mfma_f32_16x16x32_bf16 v[56:59], v[154:157], v[178:181], v[56:59]
	v_mfma_f32_16x16x32_bf16 v[44:47], v[146:149], v[198:201], v[44:47]
	v_mfma_f32_16x16x32_bf16 v[40:43], v[154:157], v[198:201], v[40:43]
	v_mfma_f32_16x16x32_bf16 v[28:31], v[146:149], v[206:209], v[28:31]
	v_mfma_f32_16x16x32_bf16 v[24:27], v[154:157], v[206:209], v[24:27]
	v_mfma_f32_16x16x32_bf16 v[12:15], v[146:149], v[214:217], v[12:15]
	v_mfma_f32_16x16x32_bf16 v[8:11], v[154:157], v[214:217], v[8:11]
	v_mfma_f32_16x16x32_bf16 v[52:55], v[158:161], v[174:177], v[52:55]
	v_mfma_f32_16x16x32_bf16 v[48:51], v[166:169], v[174:177], v[48:51]
	v_mfma_f32_16x16x32_bf16 v[36:39], v[158:161], v[182:185], v[36:39]
	v_mfma_f32_16x16x32_bf16 v[32:35], v[166:169], v[182:185], v[32:35]
	v_mfma_f32_16x16x32_bf16 v[20:23], v[158:161], v[202:205], v[20:23]
	v_mfma_f32_16x16x32_bf16 v[16:19], v[166:169], v[202:205], v[16:19]
	v_mfma_f32_16x16x32_bf16 v[4:7], v[158:161], v[210:213], v[4:7]
	v_mfma_f32_16x16x32_bf16 v[0:3], v[166:169], v[210:213], v[0:3]
	v_mfma_f32_16x16x32_bf16 v[52:55], v[162:165], v[178:181], v[52:55]
	v_mfma_f32_16x16x32_bf16 v[48:51], v[170:173], v[178:181], v[48:51]
	v_mfma_f32_16x16x32_bf16 v[36:39], v[162:165], v[198:201], v[36:39]
	v_mfma_f32_16x16x32_bf16 v[32:35], v[170:173], v[198:201], v[32:35]
	v_mfma_f32_16x16x32_bf16 v[20:23], v[162:165], v[206:209], v[20:23]
	v_mfma_f32_16x16x32_bf16 v[16:19], v[170:173], v[206:209], v[16:19]
	v_mfma_f32_16x16x32_bf16 v[4:7], v[162:165], v[214:217], v[4:7]
	v_mfma_f32_16x16x32_bf16 v[0:3], v[170:173], v[214:217], v[0:3]
	s_setprio 0
	s_barrier
	s_add_i32 s60, 0, 0x18000
	s_add_i32 s61, 0, 0x1c000
	v_add_u32_e32 v154, s60, v139
	v_add_u32_e32 v170, s61, v139
	ds_read_b128 v[142:145], v154
	ds_read_b128 v[146:149], v154 offset:1024
	ds_read_b128 v[150:153], v154 offset:2048
	ds_read_b128 v[154:157], v154 offset:3072
	ds_read_b128 v[158:161], v170
	ds_read_b128 v[162:165], v170 offset:1024
	ds_read_b128 v[166:169], v170 offset:2048
	ds_read_b128 v[170:173], v170 offset:3072
	s_add_u32 s24, s24, s0
	s_addc_u32 s25, s25, s1
	s_mov_b32 m0, s34
	v_lshl_add_u64 v[228:229], s[24:25], 0, v[132:133]
	ds_read_b128 v[174:177], v141 offset:32768
	ds_read_b128 v[178:181], v141 offset:33792
	ds_read_b128 v[182:185], v141 offset:34816
	ds_read_b128 v[198:201], v141 offset:35840
	ds_read_b128 v[202:205], v141 offset:36864
	ds_read_b128 v[206:209], v141 offset:37888
	ds_read_b128 v[210:213], v141 offset:38912
	ds_read_b128 v[214:217], v141 offset:39936
	global_load_lds_dwordx4 v[228:229], off
	v_lshl_add_u64 v[228:229], s[24:25], 0, v[130:131]
	s_mov_b32 m0, s35
	s_nop 0
	global_load_lds_dwordx4 v[228:229], off
	s_nop 0
	s_nop 0
	s_nop 0
	s_nop 0
	s_nop 0
	s_nop 0
	s_nop 0
	s_waitcnt vmcnt(8)
	s_waitcnt lgkmcnt(0)
	s_barrier
	s_setprio 1
	v_mfma_f32_16x16x32_bf16 v[120:123], v[142:145], v[174:177], v[120:123]
	v_mfma_f32_16x16x32_bf16 v[124:127], v[150:153], v[174:177], v[124:127]
	v_mfma_f32_16x16x32_bf16 v[108:111], v[142:145], v[182:185], v[108:111]
	v_mfma_f32_16x16x32_bf16 v[104:107], v[150:153], v[182:185], v[104:107]
	v_mfma_f32_16x16x32_bf16 v[92:95], v[142:145], v[202:205], v[92:95]
	v_mfma_f32_16x16x32_bf16 v[88:91], v[150:153], v[202:205], v[88:91]
	v_mfma_f32_16x16x32_bf16 v[76:79], v[142:145], v[210:213], v[76:79]
	v_mfma_f32_16x16x32_bf16 v[72:75], v[150:153], v[210:213], v[72:75]
	v_mfma_f32_16x16x32_bf16 v[120:123], v[146:149], v[178:181], v[120:123]
	v_mfma_f32_16x16x32_bf16 v[124:127], v[154:157], v[178:181], v[124:127]
	v_mfma_f32_16x16x32_bf16 v[108:111], v[146:149], v[198:201], v[108:111]
	v_mfma_f32_16x16x32_bf16 v[104:107], v[154:157], v[198:201], v[104:107]
	v_mfma_f32_16x16x32_bf16 v[92:95], v[146:149], v[206:209], v[92:95]
	v_mfma_f32_16x16x32_bf16 v[88:91], v[154:157], v[206:209], v[88:91]
	v_mfma_f32_16x16x32_bf16 v[76:79], v[146:149], v[214:217], v[76:79]
	v_mfma_f32_16x16x32_bf16 v[72:75], v[154:157], v[214:217], v[72:75]
	v_mfma_f32_16x16x32_bf16 v[116:119], v[158:161], v[174:177], v[116:119]
	v_mfma_f32_16x16x32_bf16 v[112:115], v[166:169], v[174:177], v[112:115]
	v_mfma_f32_16x16x32_bf16 v[100:103], v[158:161], v[182:185], v[100:103]
	v_mfma_f32_16x16x32_bf16 v[96:99], v[166:169], v[182:185], v[96:99]
	v_mfma_f32_16x16x32_bf16 v[84:87], v[158:161], v[202:205], v[84:87]
	v_mfma_f32_16x16x32_bf16 v[80:83], v[166:169], v[202:205], v[80:83]
	v_mfma_f32_16x16x32_bf16 v[68:71], v[158:161], v[210:213], v[68:71]
	v_mfma_f32_16x16x32_bf16 v[64:67], v[166:169], v[210:213], v[64:67]
	v_mfma_f32_16x16x32_bf16 v[116:119], v[162:165], v[178:181], v[116:119]
	v_mfma_f32_16x16x32_bf16 v[112:115], v[170:173], v[178:181], v[112:115]
	v_mfma_f32_16x16x32_bf16 v[100:103], v[162:165], v[198:201], v[100:103]
	v_mfma_f32_16x16x32_bf16 v[96:99], v[170:173], v[198:201], v[96:99]
	v_mfma_f32_16x16x32_bf16 v[84:87], v[162:165], v[206:209], v[84:87]
	v_mfma_f32_16x16x32_bf16 v[80:83], v[170:173], v[206:209], v[80:83]
	v_mfma_f32_16x16x32_bf16 v[68:71], v[162:165], v[214:217], v[68:71]
	v_mfma_f32_16x16x32_bf16 v[64:67], v[170:173], v[214:217], v[64:67]
	s_setprio 0
	s_barrier
; #define PG8_STAGE(bufoff, gbase, voff) do { _Pragma("unroll") for (int _i = 0; _i < 2; ++_i) \
;         __builtin_amdgcn_global_load_lds((const unsigned*)((const char*)(gbase) + (voff)[_i]), (PG8_LAS unsigned*)(lds + (bufoff) + ldsw + _i * 8192), 16, 0, 0); } while (0)
; #define PG8_LDA(dst, b, h) do { _Pragma("unroll") for (int m = 0; m < 4; ++m) _Pragma("unroll") for (int k = 0; k < 2; ++k) dst[m][k] = *(const PG8_LAS bf16x8*)(lds + PG8_SA(b, h) + aoff + m * 2048 + k * 1024); } while (0)
; #define PG8_MMA(ai, bj, At, Bt) do { __builtin_amdgcn_s_setprio(1); _Pragma("unroll") for (int m = 0; m < 4; ++m) _Pragma("unroll") for (int n = 0; n < 2; ++n) _Pragma("unroll") for (int k = 0; k < 2; ++k) \
;         acc[ai][bj][m][n] = __builtin_amdgcn_mfma_f32_16x16x32_bf16(Bt[n][k], At[m][k], acc[ai][bj][m][n], 0, 0, 0); __builtin_amdgcn_s_setprio(0); } while (0)
; #define PG8_WAIT_V(n) asm volatile("s_waitcnt vmcnt(" #n ")" ::: "memory")
; #define PG8_WAIT_L(n) asm volatile("s_waitcnt lgkmcnt(" #n ")" ::: "memory")
; #define PG8_BAR __builtin_amdgcn_s_barrier()
; #define PG8_SCHED __builtin_amdgcn_sched_barrier(0)
; template <class Epi, class Sched, bool ALIGN_EPI = false, bool SP2 = false>
; __device__ __forceinline__ void gemm_phase(PG8_LAS unsigned char* lds, const Gemm g, const Sched& S, const Epi& E) {
;     ...
;             PG8_LDA(At, 1, 1); PG8_STAGE(PG8_SB(1, 0), b3, voffB); PG8_STAGE(PG8_SB(1, 1), b3 + hstep, voffB); PG8_STAGE(PG8_SA(1, 0), a3, voffA);
;             PG8_WAIT_V(8); PG8_WAIT_L(0); PG8_BAR; PG8_MMA(1, 0, At, B0); PG8_MMA(1, 1, At, B1); PG8_BAR; PG8_SCHED;
	s_add_i32 s24, s60, s29
	v_lshl_add_u64 v[186:187], v[186:187], 0, s[78:79]
	s_mov_b32 m0, s24
	ds_read_b128 v[174:177], v141 offset:49152
	ds_read_b128 v[178:181], v141 offset:50176
	ds_read_b128 v[182:185], v141 offset:51200
	ds_read_b128 v[198:201], v141 offset:52224
	ds_read_b128 v[202:205], v141 offset:53248
	ds_read_b128 v[206:209], v141 offset:54272
	ds_read_b128 v[210:213], v141 offset:55296
	ds_read_b128 v[214:217], v141 offset:56320
	global_load_lds_dwordx4 v[186:187], off
	v_lshl_add_u64 v[186:187], v[218:219], 0, s[78:79]
	s_add_i32 m0, s24, 0x2000
	s_add_i32 s24, s61, s29
	global_load_lds_dwordx4 v[186:187], off
	v_lshl_add_u64 v[186:187], v[220:221], 0, s[78:79]
	s_mov_b32 m0, s24
	s_nop 0
	global_load_lds_dwordx4 v[186:187], off
	v_lshl_add_u64 v[186:187], v[222:223], 0, s[78:79]
	s_add_i32 m0, s24, 0x2000
	s_nop 0
	global_load_lds_dwordx4 v[186:187], off
	v_lshl_add_u64 v[186:187], v[224:225], 0, s[78:79]
	s_mov_b32 m0, s37
	s_nop 0
	global_load_lds_dwordx4 v[186:187], off
	v_lshl_add_u64 v[186:187], v[226:227], 0, s[78:79]
	s_mov_b32 m0, s38
	s_nop 0
	global_load_lds_dwordx4 v[186:187], off
	s_nop 0
	s_nop 0
	s_nop 0
	s_nop 0
	s_waitcnt vmcnt(8)
	s_waitcnt lgkmcnt(0)
	s_barrier
	s_setprio 1
	v_mfma_f32_16x16x32_bf16 v[60:63], v[142:145], v[174:177], v[60:63]
	v_mfma_f32_16x16x32_bf16 v[56:59], v[150:153], v[174:177], v[56:59]
	v_mfma_f32_16x16x32_bf16 v[44:47], v[142:145], v[182:185], v[44:47]
	v_mfma_f32_16x16x32_bf16 v[40:43], v[150:153], v[182:185], v[40:43]
	v_mfma_f32_16x16x32_bf16 v[28:31], v[142:145], v[202:205], v[28:31]
	v_mfma_f32_16x16x32_bf16 v[24:27], v[150:153], v[202:205], v[24:27]
	v_mfma_f32_16x16x32_bf16 v[12:15], v[142:145], v[210:213], v[12:15]
	v_mfma_f32_16x16x32_bf16 v[8:11], v[150:153], v[210:213], v[8:11]
	v_mfma_f32_16x16x32_bf16 v[60:63], v[146:149], v[178:181], v[60:63]
	v_mfma_f32_16x16x32_bf16 v[56:59], v[154:157], v[178:181], v[56:59]
	v_mfma_f32_16x16x32_bf16 v[44:47], v[146:149], v[198:201], v[44:47]
	v_mfma_f32_16x16x32_bf16 v[40:43], v[154:157], v[198:201], v[40:43]
	v_mfma_f32_16x16x32_bf16 v[28:31], v[146:149], v[206:209], v[28:31]
	v_mfma_f32_16x16x32_bf16 v[24:27], v[154:157], v[206:209], v[24:27]
	v_mfma_f32_16x16x32_bf16 v[12:15], v[146:149], v[214:217], v[12:15]
	v_mfma_f32_16x16x32_bf16 v[8:11], v[154:157], v[214:217], v[8:11]
	v_mfma_f32_16x16x32_bf16 v[52:55], v[158:161], v[174:177], v[52:55]
	v_mfma_f32_16x16x32_bf16 v[48:51], v[166:169], v[174:177], v[48:51]
	v_mfma_f32_16x16x32_bf16 v[36:39], v[158:161], v[182:185], v[36:39]
	v_mfma_f32_16x16x32_bf16 v[32:35], v[166:169], v[182:185], v[32:35]
	v_mfma_f32_16x16x32_bf16 v[20:23], v[158:161], v[202:205], v[20:23]
	v_mfma_f32_16x16x32_bf16 v[16:19], v[166:169], v[202:205], v[16:19]
	v_mfma_f32_16x16x32_bf16 v[4:7], v[158:161], v[210:213], v[4:7]
	v_mfma_f32_16x16x32_bf16 v[0:3], v[166:169], v[210:213], v[0:3]
	v_mfma_f32_16x16x32_bf16 v[52:55], v[162:165], v[178:181], v[52:55]
	v_mfma_f32_16x16x32_bf16 v[48:51], v[170:173], v[178:181], v[48:51]
	v_mfma_f32_16x16x32_bf16 v[36:39], v[162:165], v[198:201], v[36:39]
	v_mfma_f32_16x16x32_bf16 v[32:35], v[170:173], v[198:201], v[32:35]
	v_mfma_f32_16x16x32_bf16 v[20:23], v[162:165], v[206:209], v[20:23]
	v_mfma_f32_16x16x32_bf16 v[16:19], v[170:173], v[206:209], v[16:19]
	v_mfma_f32_16x16x32_bf16 v[4:7], v[162:165], v[214:217], v[4:7]
	v_mfma_f32_16x16x32_bf16 v[0:3], v[170:173], v[214:217], v[0:3]
	s_setprio 0
	s_barrier
	s_add_u32 s22, s22, 0x100
	s_addc_u32 s23, s23, 0
	s_add_u32 s58, s58, 0x100
	s_addc_u32 s62, s62, 0
	s_cmp_ge_i32 s63, s36
	s_mov_b32 s24, s63
	s_cbranch_scc0 .LBB0_851
	s_mov_b32 s67, 0x20000
	s_mov_b32 s66, 0x30000

; #define PG8_STAGE(bufoff, gbase, voff) do { _Pragma("unroll") for (int _i = 0; _i < 2; ++_i) \
;         __builtin_amdgcn_global_load_lds((const unsigned*)((const char*)(gbase) + (voff)[_i]), (PG8_LAS unsigned*)(lds + (bufoff) + ldsw + _i * 8192), 16, 0, 0); } while (0)
; #define PG8_LDA(dst, b, h) do { _Pragma("unroll") for (int m = 0; m < 4; ++m) _Pragma("unroll") for (int k = 0; k < 2; ++k) dst[m][k] = *(const PG8_LAS bf16x8*)(lds + PG8_SA(b, h) + aoff + m * 2048 + k * 1024); } while (0)
; #define PG8_LDB(dst, b, h) do { _Pragma("unroll") for (int n = 0; n < 2; ++n) _Pragma("unroll") for (int k = 0; k < 2; ++k) dst[n][k] = *(const PG8_LAS bf16x8*)(lds + PG8_SB(b, h) + boff + n * 2048 + k * 1024); } while (0)
; #define PG8_MMA(ai, bj, At, Bt) do { __builtin_amdgcn_s_setprio(1); _Pragma("unroll") for (int m = 0; m < 4; ++m) _Pragma("unroll") for (int n = 0; n < 2; ++n) _Pragma("unroll") for (int k = 0; k < 2; ++k) \
;         acc[ai][bj][m][n] = __builtin_amdgcn_mfma_f32_16x16x32_bf16(Bt[n][k], At[m][k], acc[ai][bj][m][n], 0, 0, 0); __builtin_amdgcn_s_setprio(0); } while (0)
; #define PG8_WAIT_V(n) asm volatile("s_waitcnt vmcnt(" #n ")" ::: "memory")
; #define PG8_WAIT_L(n) asm volatile("s_waitcnt lgkmcnt(" #n ")" ::: "memory")
; #define PG8_BAR __builtin_amdgcn_s_barrier()
; #define PG8_SCHED __builtin_amdgcn_sched_barrier(0)
; template <class Epi, class Sched, bool ALIGN_EPI = false, bool SP2 = false>
; __device__ __forceinline__ void gemm_phase(PG8_LAS unsigned char* lds, const Gemm g, const Sched& S, const Epi& E) {
;     ...
;             const bool last = (t == nt - 2);
;             const char* a1 = cA + (size_t)(t + 1) * kstep;
;             const char* a2 = last ? nA : cA + (size_t)(t + 2) * kstep; const char* b2 = last ? nB : cB + (size_t)(t + 2) * kstep;
;             const char* a3 = a2 + kstep; const char* b3 = b2 + kstep;
;             if (last && has_next) S.a_ready(nxt);
;             if constexpr (SP2) {
;             PG8_LDB(B0, 0, 0); PG8_LDB(B1, 0, 1); PG8_SCHED; PG8_LDA(At, 0, 0); PG8_STAGE(PG8_SA(1, 1), a1 + hstep, voffA);
;             PG8_WAIT_V(8); PG8_WAIT_L(0); PG8_BAR; PG8_MMA(0, 0, At, B0); PG8_MMA(0, 1, At, B1); PG8_BAR; PG8_SCHED;
;             PG8_LDA(At, 0, 1); PG8_STAGE(PG8_SB(0, 0), b2, voffB); PG8_STAGE(PG8_SB(0, 1), b2 + hstep, voffB); PG8_STAGE(PG8_SA(0, 0), a2, voffA);
.LBB0_872:
	s_add_u32 s36, s34, 0xfff80080
	s_addc_u32 s37, s35, -1
	s_add_i32 s60, 0, 0x10000
	s_cmp_eq_u32 s72, 28
	s_cselect_b32 s39, s23, s37
	s_cselect_b32 s38, s29, s36
	s_cselect_b32 s37, s21, s68
	s_cselect_b32 s36, s66, s67
	s_add_i32 s73, 0, 0x14000
	v_add_u32_e32 v132, s60, v225
	v_add_u32_e32 v156, s73, v225
	ds_read_b128 v[112:115], v132
	ds_read_b128 v[116:119], v132 offset:1024
	ds_read_b128 v[120:123], v132 offset:2048
	ds_read_b128 v[132:135], v132 offset:3072
	ds_read_b128 v[140:143], v156
	ds_read_b128 v[148:151], v156 offset:1024
	ds_read_b128 v[152:155], v156 offset:2048
	ds_read_b128 v[156:159], v156 offset:3072
	v_lshl_add_u64 v[212:213], s[34:35], 0, v[186:187]
	s_add_i32 m0, s2, 0xc000
	ds_read_b128 v[160:163], v227
	ds_read_b128 v[164:167], v227 offset:1024
	ds_read_b128 v[168:171], v227 offset:2048
	ds_read_b128 v[172:175], v227 offset:3072
	ds_read_b128 v[176:179], v227 offset:4096
	ds_read_b128 v[200:203], v227 offset:5120
	ds_read_b128 v[204:207], v227 offset:6144
	ds_read_b128 v[208:211], v227 offset:7168
	global_load_lds_dwordx4 v[212:213], off
	v_lshl_add_u64 v[212:213], s[34:35], 0, v[198:199]
	s_add_i32 m0, s2, 0xe000
	s_nop 0
	global_load_lds_dwordx4 v[212:213], off
	s_nop 0
	s_waitcnt vmcnt(8)
	s_waitcnt lgkmcnt(0)
	s_barrier
	s_setprio 1
	v_mfma_f32_16x16x32_bf16 v[144:147], v[112:115], v[160:163], v[144:147]
	v_mfma_f32_16x16x32_bf16 v[136:139], v[120:123], v[160:163], v[136:139]
	v_mfma_f32_16x16x32_bf16 v[108:111], v[112:115], v[168:171], v[108:111]
	v_mfma_f32_16x16x32_bf16 v[104:107], v[120:123], v[168:171], v[104:107]
	v_mfma_f32_16x16x32_bf16 v[92:95], v[112:115], v[176:179], v[92:95]
	v_mfma_f32_16x16x32_bf16 v[88:91], v[120:123], v[176:179], v[88:91]
	v_mfma_f32_16x16x32_bf16 v[76:79], v[112:115], v[204:207], v[76:79]
	v_mfma_f32_16x16x32_bf16 v[72:75], v[120:123], v[204:207], v[72:75]
	v_mfma_f32_16x16x32_bf16 v[144:147], v[116:119], v[164:167], v[144:147]
	v_mfma_f32_16x16x32_bf16 v[136:139], v[132:135], v[164:167], v[136:139]
	v_mfma_f32_16x16x32_bf16 v[108:111], v[116:119], v[172:175], v[108:111]
	v_mfma_f32_16x16x32_bf16 v[104:107], v[132:135], v[172:175], v[104:107]
	v_mfma_f32_16x16x32_bf16 v[92:95], v[116:119], v[200:203], v[92:95]
	v_mfma_f32_16x16x32_bf16 v[88:91], v[132:135], v[200:203], v[88:91]
	v_mfma_f32_16x16x32_bf16 v[76:79], v[116:119], v[208:211], v[76:79]
	v_mfma_f32_16x16x32_bf16 v[72:75], v[132:135], v[208:211], v[72:75]
	v_mfma_f32_16x16x32_bf16 v[128:131], v[140:143], v[160:163], v[128:131]
	v_mfma_f32_16x16x32_bf16 v[124:127], v[152:155], v[160:163], v[124:127]
	v_mfma_f32_16x16x32_bf16 v[100:103], v[140:143], v[168:171], v[100:103]
	v_mfma_f32_16x16x32_bf16 v[96:99], v[152:155], v[168:171], v[96:99]
	v_mfma_f32_16x16x32_bf16 v[84:87], v[140:143], v[176:179], v[84:87]
	v_mfma_f32_16x16x32_bf16 v[80:83], v[152:155], v[176:179], v[80:83]
	v_mfma_f32_16x16x32_bf16 v[68:71], v[140:143], v[204:207], v[68:71]
	v_mfma_f32_16x16x32_bf16 v[64:67], v[152:155], v[204:207], v[64:67]
	v_mfma_f32_16x16x32_bf16 v[128:131], v[148:151], v[164:167], v[128:131]
	v_mfma_f32_16x16x32_bf16 v[124:127], v[156:159], v[164:167], v[124:127]
	v_mfma_f32_16x16x32_bf16 v[100:103], v[148:151], v[172:175], v[100:103]
	v_mfma_f32_16x16x32_bf16 v[96:99], v[156:159], v[172:175], v[96:99]
	v_mfma_f32_16x16x32_bf16 v[84:87], v[148:151], v[200:203], v[84:87]
	v_mfma_f32_16x16x32_bf16 v[80:83], v[156:159], v[200:203], v[80:83]
	v_mfma_f32_16x16x32_bf16 v[68:71], v[148:151], v[208:211], v[68:71]
	v_mfma_f32_16x16x32_bf16 v[64:67], v[156:159], v[208:211], v[64:67]
	s_setprio 0
	s_barrier
	s_add_i32 s60, s60, s44
	v_lshl_add_u64 v[212:213], s[36:37], 0, v[188:189]
	s_mov_b32 m0, s60
	ds_read_b128 v[160:163], v227 offset:16384
	ds_read_b128 v[164:167], v227 offset:17408
	ds_read_b128 v[168:171], v227 offset:18432
	ds_read_b128 v[172:175], v227 offset:19456
	ds_read_b128 v[176:179], v227 offset:20480
	ds_read_b128 v[200:203], v227 offset:21504
	ds_read_b128 v[204:207], v227 offset:22528
	ds_read_b128 v[208:211], v227 offset:23552
	global_load_lds_dwordx4 v[212:213], off
	s_add_i32 m0, s60, 0x2000
	s_add_u32 s60, s36, 0x80000
	v_lshl_add_u64 v[214:215], s[36:37], 0, v[180:181]
	s_addc_u32 s61, s37, 0
	s_add_i32 s73, s73, s44
	global_load_lds_dwordx4 v[214:215], off
	v_lshl_add_u64 v[216:217], s[60:61], 0, v[188:189]
	s_mov_b32 m0, s73
	v_lshl_add_u64 v[218:219], s[38:39], 0, v[182:183]
	global_load_lds_dwordx4 v[216:217], off
	v_lshl_add_u64 v[216:217], s[60:61], 0, v[180:181]
	s_add_i32 m0, s73, 0x2000
	s_nop 0
	global_load_lds_dwordx4 v[216:217], off
	v_lshl_add_u64 v[216:217], s[38:39], 0, v[184:185]
	s_mov_b32 m0, s2
	s_nop 0
	global_load_lds_dwordx4 v[216:217], off
	s_mov_b32 m0, s31
	s_nop 0
	global_load_lds_dwordx4 v[218:219], off
	s_nop 0
	s_nop 0
	s_waitcnt vmcnt(8)
	s_waitcnt lgkmcnt(0)
	s_barrier
; #define PG8_STAGE(bufoff, gbase, voff) do { _Pragma("unroll") for (int _i = 0; _i < 2; ++_i) \
;         __builtin_amdgcn_global_load_lds((const unsigned*)((const char*)(gbase) + (voff)[_i]), (PG8_LAS unsigned*)(lds + (bufoff) + ldsw + _i * 8192), 16, 0, 0); } while (0)
; #define PG8_LDA(dst, b, h) do { _Pragma("unroll") for (int m = 0; m < 4; ++m) _Pragma("unroll") for (int k = 0; k < 2; ++k) dst[m][k] = *(const PG8_LAS bf16x8*)(lds + PG8_SA(b, h) + aoff + m * 2048 + k * 1024); } while (0)
; #define PG8_LDB(dst, b, h) do { _Pragma("unroll") for (int n = 0; n < 2; ++n) _Pragma("unroll") for (int k = 0; k < 2; ++k) dst[n][k] = *(const PG8_LAS bf16x8*)(lds + PG8_SB(b, h) + boff + n * 2048 + k * 1024); } while (0)
; #define PG8_MMA(ai, bj, At, Bt) do { __builtin_amdgcn_s_setprio(1); _Pragma("unroll") for (int m = 0; m < 4; ++m) _Pragma("unroll") for (int n = 0; n < 2; ++n) _Pragma("unroll") for (int k = 0; k < 2; ++k) \
;         acc[ai][bj][m][n] = __builtin_amdgcn_mfma_f32_16x16x32_bf16(Bt[n][k], At[m][k], acc[ai][bj][m][n], 0, 0, 0); __builtin_amdgcn_s_setprio(0); } while (0)
; #define PG8_WAIT_V(n) asm volatile("s_waitcnt vmcnt(" #n ")" ::: "memory")
; #define PG8_WAIT_L(n) asm volatile("s_waitcnt lgkmcnt(" #n ")" ::: "memory")
; #define PG8_BAR __builtin_amdgcn_s_barrier()
; #define PG8_SCHED __builtin_amdgcn_sched_barrier(0)
; template <class Epi, class Sched, bool ALIGN_EPI = false, bool SP2 = false>
; __device__ __forceinline__ void gemm_phase(PG8_LAS unsigned char* lds, const Gemm g, const Sched& S, const Epi& E) {
;     ...
;             PG8_WAIT_V(8); PG8_WAIT_L(0); PG8_BAR; PG8_MMA(1, 0, At, B0); PG8_MMA(1, 1, At, B1); PG8_BAR; PG8_SCHED;
;             PG8_LDB(B0, 1, 0); PG8_LDB(B1, 1, 1); PG8_SCHED; PG8_LDA(At, 1, 0); PG8_STAGE(PG8_SA(0, 1), a2 + hstep, voffA);
;             PG8_WAIT_V(8); PG8_WAIT_L(0); PG8_BAR; PG8_MMA(0, 0, At, B0); PG8_MMA(0, 1, At, B1); PG8_BAR; PG8_SCHED;
	s_setprio 1
	v_mfma_f32_16x16x32_bf16 v[60:63], v[112:115], v[160:163], v[60:63]
	v_mfma_f32_16x16x32_bf16 v[56:59], v[120:123], v[160:163], v[56:59]
	v_mfma_f32_16x16x32_bf16 v[44:47], v[112:115], v[168:171], v[44:47]
	v_mfma_f32_16x16x32_bf16 v[40:43], v[120:123], v[168:171], v[40:43]
	v_mfma_f32_16x16x32_bf16 v[28:31], v[112:115], v[176:179], v[28:31]
	v_mfma_f32_16x16x32_bf16 v[24:27], v[120:123], v[176:179], v[24:27]
	v_mfma_f32_16x16x32_bf16 v[12:15], v[112:115], v[204:207], v[12:15]
	v_mfma_f32_16x16x32_bf16 v[8:11], v[120:123], v[204:207], v[8:11]
	v_mfma_f32_16x16x32_bf16 v[60:63], v[116:119], v[164:167], v[60:63]
	v_mfma_f32_16x16x32_bf16 v[56:59], v[132:135], v[164:167], v[56:59]
	v_mfma_f32_16x16x32_bf16 v[44:47], v[116:119], v[172:175], v[44:47]
	v_mfma_f32_16x16x32_bf16 v[40:43], v[132:135], v[172:175], v[40:43]
	v_mfma_f32_16x16x32_bf16 v[28:31], v[116:119], v[200:203], v[28:31]
	v_mfma_f32_16x16x32_bf16 v[24:27], v[132:135], v[200:203], v[24:27]
	v_mfma_f32_16x16x32_bf16 v[12:15], v[116:119], v[208:211], v[12:15]
	v_mfma_f32_16x16x32_bf16 v[8:11], v[132:135], v[208:211], v[8:11]
	v_mfma_f32_16x16x32_bf16 v[52:55], v[140:143], v[160:163], v[52:55]
	v_mfma_f32_16x16x32_bf16 v[48:51], v[152:155], v[160:163], v[48:51]
	v_mfma_f32_16x16x32_bf16 v[36:39], v[140:143], v[168:171], v[36:39]
	v_mfma_f32_16x16x32_bf16 v[32:35], v[152:155], v[168:171], v[32:35]
	v_mfma_f32_16x16x32_bf16 v[20:23], v[140:143], v[176:179], v[20:23]
	v_mfma_f32_16x16x32_bf16 v[16:19], v[152:155], v[176:179], v[16:19]
	v_mfma_f32_16x16x32_bf16 v[4:7], v[140:143], v[204:207], v[4:7]
	v_mfma_f32_16x16x32_bf16 v[0:3], v[152:155], v[204:207], v[0:3]
	v_mfma_f32_16x16x32_bf16 v[52:55], v[148:151], v[164:167], v[52:55]
	v_mfma_f32_16x16x32_bf16 v[48:51], v[156:159], v[164:167], v[48:51]
	v_mfma_f32_16x16x32_bf16 v[36:39], v[148:151], v[172:175], v[36:39]
	v_mfma_f32_16x16x32_bf16 v[32:35], v[156:159], v[172:175], v[32:35]
	v_mfma_f32_16x16x32_bf16 v[20:23], v[148:151], v[200:203], v[20:23]
	v_mfma_f32_16x16x32_bf16 v[16:19], v[156:159], v[200:203], v[16:19]
	v_mfma_f32_16x16x32_bf16 v[4:7], v[148:151], v[208:211], v[4:7]
	v_mfma_f32_16x16x32_bf16 v[0:3], v[156:159], v[208:211], v[0:3]
	s_setprio 0
	s_barrier
	s_add_i32 s60, 0, 0x18000
	s_add_i32 s61, 0, 0x1c000
	v_add_u32_e32 v132, s60, v225
	v_add_u32_e32 v156, s61, v225
	ds_read_b128 v[112:115], v132
	ds_read_b128 v[116:119], v132 offset:1024
	ds_read_b128 v[120:123], v132 offset:2048
	ds_read_b128 v[132:135], v132 offset:3072
	ds_read_b128 v[140:143], v156
	ds_read_b128 v[148:151], v156 offset:1024
	ds_read_b128 v[152:155], v156 offset:2048
	ds_read_b128 v[156:159], v156 offset:3072
	s_add_u32 s38, s38, 0x80000
	s_addc_u32 s39, s39, 0
	s_mov_b32 m0, s45
	v_lshl_add_u64 v[220:221], s[38:39], 0, v[184:185]
	ds_read_b128 v[160:163], v227 offset:32768
	ds_read_b128 v[164:167], v227 offset:33792
	ds_read_b128 v[168:171], v227 offset:34816
	ds_read_b128 v[172:175], v227 offset:35840
	ds_read_b128 v[176:179], v227 offset:36864
	ds_read_b128 v[200:203], v227 offset:37888
	ds_read_b128 v[204:207], v227 offset:38912
	ds_read_b128 v[208:211], v227 offset:39936
	global_load_lds_dwordx4 v[220:221], off
	v_lshl_add_u64 v[220:221], s[38:39], 0, v[182:183]
	s_mov_b32 m0, s52
	s_nop 0
	global_load_lds_dwordx4 v[220:221], off
	s_nop 0
	s_nop 0
	s_nop 0
	s_nop 0
	s_nop 0
	s_nop 0
	s_waitcnt vmcnt(8)
	s_waitcnt lgkmcnt(0)
	s_barrier
	s_setprio 1
	v_mfma_f32_16x16x32_bf16 v[144:147], v[112:115], v[160:163], v[144:147]
	v_mfma_f32_16x16x32_bf16 v[136:139], v[120:123], v[160:163], v[136:139]
	v_mfma_f32_16x16x32_bf16 v[108:111], v[112:115], v[168:171], v[108:111]
	v_mfma_f32_16x16x32_bf16 v[104:107], v[120:123], v[168:171], v[104:107]
	v_mfma_f32_16x16x32_bf16 v[92:95], v[112:115], v[176:179], v[92:95]
	v_mfma_f32_16x16x32_bf16 v[88:91], v[120:123], v[176:179], v[88:91]
	v_mfma_f32_16x16x32_bf16 v[76:79], v[112:115], v[204:207], v[76:79]
	v_mfma_f32_16x16x32_bf16 v[72:75], v[120:123], v[204:207], v[72:75]
	v_mfma_f32_16x16x32_bf16 v[144:147], v[116:119], v[164:167], v[144:147]
	v_mfma_f32_16x16x32_bf16 v[136:139], v[132:135], v[164:167], v[136:139]
	v_mfma_f32_16x16x32_bf16 v[108:111], v[116:119], v[172:175], v[108:111]
	v_mfma_f32_16x16x32_bf16 v[104:107], v[132:135], v[172:175], v[104:107]
	v_mfma_f32_16x16x32_bf16 v[92:95], v[116:119], v[200:203], v[92:95]
	v_mfma_f32_16x16x32_bf16 v[88:91], v[132:135], v[200:203], v[88:91]
	v_mfma_f32_16x16x32_bf16 v[76:79], v[116:119], v[208:211], v[76:79]
	v_mfma_f32_16x16x32_bf16 v[72:75], v[132:135], v[208:211], v[72:75]
	v_mfma_f32_16x16x32_bf16 v[128:131], v[140:143], v[160:163], v[128:131]
	v_mfma_f32_16x16x32_bf16 v[124:127], v[152:155], v[160:163], v[124:127]
	v_mfma_f32_16x16x32_bf16 v[100:103], v[140:143], v[168:171], v[100:103]
	v_mfma_f32_16x16x32_bf16 v[96:99], v[152:155], v[168:171], v[96:99]
	v_mfma_f32_16x16x32_bf16 v[84:87], v[140:143], v[176:179], v[84:87]
	v_mfma_f32_16x16x32_bf16 v[80:83], v[152:155], v[176:179], v[80:83]
	v_mfma_f32_16x16x32_bf16 v[68:71], v[140:143], v[204:207], v[68:71]
	v_mfma_f32_16x16x32_bf16 v[64:67], v[152:155], v[204:207], v[64:67]
	v_mfma_f32_16x16x32_bf16 v[128:131], v[148:151], v[164:167], v[128:131]
	v_mfma_f32_16x16x32_bf16 v[124:127], v[156:159], v[164:167], v[124:127]
	v_mfma_f32_16x16x32_bf16 v[100:103], v[148:151], v[172:175], v[100:103]
	v_mfma_f32_16x16x32_bf16 v[96:99], v[156:159], v[172:175], v[96:99]
	v_mfma_f32_16x16x32_bf16 v[84:87], v[148:151], v[200:203], v[84:87]
	v_mfma_f32_16x16x32_bf16 v[80:83], v[156:159], v[200:203], v[80:83]
	v_mfma_f32_16x16x32_bf16 v[68:71], v[148:151], v[208:211], v[68:71]
	v_mfma_f32_16x16x32_bf16 v[64:67], v[156:159], v[208:211], v[64:67]
	s_setprio 0
	s_barrier
; #define PG8_STAGE(bufoff, gbase, voff) do { _Pragma("unroll") for (int _i = 0; _i < 2; ++_i) \
;         __builtin_amdgcn_global_load_lds((const unsigned*)((const char*)(gbase) + (voff)[_i]), (PG8_LAS unsigned*)(lds + (bufoff) + ldsw + _i * 8192), 16, 0, 0); } while (0)
; #define PG8_LDA(dst, b, h) do { _Pragma("unroll") for (int m = 0; m < 4; ++m) _Pragma("unroll") for (int k = 0; k < 2; ++k) dst[m][k] = *(const PG8_LAS bf16x8*)(lds + PG8_SA(b, h) + aoff + m * 2048 + k * 1024); } while (0)
; #define PG8_MMA(ai, bj, At, Bt) do { __builtin_amdgcn_s_setprio(1); _Pragma("unroll") for (int m = 0; m < 4; ++m) _Pragma("unroll") for (int n = 0; n < 2; ++n) _Pragma("unroll") for (int k = 0; k < 2; ++k) \
;         acc[ai][bj][m][n] = __builtin_amdgcn_mfma_f32_16x16x32_bf16(Bt[n][k], At[m][k], acc[ai][bj][m][n], 0, 0, 0); __builtin_amdgcn_s_setprio(0); } while (0)
; #define PG8_WAIT_V(n) asm volatile("s_waitcnt vmcnt(" #n ")" ::: "memory")
; #define PG8_WAIT_L(n) asm volatile("s_waitcnt lgkmcnt(" #n ")" ::: "memory")
; #define PG8_BAR __builtin_amdgcn_s_barrier()
; #define PG8_SCHED __builtin_amdgcn_sched_barrier(0)
; template <class Epi, class Sched, bool ALIGN_EPI = false, bool SP2 = false>
; __device__ __forceinline__ void gemm_phase(PG8_LAS unsigned char* lds, const Gemm g, const Sched& S, const Epi& E) {
;     ...
;         for (int t = 0; t < nt; t += 2) {
;             const bool last = (t == nt - 2);
;     ...
;             PG8_LDA(At, 1, 1); PG8_STAGE(PG8_SB(1, 0), b3, voffB); PG8_STAGE(PG8_SB(1, 1), b3 + hstep, voffB); PG8_STAGE(PG8_SA(1, 0), a3, voffA);
;             PG8_WAIT_V(8); PG8_WAIT_L(0); PG8_BAR; PG8_MMA(1, 0, At, B0); PG8_MMA(1, 1, At, B1); PG8_BAR; PG8_SCHED;
	s_add_i32 s38, s60, s44
	v_lshl_add_u64 v[212:213], v[212:213], 0, s[78:79]
	s_mov_b32 m0, s38
	ds_read_b128 v[160:163], v227 offset:49152
	ds_read_b128 v[164:167], v227 offset:50176
	ds_read_b128 v[168:171], v227 offset:51200
	ds_read_b128 v[172:175], v227 offset:52224
	ds_read_b128 v[176:179], v227 offset:53248
	ds_read_b128 v[200:203], v227 offset:54272
	ds_read_b128 v[204:207], v227 offset:55296
	ds_read_b128 v[208:211], v227 offset:56320
	global_load_lds_dwordx4 v[212:213], off
	s_add_i32 m0, s38, 0x2000
	s_add_u32 s36, s36, 0x80080
	v_lshl_add_u64 v[212:213], v[214:215], 0, s[78:79]
	s_addc_u32 s37, s37, 0
	s_add_i32 s38, s61, s44
	global_load_lds_dwordx4 v[212:213], off
	v_lshl_add_u64 v[212:213], s[36:37], 0, v[188:189]
	s_mov_b32 m0, s38
	s_nop 0
	global_load_lds_dwordx4 v[212:213], off
	v_lshl_add_u64 v[212:213], s[36:37], 0, v[180:181]
	s_add_i32 m0, s38, 0x2000
	s_nop 0
	global_load_lds_dwordx4 v[212:213], off
	v_lshl_add_u64 v[212:213], v[216:217], 0, s[78:79]
	s_mov_b32 m0, s58
	s_nop 0
	global_load_lds_dwordx4 v[212:213], off
	v_lshl_add_u64 v[212:213], v[218:219], 0, s[78:79]
	s_mov_b32 m0, s62
	s_nop 0
	global_load_lds_dwordx4 v[212:213], off
	s_nop 0
	s_waitcnt vmcnt(8)
	s_waitcnt lgkmcnt(0)
	s_barrier
	s_setprio 1
	v_mfma_f32_16x16x32_bf16 v[60:63], v[112:115], v[160:163], v[60:63]
	v_mfma_f32_16x16x32_bf16 v[56:59], v[120:123], v[160:163], v[56:59]
	v_mfma_f32_16x16x32_bf16 v[44:47], v[112:115], v[168:171], v[44:47]
	v_mfma_f32_16x16x32_bf16 v[40:43], v[120:123], v[168:171], v[40:43]
	v_mfma_f32_16x16x32_bf16 v[28:31], v[112:115], v[176:179], v[28:31]
	v_mfma_f32_16x16x32_bf16 v[24:27], v[120:123], v[176:179], v[24:27]
	v_mfma_f32_16x16x32_bf16 v[12:15], v[112:115], v[204:207], v[12:15]
	v_mfma_f32_16x16x32_bf16 v[8:11], v[120:123], v[204:207], v[8:11]
	v_mfma_f32_16x16x32_bf16 v[60:63], v[116:119], v[164:167], v[60:63]
	v_mfma_f32_16x16x32_bf16 v[56:59], v[132:135], v[164:167], v[56:59]
	v_mfma_f32_16x16x32_bf16 v[44:47], v[116:119], v[172:175], v[44:47]
	v_mfma_f32_16x16x32_bf16 v[40:43], v[132:135], v[172:175], v[40:43]
	v_mfma_f32_16x16x32_bf16 v[28:31], v[116:119], v[200:203], v[28:31]
	v_mfma_f32_16x16x32_bf16 v[24:27], v[132:135], v[200:203], v[24:27]
	v_mfma_f32_16x16x32_bf16 v[12:15], v[116:119], v[208:211], v[12:15]
	v_mfma_f32_16x16x32_bf16 v[8:11], v[132:135], v[208:211], v[8:11]
	v_mfma_f32_16x16x32_bf16 v[52:55], v[140:143], v[160:163], v[52:55]
	v_mfma_f32_16x16x32_bf16 v[48:51], v[152:155], v[160:163], v[48:51]
	v_mfma_f32_16x16x32_bf16 v[36:39], v[140:143], v[168:171], v[36:39]
	v_mfma_f32_16x16x32_bf16 v[32:35], v[152:155], v[168:171], v[32:35]
	v_mfma_f32_16x16x32_bf16 v[20:23], v[140:143], v[176:179], v[20:23]
	v_mfma_f32_16x16x32_bf16 v[16:19], v[152:155], v[176:179], v[16:19]
	v_mfma_f32_16x16x32_bf16 v[4:7], v[140:143], v[204:207], v[4:7]
	v_mfma_f32_16x16x32_bf16 v[0:3], v[152:155], v[204:207], v[0:3]
	v_mfma_f32_16x16x32_bf16 v[52:55], v[148:151], v[164:167], v[52:55]
	v_mfma_f32_16x16x32_bf16 v[48:51], v[156:159], v[164:167], v[48:51]
	v_mfma_f32_16x16x32_bf16 v[36:39], v[148:151], v[172:175], v[36:39]
	v_mfma_f32_16x16x32_bf16 v[32:35], v[156:159], v[172:175], v[32:35]
	v_mfma_f32_16x16x32_bf16 v[20:23], v[148:151], v[200:203], v[20:23]
	v_mfma_f32_16x16x32_bf16 v[16:19], v[156:159], v[200:203], v[16:19]
	v_mfma_f32_16x16x32_bf16 v[4:7], v[148:151], v[208:211], v[4:7]
	v_mfma_f32_16x16x32_bf16 v[0:3], v[156:159], v[208:211], v[0:3]
	s_setprio 0
	s_barrier
	s_add_i32 s72, s72, 2
	s_add_u32 s34, s34, 0x100
	s_addc_u32 s35, s35, 0
	s_add_u32 s67, s67, 0x100
	s_addc_u32 s68, s68, 0
	s_cmp_gt_u32 s72, 29
	s_cbranch_scc0 .LBB0_872
	v_mov_b32_e32 v196, 0x2000
	s_and_b64 vcc, exec, s[18:19]
	s_cbranch_vccz .LBB0_875
	s_barrier
